# MFMA order O9S: as O9 but odd A-groups issue their 4 chained pairs in reverse, so the B fragment carries over each group boundary
# speedup vs baseline: 1.0175x; 1.0018x over previous
.LBB0_170:
	ds_read_b128 v[136:139], v191
	ds_read_b128 v[158:161], v191 offset:1024
	ds_read_b128 v[162:165], v191 offset:2048
	ds_read_b128 v[166:169], v191 offset:3072
	ds_read_b128 v[170:173], v192
	ds_read_b128 v[174:177], v192 offset:1024
	ds_read_b128 v[178:181], v192 offset:2048
	ds_read_b128 v[194:197], v192 offset:3072
	s_add_u32 s0, s42, 0xfff00080
	s_addc_u32 s50, s43, -1
	s_cmp_eq_u32 s70, 60
	s_cselect_b32 s53, s23, s50
	s_cselect_b32 s52, s41, s0
	s_cselect_b32 s51, s21, s68
	s_cselect_b32 s50, s66, s67
	s_add_i32 m0, s31, 0xc000
	ds_read_b128 v[198:201], v193
	ds_read_b128 v[202:205], v193 offset:1024
	ds_read_b128 v[206:209], v193 offset:2048
	ds_read_b128 v[210:213], v193 offset:3072
	ds_read_b128 v[214:217], v193 offset:4096
	ds_read_b128 v[218:221], v193 offset:5120
	ds_read_b128 v[222:225], v193 offset:6144
	ds_read_b128 v[226:229], v193 offset:7168
	global_load_lds_dwordx4 v152, s[42:43]
	s_add_i32 m0, s31, 0xe000
	s_nop 0
	global_load_lds_dwordx4 v154, s[42:43]
	s_waitcnt vmcnt(8)
	s_waitcnt lgkmcnt(0)
	s_setprio 1
	s_barrier
	v_mfma_f32_16x16x32_bf16 v[132:135], v[136:139], v[198:201], v[132:135]
	v_mfma_f32_16x16x32_bf16 v[132:135], v[158:161], v[202:205], v[132:135]
	v_mfma_f32_16x16x32_bf16 v[128:131], v[162:165], v[198:201], v[128:131]
	v_mfma_f32_16x16x32_bf16 v[128:131], v[166:169], v[202:205], v[128:131]
	v_mfma_f32_16x16x32_bf16 v[124:127], v[170:173], v[198:201], v[124:127]
	v_mfma_f32_16x16x32_bf16 v[124:127], v[174:177], v[202:205], v[124:127]
	v_mfma_f32_16x16x32_bf16 v[120:123], v[178:181], v[198:201], v[120:123]
	v_mfma_f32_16x16x32_bf16 v[120:123], v[194:197], v[202:205], v[120:123]
	v_mfma_f32_16x16x32_bf16 v[104:107], v[178:181], v[206:209], v[104:107]
	v_mfma_f32_16x16x32_bf16 v[104:107], v[194:197], v[210:213], v[104:107]
	v_mfma_f32_16x16x32_bf16 v[108:111], v[170:173], v[206:209], v[108:111]
	v_mfma_f32_16x16x32_bf16 v[108:111], v[174:177], v[210:213], v[108:111]
	v_mfma_f32_16x16x32_bf16 v[112:115], v[162:165], v[206:209], v[112:115]
	v_mfma_f32_16x16x32_bf16 v[112:115], v[166:169], v[210:213], v[112:115]
	v_mfma_f32_16x16x32_bf16 v[116:119], v[136:139], v[206:209], v[116:119]
	v_mfma_f32_16x16x32_bf16 v[116:119], v[158:161], v[210:213], v[116:119]
	v_mfma_f32_16x16x32_bf16 v[100:103], v[136:139], v[214:217], v[100:103]
	v_mfma_f32_16x16x32_bf16 v[100:103], v[158:161], v[218:221], v[100:103]
	v_mfma_f32_16x16x32_bf16 v[96:99], v[162:165], v[214:217], v[96:99]
	v_mfma_f32_16x16x32_bf16 v[96:99], v[166:169], v[218:221], v[96:99]
	v_mfma_f32_16x16x32_bf16 v[92:95], v[170:173], v[214:217], v[92:95]
	v_mfma_f32_16x16x32_bf16 v[92:95], v[174:177], v[218:221], v[92:95]
	v_mfma_f32_16x16x32_bf16 v[88:91], v[178:181], v[214:217], v[88:91]
	v_mfma_f32_16x16x32_bf16 v[88:91], v[194:197], v[218:221], v[88:91]
	v_mfma_f32_16x16x32_bf16 v[72:75], v[178:181], v[222:225], v[72:75]
	v_mfma_f32_16x16x32_bf16 v[72:75], v[194:197], v[226:229], v[72:75]
	v_mfma_f32_16x16x32_bf16 v[76:79], v[170:173], v[222:225], v[76:79]
	v_mfma_f32_16x16x32_bf16 v[76:79], v[174:177], v[226:229], v[76:79]
	v_mfma_f32_16x16x32_bf16 v[80:83], v[162:165], v[222:225], v[80:83]
	v_mfma_f32_16x16x32_bf16 v[80:83], v[166:169], v[226:229], v[80:83]
	v_mfma_f32_16x16x32_bf16 v[84:87], v[136:139], v[222:225], v[84:87]
	v_mfma_f32_16x16x32_bf16 v[84:87], v[158:161], v[226:229], v[84:87]
	s_setprio 0
	s_barrier
	s_add_i32 s0, s61, s19
	s_mov_b32 m0, s0
	ds_read_b128 v[198:201], v193 offset:16384
	ds_read_b128 v[202:205], v193 offset:17408
	ds_read_b128 v[206:209], v193 offset:18432
	ds_read_b128 v[210:213], v193 offset:19456
	ds_read_b128 v[214:217], v193 offset:20480
	ds_read_b128 v[218:221], v193 offset:21504
	ds_read_b128 v[222:225], v193 offset:22528
	ds_read_b128 v[226:229], v193 offset:23552
	global_load_lds_dwordx4 v142, s[50:51]
	s_add_i32 m0, s0, 0x2000
	s_add_u32 s72, s50, 0x100000
	s_addc_u32 s73, s51, 0
	s_add_i32 s0, s62, s19
	global_load_lds_dwordx4 v146, s[50:51]
	s_mov_b32 m0, s0
	s_nop 0
	global_load_lds_dwordx4 v142, s[72:73]
	s_add_i32 m0, s0, 0x2000
	s_nop 0
	global_load_lds_dwordx4 v146, s[72:73]
	s_mov_b32 m0, s31
	s_nop 0
	global_load_lds_dwordx4 v140, s[52:53]
	s_mov_b32 m0, s35
	s_nop 0
	global_load_lds_dwordx4 v144, s[52:53]
	s_waitcnt vmcnt(8)
	s_waitcnt lgkmcnt(0)
	s_setprio 1
	s_barrier
	v_mfma_f32_16x16x32_bf16 v[68:71], v[136:139], v[198:201], v[68:71]
	v_mfma_f32_16x16x32_bf16 v[68:71], v[158:161], v[202:205], v[68:71]
	v_mfma_f32_16x16x32_bf16 v[64:67], v[162:165], v[198:201], v[64:67]
	v_mfma_f32_16x16x32_bf16 v[64:67], v[166:169], v[202:205], v[64:67]
	v_mfma_f32_16x16x32_bf16 v[60:63], v[170:173], v[198:201], v[60:63]
	v_mfma_f32_16x16x32_bf16 v[60:63], v[174:177], v[202:205], v[60:63]
	v_mfma_f32_16x16x32_bf16 v[56:59], v[178:181], v[198:201], v[56:59]
	v_mfma_f32_16x16x32_bf16 v[56:59], v[194:197], v[202:205], v[56:59]
	v_mfma_f32_16x16x32_bf16 v[40:43], v[178:181], v[206:209], v[40:43]
	v_mfma_f32_16x16x32_bf16 v[40:43], v[194:197], v[210:213], v[40:43]
	v_mfma_f32_16x16x32_bf16 v[44:47], v[170:173], v[206:209], v[44:47]
	v_mfma_f32_16x16x32_bf16 v[44:47], v[174:177], v[210:213], v[44:47]
	v_mfma_f32_16x16x32_bf16 v[48:51], v[162:165], v[206:209], v[48:51]
	v_mfma_f32_16x16x32_bf16 v[48:51], v[166:169], v[210:213], v[48:51]
	v_mfma_f32_16x16x32_bf16 v[52:55], v[136:139], v[206:209], v[52:55]
	v_mfma_f32_16x16x32_bf16 v[52:55], v[158:161], v[210:213], v[52:55]
	v_mfma_f32_16x16x32_bf16 v[36:39], v[136:139], v[214:217], v[36:39]
	v_mfma_f32_16x16x32_bf16 v[36:39], v[158:161], v[218:221], v[36:39]
	v_mfma_f32_16x16x32_bf16 v[32:35], v[162:165], v[214:217], v[32:35]
	v_mfma_f32_16x16x32_bf16 v[32:35], v[166:169], v[218:221], v[32:35]
	v_mfma_f32_16x16x32_bf16 v[28:31], v[170:173], v[214:217], v[28:31]
	v_mfma_f32_16x16x32_bf16 v[28:31], v[174:177], v[218:221], v[28:31]
	v_mfma_f32_16x16x32_bf16 v[24:27], v[178:181], v[214:217], v[24:27]
	v_mfma_f32_16x16x32_bf16 v[24:27], v[194:197], v[218:221], v[24:27]
	v_mfma_f32_16x16x32_bf16 v[6:9], v[178:181], v[222:225], v[8:11]
	v_mfma_f32_16x16x32_bf16 v[6:9], v[194:197], v[226:229], v[6:9]
	v_mfma_f32_16x16x32_bf16 v[12:15], v[170:173], v[222:225], v[12:15]
	v_mfma_f32_16x16x32_bf16 v[12:15], v[174:177], v[226:229], v[12:15]
	v_mfma_f32_16x16x32_bf16 v[16:19], v[162:165], v[222:225], v[16:19]
	v_mfma_f32_16x16x32_bf16 v[16:19], v[166:169], v[226:229], v[16:19]
	v_mfma_f32_16x16x32_bf16 v[20:23], v[136:139], v[222:225], v[20:23]
	v_mfma_f32_16x16x32_bf16 v[20:23], v[158:161], v[226:229], v[20:23]
	s_setprio 0
	s_barrier
	s_add_i32 s0, 0, 0x18000
	v_add_u32_e32 v5, s0, v1
	s_add_i32 s71, 0, 0x1c000
	ds_read_b128 v[136:139], v5
	ds_read_b128 v[158:161], v5 offset:1024
	ds_read_b128 v[162:165], v5 offset:2048
	ds_read_b128 v[166:169], v5 offset:3072
	v_add_u32_e32 v5, s71, v1
	ds_read_b128 v[170:173], v5
	ds_read_b128 v[174:177], v5 offset:1024
	ds_read_b128 v[178:181], v5 offset:2048
	ds_read_b128 v[194:197], v5 offset:3072
	s_add_u32 s98, s52, 0x100000
	s_addc_u32 s99, s53, 0
	s_mov_b32 m0, s45
	ds_read_b128 v[198:201], v193 offset:32768
	ds_read_b128 v[202:205], v193 offset:33792
	ds_read_b128 v[206:209], v193 offset:34816
	ds_read_b128 v[210:213], v193 offset:35840
	ds_read_b128 v[214:217], v193 offset:36864
	ds_read_b128 v[218:221], v193 offset:37888
	ds_read_b128 v[222:225], v193 offset:38912
	ds_read_b128 v[226:229], v193 offset:39936
	global_load_lds_dwordx4 v140, s[98:99]
	s_mov_b32 m0, s46
	s_nop 0
	global_load_lds_dwordx4 v144, s[98:99]
	s_waitcnt vmcnt(8)
	s_waitcnt lgkmcnt(0)
	s_setprio 1
	s_barrier
	v_mfma_f32_16x16x32_bf16 v[132:135], v[136:139], v[198:201], v[132:135]
	v_mfma_f32_16x16x32_bf16 v[132:135], v[158:161], v[202:205], v[132:135]
	v_mfma_f32_16x16x32_bf16 v[128:131], v[162:165], v[198:201], v[128:131]
	v_mfma_f32_16x16x32_bf16 v[128:131], v[166:169], v[202:205], v[128:131]
	v_mfma_f32_16x16x32_bf16 v[124:127], v[170:173], v[198:201], v[124:127]
	v_mfma_f32_16x16x32_bf16 v[124:127], v[174:177], v[202:205], v[124:127]
	v_mfma_f32_16x16x32_bf16 v[120:123], v[178:181], v[198:201], v[120:123]
	v_mfma_f32_16x16x32_bf16 v[120:123], v[194:197], v[202:205], v[120:123]
	v_mfma_f32_16x16x32_bf16 v[104:107], v[178:181], v[206:209], v[104:107]
	v_mfma_f32_16x16x32_bf16 v[104:107], v[194:197], v[210:213], v[104:107]
	v_mfma_f32_16x16x32_bf16 v[108:111], v[170:173], v[206:209], v[108:111]
	v_mfma_f32_16x16x32_bf16 v[108:111], v[174:177], v[210:213], v[108:111]
	v_mfma_f32_16x16x32_bf16 v[112:115], v[162:165], v[206:209], v[112:115]
	v_mfma_f32_16x16x32_bf16 v[112:115], v[166:169], v[210:213], v[112:115]
	v_mfma_f32_16x16x32_bf16 v[116:119], v[136:139], v[206:209], v[116:119]
	v_mfma_f32_16x16x32_bf16 v[116:119], v[158:161], v[210:213], v[116:119]
	v_mfma_f32_16x16x32_bf16 v[100:103], v[136:139], v[214:217], v[100:103]
	v_mfma_f32_16x16x32_bf16 v[100:103], v[158:161], v[218:221], v[100:103]
	v_mfma_f32_16x16x32_bf16 v[96:99], v[162:165], v[214:217], v[96:99]
	v_mfma_f32_16x16x32_bf16 v[96:99], v[166:169], v[218:221], v[96:99]
	v_mfma_f32_16x16x32_bf16 v[92:95], v[170:173], v[214:217], v[92:95]
	v_mfma_f32_16x16x32_bf16 v[92:95], v[174:177], v[218:221], v[92:95]
	v_mfma_f32_16x16x32_bf16 v[88:91], v[178:181], v[214:217], v[88:91]
	v_mfma_f32_16x16x32_bf16 v[88:91], v[194:197], v[218:221], v[88:91]
	v_mfma_f32_16x16x32_bf16 v[72:75], v[178:181], v[222:225], v[72:75]
	v_mfma_f32_16x16x32_bf16 v[72:75], v[194:197], v[226:229], v[72:75]
	v_mfma_f32_16x16x32_bf16 v[76:79], v[170:173], v[222:225], v[76:79]
	v_mfma_f32_16x16x32_bf16 v[76:79], v[174:177], v[226:229], v[76:79]
	v_mfma_f32_16x16x32_bf16 v[80:83], v[162:165], v[222:225], v[80:83]
	v_mfma_f32_16x16x32_bf16 v[80:83], v[166:169], v[226:229], v[80:83]
	v_mfma_f32_16x16x32_bf16 v[84:87], v[136:139], v[222:225], v[84:87]
	v_mfma_f32_16x16x32_bf16 v[84:87], v[158:161], v[226:229], v[84:87]
	s_setprio 0
	s_barrier
	s_add_i32 s0, s0, s19
	s_add_i32 m0, s0, 0xffffff80
	ds_read_b128 v[198:201], v193 offset:49152
	ds_read_b128 v[202:205], v193 offset:50176
	ds_read_b128 v[206:209], v193 offset:51200
	ds_read_b128 v[210:213], v193 offset:52224
	ds_read_b128 v[214:217], v193 offset:53248
	ds_read_b128 v[218:221], v193 offset:54272
	ds_read_b128 v[222:225], v193 offset:55296
	ds_read_b128 v[226:229], v193 offset:56320
	global_load_lds_dwordx4 v142, s[50:51] offset:128
	s_add_i32 m0, s0, 0x1f80
	s_add_i32 s0, s71, s19
	global_load_lds_dwordx4 v146, s[50:51] offset:128
	s_add_u32 s50, s50, 0x100080
	s_addc_u32 s51, s51, 0
	s_mov_b32 m0, s0
	s_nop 0
	global_load_lds_dwordx4 v142, s[50:51]
	s_add_i32 m0, s0, 0x2000
	s_nop 0
	global_load_lds_dwordx4 v146, s[50:51]
	s_add_i32 m0, s56, 0xffffff80
	s_nop 0
	global_load_lds_dwordx4 v140, s[52:53] offset:128
	s_add_i32 m0, s57, 0xffffff80
	s_nop 0
	global_load_lds_dwordx4 v144, s[52:53] offset:128
	s_waitcnt vmcnt(8)
	s_waitcnt lgkmcnt(0)
	s_setprio 1
	s_barrier
	v_mfma_f32_16x16x32_bf16 v[68:71], v[136:139], v[198:201], v[68:71]
	v_mfma_f32_16x16x32_bf16 v[68:71], v[158:161], v[202:205], v[68:71]
	v_mfma_f32_16x16x32_bf16 v[64:67], v[162:165], v[198:201], v[64:67]
	v_mfma_f32_16x16x32_bf16 v[64:67], v[166:169], v[202:205], v[64:67]
	v_mfma_f32_16x16x32_bf16 v[60:63], v[170:173], v[198:201], v[60:63]
	v_mfma_f32_16x16x32_bf16 v[60:63], v[174:177], v[202:205], v[60:63]
	v_mfma_f32_16x16x32_bf16 v[56:59], v[178:181], v[198:201], v[56:59]
	v_mfma_f32_16x16x32_bf16 v[56:59], v[194:197], v[202:205], v[56:59]
	v_mfma_f32_16x16x32_bf16 v[52:55], v[136:139], v[206:209], v[52:55]
	v_mfma_f32_16x16x32_bf16 v[52:55], v[158:161], v[210:213], v[52:55]
	v_mfma_f32_16x16x32_bf16 v[48:51], v[162:165], v[206:209], v[48:51]
	v_mfma_f32_16x16x32_bf16 v[48:51], v[166:169], v[210:213], v[48:51]
	v_mfma_f32_16x16x32_bf16 v[44:47], v[170:173], v[206:209], v[44:47]
	v_mfma_f32_16x16x32_bf16 v[44:47], v[174:177], v[210:213], v[44:47]
	v_mfma_f32_16x16x32_bf16 v[40:43], v[178:181], v[206:209], v[40:43]
	v_mfma_f32_16x16x32_bf16 v[40:43], v[194:197], v[210:213], v[40:43]
	v_mfma_f32_16x16x32_bf16 v[36:39], v[136:139], v[214:217], v[36:39]
	v_mfma_f32_16x16x32_bf16 v[36:39], v[158:161], v[218:221], v[36:39]
	v_mfma_f32_16x16x32_bf16 v[32:35], v[162:165], v[214:217], v[32:35]
	v_mfma_f32_16x16x32_bf16 v[32:35], v[166:169], v[218:221], v[32:35]
	v_mfma_f32_16x16x32_bf16 v[28:31], v[170:173], v[214:217], v[28:31]
	v_mfma_f32_16x16x32_bf16 v[28:31], v[174:177], v[218:221], v[28:31]
	v_mfma_f32_16x16x32_bf16 v[24:27], v[178:181], v[214:217], v[24:27]
	v_mfma_f32_16x16x32_bf16 v[24:27], v[194:197], v[218:221], v[24:27]
	v_mfma_f32_16x16x32_bf16 v[20:23], v[136:139], v[222:225], v[20:23]
	v_mfma_f32_16x16x32_bf16 v[20:23], v[158:161], v[226:229], v[20:23]
	v_mfma_f32_16x16x32_bf16 v[16:19], v[162:165], v[222:225], v[16:19]
	v_mfma_f32_16x16x32_bf16 v[16:19], v[166:169], v[226:229], v[16:19]
	v_mfma_f32_16x16x32_bf16 v[10:13], v[170:173], v[222:225], v[12:15]
	v_mfma_f32_16x16x32_bf16 v[12:15], v[174:177], v[226:229], v[10:13]
	v_mfma_f32_16x16x32_bf16 v[6:9], v[178:181], v[222:225], v[6:9]
	v_mfma_f32_16x16x32_bf16 v[8:11], v[194:197], v[226:229], v[6:9]
	s_setprio 0
	s_barrier
	s_add_i32 s70, s70, 2
	s_add_u32 s42, s42, 0x100
	s_addc_u32 s43, s43, 0
	s_add_u32 s67, s67, 0x100
	s_addc_u32 s68, s68, 0
	s_cmp_gt_u32 s70, 61
	s_cbranch_scc0 .LBB0_170
	s_and_b64 vcc, exec, s[16:17]
	s_cbranch_vccz .LBB0_173
	s_barrier

.LBB0_342:
	ds_read_b128 v[132:135], v209
	ds_read_b128 v[136:139], v209 offset:1024
	ds_read_b128 v[140:143], v209 offset:2048
	ds_read_b128 v[144:147], v209 offset:3072
	ds_read_b128 v[148:151], v210
	ds_read_b128 v[152:155], v210 offset:1024
	ds_read_b128 v[156:159], v210 offset:2048
	ds_read_b128 v[160:163], v210 offset:3072
	s_add_u32 s0, s26, 0xffd50080
	s_addc_u32 s28, s27, -1
	s_cmpk_eq_i32 s62, 0xa8
	s_cselect_b32 s31, s7, s28
	s_cselect_b32 s30, s6, s0
	s_cselect_b32 s29, s25, s61
	s_cselect_b32 s28, s24, s60
	s_add_i32 m0, s43, 0xc000
	ds_read_b128 v[164:167], v211
	ds_read_b128 v[168:171], v211 offset:1024
	ds_read_b128 v[172:175], v211 offset:2048
	ds_read_b128 v[176:179], v211 offset:3072
	ds_read_b128 v[196:199], v211 offset:4096
	ds_read_b128 v[200:203], v211 offset:5120
	ds_read_b128 v[204:207], v211 offset:6144
	ds_read_b128 v[214:217], v211 offset:7168
	global_load_lds_dwordx4 v188, s[26:27]
	s_add_i32 m0, s43, 0xe000
	s_nop 0
	global_load_lds_dwordx4 v190, s[26:27]
	s_waitcnt vmcnt(8)
	s_waitcnt lgkmcnt(0)
	s_setprio 1
	s_barrier
	v_mfma_f32_16x16x32_bf16 v[128:131], v[132:135], v[164:167], v[128:131]
	v_mfma_f32_16x16x32_bf16 v[128:131], v[136:139], v[168:171], v[128:131]
	v_mfma_f32_16x16x32_bf16 v[124:127], v[140:143], v[164:167], v[124:127]
	v_mfma_f32_16x16x32_bf16 v[124:127], v[144:147], v[168:171], v[124:127]
	v_mfma_f32_16x16x32_bf16 v[120:123], v[148:151], v[164:167], v[120:123]
	v_mfma_f32_16x16x32_bf16 v[120:123], v[152:155], v[168:171], v[120:123]
	v_mfma_f32_16x16x32_bf16 v[116:119], v[156:159], v[164:167], v[116:119]
	v_mfma_f32_16x16x32_bf16 v[116:119], v[160:163], v[168:171], v[116:119]
	v_mfma_f32_16x16x32_bf16 v[100:103], v[156:159], v[172:175], v[100:103]
	v_mfma_f32_16x16x32_bf16 v[100:103], v[160:163], v[176:179], v[100:103]
	v_mfma_f32_16x16x32_bf16 v[104:107], v[148:151], v[172:175], v[104:107]
	v_mfma_f32_16x16x32_bf16 v[104:107], v[152:155], v[176:179], v[104:107]
	v_mfma_f32_16x16x32_bf16 v[108:111], v[140:143], v[172:175], v[108:111]
	v_mfma_f32_16x16x32_bf16 v[108:111], v[144:147], v[176:179], v[108:111]
	v_mfma_f32_16x16x32_bf16 v[112:115], v[132:135], v[172:175], v[112:115]
	v_mfma_f32_16x16x32_bf16 v[112:115], v[136:139], v[176:179], v[112:115]
	v_mfma_f32_16x16x32_bf16 v[96:99], v[132:135], v[196:199], v[96:99]
	v_mfma_f32_16x16x32_bf16 v[96:99], v[136:139], v[200:203], v[96:99]
	v_mfma_f32_16x16x32_bf16 v[92:95], v[140:143], v[196:199], v[92:95]
	v_mfma_f32_16x16x32_bf16 v[92:95], v[144:147], v[200:203], v[92:95]
	v_mfma_f32_16x16x32_bf16 v[88:91], v[148:151], v[196:199], v[88:91]
	v_mfma_f32_16x16x32_bf16 v[88:91], v[152:155], v[200:203], v[88:91]
	v_mfma_f32_16x16x32_bf16 v[84:87], v[156:159], v[196:199], v[84:87]
	v_mfma_f32_16x16x32_bf16 v[84:87], v[160:163], v[200:203], v[84:87]
	v_mfma_f32_16x16x32_bf16 v[68:71], v[156:159], v[204:207], v[68:71]
	v_mfma_f32_16x16x32_bf16 v[68:71], v[160:163], v[214:217], v[68:71]
	v_mfma_f32_16x16x32_bf16 v[72:75], v[148:151], v[204:207], v[72:75]
	v_mfma_f32_16x16x32_bf16 v[72:75], v[152:155], v[214:217], v[72:75]
	v_mfma_f32_16x16x32_bf16 v[76:79], v[140:143], v[204:207], v[76:79]
	v_mfma_f32_16x16x32_bf16 v[76:79], v[144:147], v[214:217], v[76:79]
	v_mfma_f32_16x16x32_bf16 v[80:83], v[132:135], v[204:207], v[80:83]
	v_mfma_f32_16x16x32_bf16 v[80:83], v[136:139], v[214:217], v[80:83]
	s_setprio 0
	s_barrier
	s_add_i32 s0, s53, s42
	s_mov_b32 m0, s0
	ds_read_b128 v[164:167], v211 offset:16384
	ds_read_b128 v[168:171], v211 offset:17408
	ds_read_b128 v[172:175], v211 offset:18432
	ds_read_b128 v[176:179], v211 offset:19456
	ds_read_b128 v[196:199], v211 offset:20480
	ds_read_b128 v[200:203], v211 offset:21504
	ds_read_b128 v[204:207], v211 offset:22528
	ds_read_b128 v[214:217], v211 offset:23552
	global_load_lds_dwordx4 v182, s[28:29]
	s_add_i32 m0, s0, 0x2000
	s_add_u32 s64, s28, 0x2b0000
	s_addc_u32 s65, s29, 0
	s_add_i32 s0, s54, s42
	global_load_lds_dwordx4 v186, s[28:29]
	s_mov_b32 m0, s0
	s_nop 0
	global_load_lds_dwordx4 v182, s[64:65]
	s_add_i32 m0, s0, 0x2000
	s_nop 0
	global_load_lds_dwordx4 v186, s[64:65]
	s_mov_b32 m0, s43
	s_nop 0
	global_load_lds_dwordx4 v180, s[30:31]
	s_mov_b32 m0, s45
	s_nop 0
	global_load_lds_dwordx4 v184, s[30:31]
	s_waitcnt vmcnt(8)
	s_waitcnt lgkmcnt(0)
	s_setprio 1
	s_barrier
	v_mfma_f32_16x16x32_bf16 v[64:67], v[132:135], v[164:167], v[64:67]
	v_mfma_f32_16x16x32_bf16 v[64:67], v[136:139], v[168:171], v[64:67]
	v_mfma_f32_16x16x32_bf16 v[60:63], v[140:143], v[164:167], v[60:63]
	v_mfma_f32_16x16x32_bf16 v[60:63], v[144:147], v[168:171], v[60:63]
	v_mfma_f32_16x16x32_bf16 v[56:59], v[148:151], v[164:167], v[56:59]
	v_mfma_f32_16x16x32_bf16 v[56:59], v[152:155], v[168:171], v[56:59]
	v_mfma_f32_16x16x32_bf16 v[52:55], v[156:159], v[164:167], v[52:55]
	v_mfma_f32_16x16x32_bf16 v[52:55], v[160:163], v[168:171], v[52:55]
	v_mfma_f32_16x16x32_bf16 v[36:39], v[156:159], v[172:175], v[36:39]
	v_mfma_f32_16x16x32_bf16 v[36:39], v[160:163], v[176:179], v[36:39]
	v_mfma_f32_16x16x32_bf16 v[40:43], v[148:151], v[172:175], v[40:43]
	v_mfma_f32_16x16x32_bf16 v[40:43], v[152:155], v[176:179], v[40:43]
	v_mfma_f32_16x16x32_bf16 v[44:47], v[140:143], v[172:175], v[44:47]
	v_mfma_f32_16x16x32_bf16 v[44:47], v[144:147], v[176:179], v[44:47]
	v_mfma_f32_16x16x32_bf16 v[48:51], v[132:135], v[172:175], v[48:51]
	v_mfma_f32_16x16x32_bf16 v[48:51], v[136:139], v[176:179], v[48:51]
	v_mfma_f32_16x16x32_bf16 v[32:35], v[132:135], v[196:199], v[32:35]
	v_mfma_f32_16x16x32_bf16 v[32:35], v[136:139], v[200:203], v[32:35]
	v_mfma_f32_16x16x32_bf16 v[28:31], v[140:143], v[196:199], v[28:31]
	v_mfma_f32_16x16x32_bf16 v[28:31], v[144:147], v[200:203], v[28:31]
	v_mfma_f32_16x16x32_bf16 v[24:27], v[148:151], v[196:199], v[24:27]
	v_mfma_f32_16x16x32_bf16 v[24:27], v[152:155], v[200:203], v[24:27]
	v_mfma_f32_16x16x32_bf16 v[20:23], v[156:159], v[196:199], v[20:23]
	v_mfma_f32_16x16x32_bf16 v[20:23], v[160:163], v[200:203], v[20:23]
	v_mfma_f32_16x16x32_bf16 v[4:7], v[156:159], v[204:207], v[4:7]
	v_mfma_f32_16x16x32_bf16 v[4:7], v[160:163], v[214:217], v[4:7]
	v_mfma_f32_16x16x32_bf16 v[8:11], v[148:151], v[204:207], v[8:11]
	v_mfma_f32_16x16x32_bf16 v[8:11], v[152:155], v[214:217], v[8:11]
	v_mfma_f32_16x16x32_bf16 v[12:15], v[140:143], v[204:207], v[12:15]
	v_mfma_f32_16x16x32_bf16 v[12:15], v[144:147], v[214:217], v[12:15]
	v_mfma_f32_16x16x32_bf16 v[16:19], v[132:135], v[204:207], v[16:19]
	v_mfma_f32_16x16x32_bf16 v[16:19], v[136:139], v[214:217], v[16:19]
	s_setprio 0
	s_barrier
	s_add_i32 s0, 0, 0x18000
	s_add_i32 s63, 0, 0x1c000
	v_add_u32_e32 v144, s0, v3
	v_add_u32_e32 v160, s63, v3
	ds_read_b128 v[132:135], v144
	ds_read_b128 v[136:139], v144 offset:1024
	ds_read_b128 v[140:143], v144 offset:2048
	ds_read_b128 v[144:147], v144 offset:3072
	ds_read_b128 v[148:151], v160
	ds_read_b128 v[152:155], v160 offset:1024
	ds_read_b128 v[156:159], v160 offset:2048
	ds_read_b128 v[160:163], v160 offset:3072
	s_add_u32 s98, s30, 0x2b0000
	s_addc_u32 s99, s31, 0
	s_mov_b32 m0, s46
	ds_read_b128 v[164:167], v211 offset:32768
	ds_read_b128 v[168:171], v211 offset:33792
	ds_read_b128 v[172:175], v211 offset:34816
	ds_read_b128 v[176:179], v211 offset:35840
	ds_read_b128 v[196:199], v211 offset:36864
	ds_read_b128 v[200:203], v211 offset:37888
	ds_read_b128 v[204:207], v211 offset:38912
	ds_read_b128 v[214:217], v211 offset:39936
	global_load_lds_dwordx4 v180, s[98:99]
	s_mov_b32 m0, s47
	s_nop 0
	global_load_lds_dwordx4 v184, s[98:99]
	s_waitcnt vmcnt(8)
	s_waitcnt lgkmcnt(0)
	s_setprio 1
	s_barrier
	v_mfma_f32_16x16x32_bf16 v[128:131], v[132:135], v[164:167], v[128:131]
	v_mfma_f32_16x16x32_bf16 v[128:131], v[136:139], v[168:171], v[128:131]
	v_mfma_f32_16x16x32_bf16 v[124:127], v[140:143], v[164:167], v[124:127]
	v_mfma_f32_16x16x32_bf16 v[124:127], v[144:147], v[168:171], v[124:127]
	v_mfma_f32_16x16x32_bf16 v[120:123], v[148:151], v[164:167], v[120:123]
	v_mfma_f32_16x16x32_bf16 v[120:123], v[152:155], v[168:171], v[120:123]
	v_mfma_f32_16x16x32_bf16 v[116:119], v[156:159], v[164:167], v[116:119]
	v_mfma_f32_16x16x32_bf16 v[116:119], v[160:163], v[168:171], v[116:119]
	v_mfma_f32_16x16x32_bf16 v[100:103], v[156:159], v[172:175], v[100:103]
	v_mfma_f32_16x16x32_bf16 v[100:103], v[160:163], v[176:179], v[100:103]
	v_mfma_f32_16x16x32_bf16 v[104:107], v[148:151], v[172:175], v[104:107]
	v_mfma_f32_16x16x32_bf16 v[104:107], v[152:155], v[176:179], v[104:107]
	v_mfma_f32_16x16x32_bf16 v[108:111], v[140:143], v[172:175], v[108:111]
	v_mfma_f32_16x16x32_bf16 v[108:111], v[144:147], v[176:179], v[108:111]
	v_mfma_f32_16x16x32_bf16 v[112:115], v[132:135], v[172:175], v[112:115]
	v_mfma_f32_16x16x32_bf16 v[112:115], v[136:139], v[176:179], v[112:115]
	v_mfma_f32_16x16x32_bf16 v[96:99], v[132:135], v[196:199], v[96:99]
	v_mfma_f32_16x16x32_bf16 v[96:99], v[136:139], v[200:203], v[96:99]
	v_mfma_f32_16x16x32_bf16 v[92:95], v[140:143], v[196:199], v[92:95]
	v_mfma_f32_16x16x32_bf16 v[92:95], v[144:147], v[200:203], v[92:95]
	v_mfma_f32_16x16x32_bf16 v[88:91], v[148:151], v[196:199], v[88:91]
	v_mfma_f32_16x16x32_bf16 v[88:91], v[152:155], v[200:203], v[88:91]
	v_mfma_f32_16x16x32_bf16 v[84:87], v[156:159], v[196:199], v[84:87]
	v_mfma_f32_16x16x32_bf16 v[84:87], v[160:163], v[200:203], v[84:87]
	v_mfma_f32_16x16x32_bf16 v[68:71], v[156:159], v[204:207], v[68:71]
	v_mfma_f32_16x16x32_bf16 v[68:71], v[160:163], v[214:217], v[68:71]
	v_mfma_f32_16x16x32_bf16 v[72:75], v[148:151], v[204:207], v[72:75]
	v_mfma_f32_16x16x32_bf16 v[72:75], v[152:155], v[214:217], v[72:75]
	v_mfma_f32_16x16x32_bf16 v[76:79], v[140:143], v[204:207], v[76:79]
	v_mfma_f32_16x16x32_bf16 v[76:79], v[144:147], v[214:217], v[76:79]
	v_mfma_f32_16x16x32_bf16 v[80:83], v[132:135], v[204:207], v[80:83]
	v_mfma_f32_16x16x32_bf16 v[80:83], v[136:139], v[214:217], v[80:83]
	s_setprio 0
	s_barrier
	s_add_i32 s0, s0, s42
	s_add_i32 m0, s0, 0xffffff80
	ds_read_b128 v[164:167], v211 offset:49152
	ds_read_b128 v[168:171], v211 offset:50176
	ds_read_b128 v[172:175], v211 offset:51200
	ds_read_b128 v[176:179], v211 offset:52224
	ds_read_b128 v[196:199], v211 offset:53248
	ds_read_b128 v[200:203], v211 offset:54272
	ds_read_b128 v[204:207], v211 offset:55296
	ds_read_b128 v[214:217], v211 offset:56320
	global_load_lds_dwordx4 v182, s[28:29] offset:128
	s_add_i32 m0, s0, 0x1f80
	s_add_i32 s0, s63, s42
	global_load_lds_dwordx4 v186, s[28:29] offset:128
	s_add_u32 s28, s28, 0x2b0080
	s_addc_u32 s29, s29, 0
	s_mov_b32 m0, s0
	s_nop 0
	global_load_lds_dwordx4 v182, s[28:29]
	s_add_i32 m0, s0, 0x2000
	s_nop 0
	global_load_lds_dwordx4 v186, s[28:29]
	s_add_i32 m0, s51, 0xffffff80
	s_nop 0
	global_load_lds_dwordx4 v180, s[30:31] offset:128
	s_add_i32 m0, s52, 0xffffff80
	s_nop 0
	global_load_lds_dwordx4 v184, s[30:31] offset:128
	s_waitcnt vmcnt(8)
	s_waitcnt lgkmcnt(0)
	s_setprio 1
	s_barrier
	v_mfma_f32_16x16x32_bf16 v[64:67], v[132:135], v[164:167], v[64:67]
	v_mfma_f32_16x16x32_bf16 v[64:67], v[136:139], v[168:171], v[64:67]
	v_mfma_f32_16x16x32_bf16 v[60:63], v[140:143], v[164:167], v[60:63]
	v_mfma_f32_16x16x32_bf16 v[60:63], v[144:147], v[168:171], v[60:63]
	v_mfma_f32_16x16x32_bf16 v[56:59], v[148:151], v[164:167], v[56:59]
	v_mfma_f32_16x16x32_bf16 v[56:59], v[152:155], v[168:171], v[56:59]
	v_mfma_f32_16x16x32_bf16 v[52:55], v[156:159], v[164:167], v[52:55]
	v_mfma_f32_16x16x32_bf16 v[52:55], v[160:163], v[168:171], v[52:55]
	v_mfma_f32_16x16x32_bf16 v[36:39], v[156:159], v[172:175], v[36:39]
	v_mfma_f32_16x16x32_bf16 v[36:39], v[160:163], v[176:179], v[36:39]
	v_mfma_f32_16x16x32_bf16 v[40:43], v[148:151], v[172:175], v[40:43]
	v_mfma_f32_16x16x32_bf16 v[40:43], v[152:155], v[176:179], v[40:43]
	v_mfma_f32_16x16x32_bf16 v[44:47], v[140:143], v[172:175], v[44:47]
	v_mfma_f32_16x16x32_bf16 v[44:47], v[144:147], v[176:179], v[44:47]
	v_mfma_f32_16x16x32_bf16 v[48:51], v[132:135], v[172:175], v[48:51]
	v_mfma_f32_16x16x32_bf16 v[48:51], v[136:139], v[176:179], v[48:51]
	v_mfma_f32_16x16x32_bf16 v[32:35], v[132:135], v[196:199], v[32:35]
	v_mfma_f32_16x16x32_bf16 v[32:35], v[136:139], v[200:203], v[32:35]
	v_mfma_f32_16x16x32_bf16 v[28:31], v[140:143], v[196:199], v[28:31]
	v_mfma_f32_16x16x32_bf16 v[28:31], v[144:147], v[200:203], v[28:31]
	v_mfma_f32_16x16x32_bf16 v[24:27], v[148:151], v[196:199], v[24:27]
	v_mfma_f32_16x16x32_bf16 v[24:27], v[152:155], v[200:203], v[24:27]
	v_mfma_f32_16x16x32_bf16 v[20:23], v[156:159], v[196:199], v[20:23]
	v_mfma_f32_16x16x32_bf16 v[20:23], v[160:163], v[200:203], v[20:23]
	v_mfma_f32_16x16x32_bf16 v[4:7], v[156:159], v[204:207], v[4:7]
	v_mfma_f32_16x16x32_bf16 v[4:7], v[160:163], v[214:217], v[4:7]
	v_mfma_f32_16x16x32_bf16 v[8:11], v[148:151], v[204:207], v[8:11]
	v_mfma_f32_16x16x32_bf16 v[8:11], v[152:155], v[214:217], v[8:11]
	v_mfma_f32_16x16x32_bf16 v[12:15], v[140:143], v[204:207], v[12:15]
	v_mfma_f32_16x16x32_bf16 v[12:15], v[144:147], v[214:217], v[12:15]
	v_mfma_f32_16x16x32_bf16 v[16:19], v[132:135], v[204:207], v[16:19]
	v_mfma_f32_16x16x32_bf16 v[16:19], v[136:139], v[214:217], v[16:19]
	s_setprio 0
	s_barrier
	s_add_i32 s62, s62, 2
	s_add_u32 s26, s26, 0x100
	s_addc_u32 s27, s27, 0
	s_add_u32 s60, s60, 0x100
	s_addc_u32 s61, s61, 0
	s_cmpk_gt_u32 s62, 0xa9
	s_cbranch_scc0 .LBB0_342
	s_and_b64 vcc, exec, s[22:23]
	s_cbranch_vccz .LBB0_345
	s_barrier

.LBB0_429:
	ds_read_b128 v[150:153], v156
	ds_read_b128 v[162:165], v156 offset:1024
	ds_read_b128 v[166:169], v156 offset:2048
	ds_read_b128 v[170:173], v156 offset:3072
	ds_read_b128 v[174:177], v157
	ds_read_b128 v[178:181], v157 offset:1024
	ds_read_b128 v[182:185], v157 offset:2048
	ds_read_b128 v[186:189], v157 offset:3072
	s_add_u32 s0, s50, 0xfff00080
	s_addc_u32 s52, s51, -1
	s_cmp_eq_u32 s72, 60
	s_cselect_b32 s55, s27, s52
	s_cselect_b32 s54, s67, s0
	s_cselect_b32 s53, s25, s71
	s_cselect_b32 s52, s68, s70
	s_add_i32 m0, s43, 0xc000
	ds_read_b128 v[190:193], v158
	ds_read_b128 v[194:197], v158 offset:1024
	ds_read_b128 v[198:201], v158 offset:2048
	ds_read_b128 v[202:205], v158 offset:3072
	ds_read_b128 v[206:209], v158 offset:4096
	ds_read_b128 v[210:213], v158 offset:5120
	ds_read_b128 v[214:217], v158 offset:6144
	ds_read_b128 v[218:221], v158 offset:7168
	global_load_lds_dwordx4 v142, s[50:51]
	s_add_i32 m0, s43, 0xe000
	s_nop 0
	global_load_lds_dwordx4 v144, s[50:51]
	s_waitcnt vmcnt(8)
	s_waitcnt lgkmcnt(0)
	s_setprio 1
	s_barrier
	v_mfma_f32_16x16x32_bf16 v[128:131], v[150:153], v[190:193], v[128:131]
	v_mfma_f32_16x16x32_bf16 v[128:131], v[162:165], v[194:197], v[128:131]
	v_mfma_f32_16x16x32_bf16 v[124:127], v[166:169], v[190:193], v[124:127]
	v_mfma_f32_16x16x32_bf16 v[124:127], v[170:173], v[194:197], v[124:127]
	v_mfma_f32_16x16x32_bf16 v[120:123], v[174:177], v[190:193], v[120:123]
	v_mfma_f32_16x16x32_bf16 v[120:123], v[178:181], v[194:197], v[120:123]
	v_mfma_f32_16x16x32_bf16 v[116:119], v[182:185], v[190:193], v[116:119]
	v_mfma_f32_16x16x32_bf16 v[116:119], v[186:189], v[194:197], v[116:119]
	v_mfma_f32_16x16x32_bf16 v[100:103], v[182:185], v[198:201], v[100:103]
	v_mfma_f32_16x16x32_bf16 v[100:103], v[186:189], v[202:205], v[100:103]
	v_mfma_f32_16x16x32_bf16 v[104:107], v[174:177], v[198:201], v[104:107]
	v_mfma_f32_16x16x32_bf16 v[104:107], v[178:181], v[202:205], v[104:107]
	v_mfma_f32_16x16x32_bf16 v[108:111], v[166:169], v[198:201], v[108:111]
	v_mfma_f32_16x16x32_bf16 v[108:111], v[170:173], v[202:205], v[108:111]
	v_mfma_f32_16x16x32_bf16 v[112:115], v[150:153], v[198:201], v[112:115]
	v_mfma_f32_16x16x32_bf16 v[112:115], v[162:165], v[202:205], v[112:115]
	v_mfma_f32_16x16x32_bf16 v[96:99], v[150:153], v[206:209], v[96:99]
	v_mfma_f32_16x16x32_bf16 v[96:99], v[162:165], v[210:213], v[96:99]
	v_mfma_f32_16x16x32_bf16 v[92:95], v[166:169], v[206:209], v[92:95]
	v_mfma_f32_16x16x32_bf16 v[92:95], v[170:173], v[210:213], v[92:95]
	v_mfma_f32_16x16x32_bf16 v[88:91], v[174:177], v[206:209], v[88:91]
	v_mfma_f32_16x16x32_bf16 v[88:91], v[178:181], v[210:213], v[88:91]
	v_mfma_f32_16x16x32_bf16 v[84:87], v[182:185], v[206:209], v[84:87]
	v_mfma_f32_16x16x32_bf16 v[84:87], v[186:189], v[210:213], v[84:87]
	v_mfma_f32_16x16x32_bf16 v[68:71], v[182:185], v[214:217], v[68:71]
	v_mfma_f32_16x16x32_bf16 v[68:71], v[186:189], v[218:221], v[68:71]
	v_mfma_f32_16x16x32_bf16 v[72:75], v[174:177], v[214:217], v[72:75]
	v_mfma_f32_16x16x32_bf16 v[72:75], v[178:181], v[218:221], v[72:75]
	v_mfma_f32_16x16x32_bf16 v[76:79], v[166:169], v[214:217], v[76:79]
	v_mfma_f32_16x16x32_bf16 v[76:79], v[170:173], v[218:221], v[76:79]
	v_mfma_f32_16x16x32_bf16 v[80:83], v[150:153], v[214:217], v[80:83]
	v_mfma_f32_16x16x32_bf16 v[80:83], v[162:165], v[218:221], v[80:83]
	s_setprio 0
	s_barrier
	s_add_i32 s0, s62, s41
	s_mov_b32 m0, s0
	ds_read_b128 v[190:193], v158 offset:16384
	ds_read_b128 v[194:197], v158 offset:17408
	ds_read_b128 v[198:201], v158 offset:18432
	ds_read_b128 v[202:205], v158 offset:19456
	ds_read_b128 v[206:209], v158 offset:20480
	ds_read_b128 v[210:213], v158 offset:21504
	ds_read_b128 v[214:217], v158 offset:22528
	ds_read_b128 v[218:221], v158 offset:23552
	global_load_lds_dwordx4 v136, s[52:53]
	s_add_i32 m0, s0, 0x2000
	s_add_u32 s74, s52, 0x100000
	s_addc_u32 s75, s53, 0
	s_add_i32 s0, s63, s41
	global_load_lds_dwordx4 v140, s[52:53]
	s_mov_b32 m0, s0
	s_nop 0
	global_load_lds_dwordx4 v136, s[74:75]
	s_add_i32 m0, s0, 0x2000
	s_nop 0
	global_load_lds_dwordx4 v140, s[74:75]
	s_mov_b32 m0, s43
	s_nop 0
	global_load_lds_dwordx4 v134, s[54:55]
	s_mov_b32 m0, s48
	s_nop 0
	global_load_lds_dwordx4 v138, s[54:55]
	s_waitcnt vmcnt(8)
	s_waitcnt lgkmcnt(0)
	s_setprio 1
	s_barrier
	v_mfma_f32_16x16x32_bf16 v[64:67], v[150:153], v[190:193], v[64:67]
	v_mfma_f32_16x16x32_bf16 v[64:67], v[162:165], v[194:197], v[64:67]
	v_mfma_f32_16x16x32_bf16 v[60:63], v[166:169], v[190:193], v[60:63]
	v_mfma_f32_16x16x32_bf16 v[60:63], v[170:173], v[194:197], v[60:63]
	v_mfma_f32_16x16x32_bf16 v[56:59], v[174:177], v[190:193], v[56:59]
	v_mfma_f32_16x16x32_bf16 v[56:59], v[178:181], v[194:197], v[56:59]
	v_mfma_f32_16x16x32_bf16 v[52:55], v[182:185], v[190:193], v[52:55]
	v_mfma_f32_16x16x32_bf16 v[52:55], v[186:189], v[194:197], v[52:55]
	v_mfma_f32_16x16x32_bf16 v[36:39], v[182:185], v[198:201], v[36:39]
	v_mfma_f32_16x16x32_bf16 v[36:39], v[186:189], v[202:205], v[36:39]
	v_mfma_f32_16x16x32_bf16 v[40:43], v[174:177], v[198:201], v[40:43]
	v_mfma_f32_16x16x32_bf16 v[40:43], v[178:181], v[202:205], v[40:43]
	v_mfma_f32_16x16x32_bf16 v[44:47], v[166:169], v[198:201], v[44:47]
	v_mfma_f32_16x16x32_bf16 v[44:47], v[170:173], v[202:205], v[44:47]
	v_mfma_f32_16x16x32_bf16 v[48:51], v[150:153], v[198:201], v[48:51]
	v_mfma_f32_16x16x32_bf16 v[48:51], v[162:165], v[202:205], v[48:51]
	v_mfma_f32_16x16x32_bf16 v[32:35], v[150:153], v[206:209], v[32:35]
	v_mfma_f32_16x16x32_bf16 v[32:35], v[162:165], v[210:213], v[32:35]
	v_mfma_f32_16x16x32_bf16 v[28:31], v[166:169], v[206:209], v[28:31]
	v_mfma_f32_16x16x32_bf16 v[28:31], v[170:173], v[210:213], v[28:31]
	v_mfma_f32_16x16x32_bf16 v[24:27], v[174:177], v[206:209], v[24:27]
	v_mfma_f32_16x16x32_bf16 v[24:27], v[178:181], v[210:213], v[24:27]
	v_mfma_f32_16x16x32_bf16 v[20:23], v[182:185], v[206:209], v[20:23]
	v_mfma_f32_16x16x32_bf16 v[20:23], v[186:189], v[210:213], v[20:23]
	v_mfma_f32_16x16x32_bf16 v[4:7], v[182:185], v[214:217], v[4:7]
	v_mfma_f32_16x16x32_bf16 v[4:7], v[186:189], v[218:221], v[4:7]
	v_mfma_f32_16x16x32_bf16 v[8:11], v[174:177], v[214:217], v[8:11]
	v_mfma_f32_16x16x32_bf16 v[8:11], v[178:181], v[218:221], v[8:11]
	v_mfma_f32_16x16x32_bf16 v[12:15], v[166:169], v[214:217], v[12:15]
	v_mfma_f32_16x16x32_bf16 v[12:15], v[170:173], v[218:221], v[12:15]
	v_mfma_f32_16x16x32_bf16 v[16:19], v[150:153], v[214:217], v[16:19]
	v_mfma_f32_16x16x32_bf16 v[16:19], v[162:165], v[218:221], v[16:19]
	s_setprio 0
	s_barrier
	s_add_i32 s0, 0, 0x18000
	v_add_u32_e32 v161, s0, v133
	s_add_i32 s73, 0, 0x1c000
	ds_read_b128 v[150:153], v161
	ds_read_b128 v[162:165], v161 offset:1024
	ds_read_b128 v[166:169], v161 offset:2048
	ds_read_b128 v[170:173], v161 offset:3072
	v_add_u32_e32 v161, s73, v133
	ds_read_b128 v[174:177], v161
	ds_read_b128 v[178:181], v161 offset:1024
	ds_read_b128 v[182:185], v161 offset:2048
	ds_read_b128 v[186:189], v161 offset:3072
	s_add_u32 s98, s54, 0x100000
	s_addc_u32 s99, s55, 0
	s_mov_b32 m0, s49
	ds_read_b128 v[190:193], v158 offset:32768
	ds_read_b128 v[194:197], v158 offset:33792
	ds_read_b128 v[198:201], v158 offset:34816
	ds_read_b128 v[202:205], v158 offset:35840
	ds_read_b128 v[206:209], v158 offset:36864
	ds_read_b128 v[210:213], v158 offset:37888
	ds_read_b128 v[214:217], v158 offset:38912
	ds_read_b128 v[218:221], v158 offset:39936
	global_load_lds_dwordx4 v134, s[98:99]
	s_mov_b32 m0, s56
	s_nop 0
	global_load_lds_dwordx4 v138, s[98:99]
	s_waitcnt vmcnt(8)
	s_waitcnt lgkmcnt(0)
	s_setprio 1
	s_barrier
	v_mfma_f32_16x16x32_bf16 v[128:131], v[150:153], v[190:193], v[128:131]
	v_mfma_f32_16x16x32_bf16 v[128:131], v[162:165], v[194:197], v[128:131]
	v_mfma_f32_16x16x32_bf16 v[124:127], v[166:169], v[190:193], v[124:127]
	v_mfma_f32_16x16x32_bf16 v[124:127], v[170:173], v[194:197], v[124:127]
	v_mfma_f32_16x16x32_bf16 v[120:123], v[174:177], v[190:193], v[120:123]
	v_mfma_f32_16x16x32_bf16 v[120:123], v[178:181], v[194:197], v[120:123]
	v_mfma_f32_16x16x32_bf16 v[116:119], v[182:185], v[190:193], v[116:119]
	v_mfma_f32_16x16x32_bf16 v[116:119], v[186:189], v[194:197], v[116:119]
	v_mfma_f32_16x16x32_bf16 v[100:103], v[182:185], v[198:201], v[100:103]
	v_mfma_f32_16x16x32_bf16 v[100:103], v[186:189], v[202:205], v[100:103]
	v_mfma_f32_16x16x32_bf16 v[104:107], v[174:177], v[198:201], v[104:107]
	v_mfma_f32_16x16x32_bf16 v[104:107], v[178:181], v[202:205], v[104:107]
	v_mfma_f32_16x16x32_bf16 v[108:111], v[166:169], v[198:201], v[108:111]
	v_mfma_f32_16x16x32_bf16 v[108:111], v[170:173], v[202:205], v[108:111]
	v_mfma_f32_16x16x32_bf16 v[112:115], v[150:153], v[198:201], v[112:115]
	v_mfma_f32_16x16x32_bf16 v[112:115], v[162:165], v[202:205], v[112:115]
	v_mfma_f32_16x16x32_bf16 v[96:99], v[150:153], v[206:209], v[96:99]
	v_mfma_f32_16x16x32_bf16 v[96:99], v[162:165], v[210:213], v[96:99]
	v_mfma_f32_16x16x32_bf16 v[92:95], v[166:169], v[206:209], v[92:95]
	v_mfma_f32_16x16x32_bf16 v[92:95], v[170:173], v[210:213], v[92:95]
	v_mfma_f32_16x16x32_bf16 v[88:91], v[174:177], v[206:209], v[88:91]
	v_mfma_f32_16x16x32_bf16 v[88:91], v[178:181], v[210:213], v[88:91]
	v_mfma_f32_16x16x32_bf16 v[84:87], v[182:185], v[206:209], v[84:87]
	v_mfma_f32_16x16x32_bf16 v[84:87], v[186:189], v[210:213], v[84:87]
	v_mfma_f32_16x16x32_bf16 v[68:71], v[182:185], v[214:217], v[68:71]
	v_mfma_f32_16x16x32_bf16 v[68:71], v[186:189], v[218:221], v[68:71]
	v_mfma_f32_16x16x32_bf16 v[72:75], v[174:177], v[214:217], v[72:75]
	v_mfma_f32_16x16x32_bf16 v[72:75], v[178:181], v[218:221], v[72:75]
	v_mfma_f32_16x16x32_bf16 v[76:79], v[166:169], v[214:217], v[76:79]
	v_mfma_f32_16x16x32_bf16 v[76:79], v[170:173], v[218:221], v[76:79]
	v_mfma_f32_16x16x32_bf16 v[80:83], v[150:153], v[214:217], v[80:83]
	v_mfma_f32_16x16x32_bf16 v[80:83], v[162:165], v[218:221], v[80:83]
	s_setprio 0
	s_barrier
	s_add_i32 s0, s0, s41
	s_add_i32 m0, s0, 0xffffff80
	ds_read_b128 v[190:193], v158 offset:49152
	ds_read_b128 v[194:197], v158 offset:50176
	ds_read_b128 v[198:201], v158 offset:51200
	ds_read_b128 v[202:205], v158 offset:52224
	ds_read_b128 v[206:209], v158 offset:53248
	ds_read_b128 v[210:213], v158 offset:54272
	ds_read_b128 v[214:217], v158 offset:55296
	ds_read_b128 v[218:221], v158 offset:56320
	global_load_lds_dwordx4 v136, s[52:53] offset:128
	s_add_i32 m0, s0, 0x1f80
	s_add_i32 s0, s73, s41
	global_load_lds_dwordx4 v140, s[52:53] offset:128
	s_add_u32 s52, s52, 0x100080
	s_addc_u32 s53, s53, 0
	s_mov_b32 m0, s0
	s_nop 0
	global_load_lds_dwordx4 v136, s[52:53]
	s_add_i32 m0, s0, 0x2000
	s_nop 0
	global_load_lds_dwordx4 v140, s[52:53]
	s_add_i32 m0, s59, 0xffffff80
	s_nop 0
	global_load_lds_dwordx4 v134, s[54:55] offset:128
	s_add_i32 m0, s60, 0xffffff80
	s_nop 0
	global_load_lds_dwordx4 v138, s[54:55] offset:128
	s_waitcnt vmcnt(8)
	s_waitcnt lgkmcnt(0)
	s_setprio 1
	s_barrier
	v_mfma_f32_16x16x32_bf16 v[64:67], v[150:153], v[190:193], v[64:67]
	v_mfma_f32_16x16x32_bf16 v[64:67], v[162:165], v[194:197], v[64:67]
	v_mfma_f32_16x16x32_bf16 v[60:63], v[166:169], v[190:193], v[60:63]
	v_mfma_f32_16x16x32_bf16 v[60:63], v[170:173], v[194:197], v[60:63]
	v_mfma_f32_16x16x32_bf16 v[56:59], v[174:177], v[190:193], v[56:59]
	v_mfma_f32_16x16x32_bf16 v[56:59], v[178:181], v[194:197], v[56:59]
	v_mfma_f32_16x16x32_bf16 v[52:55], v[182:185], v[190:193], v[52:55]
	v_mfma_f32_16x16x32_bf16 v[52:55], v[186:189], v[194:197], v[52:55]
	v_mfma_f32_16x16x32_bf16 v[36:39], v[182:185], v[198:201], v[36:39]
	v_mfma_f32_16x16x32_bf16 v[36:39], v[186:189], v[202:205], v[36:39]
	v_mfma_f32_16x16x32_bf16 v[40:43], v[174:177], v[198:201], v[40:43]
	v_mfma_f32_16x16x32_bf16 v[40:43], v[178:181], v[202:205], v[40:43]
	v_mfma_f32_16x16x32_bf16 v[44:47], v[166:169], v[198:201], v[44:47]
	v_mfma_f32_16x16x32_bf16 v[44:47], v[170:173], v[202:205], v[44:47]
	v_mfma_f32_16x16x32_bf16 v[48:51], v[150:153], v[198:201], v[48:51]
	v_mfma_f32_16x16x32_bf16 v[48:51], v[162:165], v[202:205], v[48:51]
	v_mfma_f32_16x16x32_bf16 v[32:35], v[150:153], v[206:209], v[32:35]
	v_mfma_f32_16x16x32_bf16 v[32:35], v[162:165], v[210:213], v[32:35]
	v_mfma_f32_16x16x32_bf16 v[28:31], v[166:169], v[206:209], v[28:31]
	v_mfma_f32_16x16x32_bf16 v[28:31], v[170:173], v[210:213], v[28:31]
	v_mfma_f32_16x16x32_bf16 v[24:27], v[174:177], v[206:209], v[24:27]
	v_mfma_f32_16x16x32_bf16 v[24:27], v[178:181], v[210:213], v[24:27]
	v_mfma_f32_16x16x32_bf16 v[20:23], v[182:185], v[206:209], v[20:23]
	v_mfma_f32_16x16x32_bf16 v[20:23], v[186:189], v[210:213], v[20:23]
	v_mfma_f32_16x16x32_bf16 v[4:7], v[182:185], v[214:217], v[4:7]
	v_mfma_f32_16x16x32_bf16 v[4:7], v[186:189], v[218:221], v[4:7]
	v_mfma_f32_16x16x32_bf16 v[8:11], v[174:177], v[214:217], v[8:11]
	v_mfma_f32_16x16x32_bf16 v[8:11], v[178:181], v[218:221], v[8:11]
	v_mfma_f32_16x16x32_bf16 v[12:15], v[166:169], v[214:217], v[12:15]
	v_mfma_f32_16x16x32_bf16 v[12:15], v[170:173], v[218:221], v[12:15]
	v_mfma_f32_16x16x32_bf16 v[16:19], v[150:153], v[214:217], v[16:19]
	v_mfma_f32_16x16x32_bf16 v[16:19], v[162:165], v[218:221], v[16:19]
	s_setprio 0
	s_barrier
	s_add_i32 s72, s72, 2
	s_add_u32 s50, s50, 0x100
	s_addc_u32 s51, s51, 0
	s_add_u32 s70, s70, 0x100
	s_addc_u32 s71, s71, 0
	s_cmp_gt_u32 s72, 61
	s_cbranch_scc0 .LBB0_429
	s_and_b64 vcc, exec, s[22:23]
	s_cbranch_vccz .LBB0_432
	s_barrier

.LBB0_1032:
	v_add_u32_e32 v5, s60, v3
	ds_read_b128 v[140:143], v5
	ds_read_b128 v[144:147], v5 offset:1024
	ds_read_b128 v[148:151], v5 offset:2048
	ds_read_b128 v[152:155], v5 offset:3072
	v_add_u32_e32 v5, s61, v3
	ds_read_b128 v[156:159], v5
	ds_read_b128 v[160:163], v5 offset:1024
	ds_read_b128 v[164:167], v5 offset:2048
	ds_read_b128 v[168:171], v5 offset:3072
	s_add_u32 s42, s40, 0xfff80080
	s_addc_u32 s43, s41, -1
	s_cmp_eq_u32 s67, 28
	s_cselect_b32 s51, s5, s43
	s_cselect_b32 s50, s7, s42
	s_cselect_b32 s43, s25, s66
	s_cselect_b32 s42, s27, s65
	s_add_i32 m0, s47, 0xc000
	ds_read_b128 v[172:175], v246
	ds_read_b128 v[176:179], v246 offset:1024
	ds_read_b128 v[180:183], v246 offset:2048
	ds_read_b128 v[184:187], v246 offset:3072
	ds_read_b128 v[188:191], v246 offset:4096
	ds_read_b128 v[192:195], v246 offset:5120
	ds_read_b128 v[196:199], v246 offset:6144
	ds_read_b128 v[200:203], v246 offset:7168
	global_load_lds_dwordx4 v216, s[40:41]
	s_add_i32 m0, s47, 0xe000
	s_nop 0
	global_load_lds_dwordx4 v218, s[40:41]
	s_waitcnt vmcnt(8)
	s_waitcnt lgkmcnt(0)
	s_setprio 1
	s_barrier
	v_mfma_f32_16x16x32_bf16 v[136:139], v[140:143], v[172:175], v[136:139]
	v_mfma_f32_16x16x32_bf16 v[136:139], v[144:147], v[176:179], v[136:139]
	v_mfma_f32_16x16x32_bf16 v[132:135], v[148:151], v[172:175], v[132:135]
	v_mfma_f32_16x16x32_bf16 v[132:135], v[152:155], v[176:179], v[132:135]
	v_mfma_f32_16x16x32_bf16 v[104:107], v[156:159], v[172:175], v[104:107]
	v_mfma_f32_16x16x32_bf16 v[104:107], v[160:163], v[176:179], v[104:107]
	v_mfma_f32_16x16x32_bf16 v[100:103], v[164:167], v[172:175], v[100:103]
	v_mfma_f32_16x16x32_bf16 v[100:103], v[168:171], v[176:179], v[100:103]
	v_mfma_f32_16x16x32_bf16 v[92:95], v[164:167], v[180:183], v[92:95]
	v_mfma_f32_16x16x32_bf16 v[92:95], v[168:171], v[184:187], v[92:95]
	v_mfma_f32_16x16x32_bf16 v[96:99], v[156:159], v[180:183], v[96:99]
	v_mfma_f32_16x16x32_bf16 v[96:99], v[160:163], v[184:187], v[96:99]
	v_mfma_f32_16x16x32_bf16 v[124:127], v[148:151], v[180:183], v[124:127]
	v_mfma_f32_16x16x32_bf16 v[124:127], v[152:155], v[184:187], v[124:127]
	v_mfma_f32_16x16x32_bf16 v[128:131], v[140:143], v[180:183], v[128:131]
	v_mfma_f32_16x16x32_bf16 v[128:131], v[144:147], v[184:187], v[128:131]
	v_mfma_f32_16x16x32_bf16 v[120:123], v[140:143], v[188:191], v[120:123]
	v_mfma_f32_16x16x32_bf16 v[120:123], v[144:147], v[192:195], v[120:123]
	v_mfma_f32_16x16x32_bf16 v[116:119], v[148:151], v[188:191], v[116:119]
	v_mfma_f32_16x16x32_bf16 v[116:119], v[152:155], v[192:195], v[116:119]
	v_mfma_f32_16x16x32_bf16 v[88:91], v[156:159], v[188:191], v[88:91]
	v_mfma_f32_16x16x32_bf16 v[88:91], v[160:163], v[192:195], v[88:91]
	v_mfma_f32_16x16x32_bf16 v[84:87], v[164:167], v[188:191], v[84:87]
	v_mfma_f32_16x16x32_bf16 v[84:87], v[168:171], v[192:195], v[84:87]
	v_mfma_f32_16x16x32_bf16 v[76:79], v[164:167], v[196:199], v[76:79]
	v_mfma_f32_16x16x32_bf16 v[76:79], v[168:171], v[200:203], v[76:79]
	v_mfma_f32_16x16x32_bf16 v[80:83], v[156:159], v[196:199], v[80:83]
	v_mfma_f32_16x16x32_bf16 v[80:83], v[160:163], v[200:203], v[80:83]
	v_mfma_f32_16x16x32_bf16 v[108:111], v[148:151], v[196:199], v[108:111]
	v_mfma_f32_16x16x32_bf16 v[108:111], v[152:155], v[200:203], v[108:111]
	v_mfma_f32_16x16x32_bf16 v[112:115], v[140:143], v[196:199], v[112:115]
	v_mfma_f32_16x16x32_bf16 v[112:115], v[144:147], v[200:203], v[112:115]
	s_setprio 0
	s_barrier
	s_add_i32 s68, s60, s46
	s_mov_b32 m0, s68
	ds_read_b128 v[172:175], v246 offset:16384
	ds_read_b128 v[176:179], v246 offset:17408
	ds_read_b128 v[180:183], v246 offset:18432
	ds_read_b128 v[184:187], v246 offset:19456
	ds_read_b128 v[188:191], v246 offset:20480
	ds_read_b128 v[192:195], v246 offset:21504
	ds_read_b128 v[196:199], v246 offset:22528
	ds_read_b128 v[200:203], v246 offset:23552
	global_load_lds_dwordx4 v210, s[42:43]
	s_add_i32 m0, s68, 0x2000
	s_add_u32 s70, s42, 0x80000
	s_addc_u32 s71, s43, 0
	s_add_i32 s68, s61, s46
	global_load_lds_dwordx4 v214, s[42:43]
	s_mov_b32 m0, s68
	s_nop 0
	global_load_lds_dwordx4 v210, s[70:71]
	s_add_i32 m0, s68, 0x2000
	s_nop 0
	global_load_lds_dwordx4 v214, s[70:71]
	s_mov_b32 m0, s47
	s_nop 0
	global_load_lds_dwordx4 v208, s[50:51]
	s_mov_b32 m0, s48
	s_nop 0
	global_load_lds_dwordx4 v212, s[50:51]
	s_waitcnt vmcnt(8)
	s_waitcnt lgkmcnt(0)
	s_setprio 1
	s_barrier
	v_mfma_f32_16x16x32_bf16 v[72:75], v[140:143], v[172:175], v[72:75]
	v_mfma_f32_16x16x32_bf16 v[72:75], v[144:147], v[176:179], v[72:75]
	v_mfma_f32_16x16x32_bf16 v[68:71], v[148:151], v[172:175], v[68:71]
	v_mfma_f32_16x16x32_bf16 v[68:71], v[152:155], v[176:179], v[68:71]
	v_mfma_f32_16x16x32_bf16 v[40:43], v[156:159], v[172:175], v[40:43]
	v_mfma_f32_16x16x32_bf16 v[40:43], v[160:163], v[176:179], v[40:43]
	v_mfma_f32_16x16x32_bf16 v[36:39], v[164:167], v[172:175], v[36:39]
	v_mfma_f32_16x16x32_bf16 v[36:39], v[168:171], v[176:179], v[36:39]
	v_mfma_f32_16x16x32_bf16 v[28:31], v[164:167], v[180:183], v[28:31]
	v_mfma_f32_16x16x32_bf16 v[28:31], v[168:171], v[184:187], v[28:31]
	v_mfma_f32_16x16x32_bf16 v[32:35], v[156:159], v[180:183], v[32:35]
	v_mfma_f32_16x16x32_bf16 v[32:35], v[160:163], v[184:187], v[32:35]
	v_mfma_f32_16x16x32_bf16 v[60:63], v[148:151], v[180:183], v[60:63]
	v_mfma_f32_16x16x32_bf16 v[60:63], v[152:155], v[184:187], v[60:63]
	v_mfma_f32_16x16x32_bf16 v[64:67], v[140:143], v[180:183], v[64:67]
	v_mfma_f32_16x16x32_bf16 v[64:67], v[144:147], v[184:187], v[64:67]
	v_mfma_f32_16x16x32_bf16 v[56:59], v[140:143], v[188:191], v[56:59]
	v_mfma_f32_16x16x32_bf16 v[56:59], v[144:147], v[192:195], v[56:59]
	v_mfma_f32_16x16x32_bf16 v[52:55], v[148:151], v[188:191], v[52:55]
	v_mfma_f32_16x16x32_bf16 v[52:55], v[152:155], v[192:195], v[52:55]
	v_mfma_f32_16x16x32_bf16 v[24:27], v[156:159], v[188:191], v[24:27]
	v_mfma_f32_16x16x32_bf16 v[24:27], v[160:163], v[192:195], v[24:27]
	v_mfma_f32_16x16x32_bf16 v[20:23], v[164:167], v[188:191], v[20:23]
	v_mfma_f32_16x16x32_bf16 v[20:23], v[168:171], v[192:195], v[20:23]
	v_mfma_f32_16x16x32_bf16 v[12:15], v[164:167], v[196:199], v[12:15]
	v_mfma_f32_16x16x32_bf16 v[12:15], v[168:171], v[200:203], v[12:15]
	v_mfma_f32_16x16x32_bf16 v[16:19], v[156:159], v[196:199], v[16:19]
	v_mfma_f32_16x16x32_bf16 v[16:19], v[160:163], v[200:203], v[16:19]
	v_mfma_f32_16x16x32_bf16 v[44:47], v[148:151], v[196:199], v[44:47]
	v_mfma_f32_16x16x32_bf16 v[44:47], v[152:155], v[200:203], v[44:47]
	v_mfma_f32_16x16x32_bf16 v[48:51], v[140:143], v[196:199], v[48:51]
	v_mfma_f32_16x16x32_bf16 v[48:51], v[144:147], v[200:203], v[48:51]
	s_setprio 0
	s_barrier
	s_add_i32 s68, 0, 0x18000
	v_add_u32_e32 v5, s68, v3
	s_add_i32 s70, 0, 0x1c000
	ds_read_b128 v[140:143], v5
	ds_read_b128 v[144:147], v5 offset:1024
	ds_read_b128 v[148:151], v5 offset:2048
	ds_read_b128 v[152:155], v5 offset:3072
	v_add_u32_e32 v5, s70, v3
	ds_read_b128 v[156:159], v5
	ds_read_b128 v[160:163], v5 offset:1024
	ds_read_b128 v[164:167], v5 offset:2048
	ds_read_b128 v[168:171], v5 offset:3072
	s_add_u32 s98, s50, 0x80000
	s_addc_u32 s99, s51, 0
	s_mov_b64 s[100:101], s[50:51]
	s_mov_b32 m0, s49
	ds_read_b128 v[172:175], v246 offset:32768
	ds_read_b128 v[176:179], v246 offset:33792
	ds_read_b128 v[180:183], v246 offset:34816
	ds_read_b128 v[184:187], v246 offset:35840
	ds_read_b128 v[188:191], v246 offset:36864
	ds_read_b128 v[192:195], v246 offset:37888
	ds_read_b128 v[196:199], v246 offset:38912
	ds_read_b128 v[200:203], v246 offset:39936
	global_load_lds_dwordx4 v208, s[98:99]
	s_mov_b32 m0, s52
	s_nop 0
	global_load_lds_dwordx4 v212, s[98:99]
	s_waitcnt vmcnt(8)
	s_waitcnt lgkmcnt(0)
	s_setprio 1
	s_barrier
	v_mfma_f32_16x16x32_bf16 v[136:139], v[140:143], v[172:175], v[136:139]
	v_mfma_f32_16x16x32_bf16 v[136:139], v[144:147], v[176:179], v[136:139]
	v_mfma_f32_16x16x32_bf16 v[132:135], v[148:151], v[172:175], v[132:135]
	v_mfma_f32_16x16x32_bf16 v[132:135], v[152:155], v[176:179], v[132:135]
	v_mfma_f32_16x16x32_bf16 v[104:107], v[156:159], v[172:175], v[104:107]
	v_mfma_f32_16x16x32_bf16 v[104:107], v[160:163], v[176:179], v[104:107]
	v_mfma_f32_16x16x32_bf16 v[100:103], v[164:167], v[172:175], v[100:103]
	v_mfma_f32_16x16x32_bf16 v[100:103], v[168:171], v[176:179], v[100:103]
	v_mfma_f32_16x16x32_bf16 v[92:95], v[164:167], v[180:183], v[92:95]
	v_mfma_f32_16x16x32_bf16 v[92:95], v[168:171], v[184:187], v[92:95]
	v_mfma_f32_16x16x32_bf16 v[96:99], v[156:159], v[180:183], v[96:99]
	v_mfma_f32_16x16x32_bf16 v[96:99], v[160:163], v[184:187], v[96:99]
	v_mfma_f32_16x16x32_bf16 v[124:127], v[148:151], v[180:183], v[124:127]
	v_mfma_f32_16x16x32_bf16 v[124:127], v[152:155], v[184:187], v[124:127]
	v_mfma_f32_16x16x32_bf16 v[128:131], v[140:143], v[180:183], v[128:131]
	v_mfma_f32_16x16x32_bf16 v[128:131], v[144:147], v[184:187], v[128:131]
	v_mfma_f32_16x16x32_bf16 v[120:123], v[140:143], v[188:191], v[120:123]
	v_mfma_f32_16x16x32_bf16 v[120:123], v[144:147], v[192:195], v[120:123]
	v_mfma_f32_16x16x32_bf16 v[116:119], v[148:151], v[188:191], v[116:119]
	v_mfma_f32_16x16x32_bf16 v[116:119], v[152:155], v[192:195], v[116:119]
	v_mfma_f32_16x16x32_bf16 v[88:91], v[156:159], v[188:191], v[88:91]
	v_mfma_f32_16x16x32_bf16 v[88:91], v[160:163], v[192:195], v[88:91]
	v_mfma_f32_16x16x32_bf16 v[84:87], v[164:167], v[188:191], v[84:87]
	v_mfma_f32_16x16x32_bf16 v[84:87], v[168:171], v[192:195], v[84:87]
	v_mfma_f32_16x16x32_bf16 v[76:79], v[164:167], v[196:199], v[76:79]
	v_mfma_f32_16x16x32_bf16 v[76:79], v[168:171], v[200:203], v[76:79]
	v_mfma_f32_16x16x32_bf16 v[80:83], v[156:159], v[196:199], v[80:83]
	v_mfma_f32_16x16x32_bf16 v[80:83], v[160:163], v[200:203], v[80:83]
	v_mfma_f32_16x16x32_bf16 v[108:111], v[148:151], v[196:199], v[108:111]
	v_mfma_f32_16x16x32_bf16 v[108:111], v[152:155], v[200:203], v[108:111]
	v_mfma_f32_16x16x32_bf16 v[112:115], v[140:143], v[196:199], v[112:115]
	v_mfma_f32_16x16x32_bf16 v[112:115], v[144:147], v[200:203], v[112:115]
	s_setprio 0
	s_barrier
	s_add_i32 s50, s68, s46
	s_add_i32 m0, s50, 0xffffff80
	ds_read_b128 v[172:175], v246 offset:49152
	ds_read_b128 v[176:179], v246 offset:50176
	ds_read_b128 v[180:183], v246 offset:51200
	ds_read_b128 v[184:187], v246 offset:52224
	ds_read_b128 v[188:191], v246 offset:53248
	ds_read_b128 v[192:195], v246 offset:54272
	ds_read_b128 v[196:199], v246 offset:55296
	ds_read_b128 v[200:203], v246 offset:56320
	global_load_lds_dwordx4 v210, s[42:43] offset:128
	s_add_i32 m0, s50, 0x1f80
	s_add_i32 s50, s70, s46
	global_load_lds_dwordx4 v214, s[42:43] offset:128
	s_add_u32 s42, s42, 0x80080
	s_addc_u32 s43, s43, 0
	s_mov_b32 m0, s50
	s_nop 0
	global_load_lds_dwordx4 v210, s[42:43]
	s_add_i32 m0, s50, 0x2000
	s_nop 0
	global_load_lds_dwordx4 v214, s[42:43]
	s_add_i32 m0, s58, 0xffffff80
	s_nop 0
	global_load_lds_dwordx4 v208, s[100:101] offset:128
	s_add_i32 m0, s59, 0xffffff80
	s_nop 0
	global_load_lds_dwordx4 v212, s[100:101] offset:128
	s_waitcnt vmcnt(8)
	s_waitcnt lgkmcnt(0)
	s_setprio 1
	s_barrier
	v_mfma_f32_16x16x32_bf16 v[72:75], v[140:143], v[172:175], v[72:75]
	v_mfma_f32_16x16x32_bf16 v[72:75], v[144:147], v[176:179], v[72:75]
	v_mfma_f32_16x16x32_bf16 v[68:71], v[148:151], v[172:175], v[68:71]
	v_mfma_f32_16x16x32_bf16 v[68:71], v[152:155], v[176:179], v[68:71]
	v_mfma_f32_16x16x32_bf16 v[40:43], v[156:159], v[172:175], v[40:43]
	v_mfma_f32_16x16x32_bf16 v[40:43], v[160:163], v[176:179], v[40:43]
	v_mfma_f32_16x16x32_bf16 v[36:39], v[164:167], v[172:175], v[36:39]
	v_mfma_f32_16x16x32_bf16 v[36:39], v[168:171], v[176:179], v[36:39]
	v_mfma_f32_16x16x32_bf16 v[28:31], v[164:167], v[180:183], v[28:31]
	v_mfma_f32_16x16x32_bf16 v[28:31], v[168:171], v[184:187], v[28:31]
	v_mfma_f32_16x16x32_bf16 v[32:35], v[156:159], v[180:183], v[32:35]
	v_mfma_f32_16x16x32_bf16 v[32:35], v[160:163], v[184:187], v[32:35]
	v_mfma_f32_16x16x32_bf16 v[60:63], v[148:151], v[180:183], v[60:63]
	v_mfma_f32_16x16x32_bf16 v[60:63], v[152:155], v[184:187], v[60:63]
	v_mfma_f32_16x16x32_bf16 v[64:67], v[140:143], v[180:183], v[64:67]
	v_mfma_f32_16x16x32_bf16 v[64:67], v[144:147], v[184:187], v[64:67]
	v_mfma_f32_16x16x32_bf16 v[56:59], v[140:143], v[188:191], v[56:59]
	v_mfma_f32_16x16x32_bf16 v[56:59], v[144:147], v[192:195], v[56:59]
	v_mfma_f32_16x16x32_bf16 v[52:55], v[148:151], v[188:191], v[52:55]
	v_mfma_f32_16x16x32_bf16 v[52:55], v[152:155], v[192:195], v[52:55]
	v_mfma_f32_16x16x32_bf16 v[24:27], v[156:159], v[188:191], v[24:27]
	v_mfma_f32_16x16x32_bf16 v[24:27], v[160:163], v[192:195], v[24:27]
	v_mfma_f32_16x16x32_bf16 v[20:23], v[164:167], v[188:191], v[20:23]
	v_mfma_f32_16x16x32_bf16 v[20:23], v[168:171], v[192:195], v[20:23]
	v_mfma_f32_16x16x32_bf16 v[12:15], v[164:167], v[196:199], v[12:15]
	v_mfma_f32_16x16x32_bf16 v[12:15], v[168:171], v[200:203], v[12:15]
	v_mfma_f32_16x16x32_bf16 v[16:19], v[156:159], v[196:199], v[16:19]
	v_mfma_f32_16x16x32_bf16 v[16:19], v[160:163], v[200:203], v[16:19]
	v_mfma_f32_16x16x32_bf16 v[44:47], v[148:151], v[196:199], v[44:47]
	v_mfma_f32_16x16x32_bf16 v[44:47], v[152:155], v[200:203], v[44:47]
	v_mfma_f32_16x16x32_bf16 v[48:51], v[140:143], v[196:199], v[48:51]
	v_mfma_f32_16x16x32_bf16 v[48:51], v[144:147], v[200:203], v[48:51]
	s_setprio 0
	s_barrier
	s_add_i32 s67, s67, 2
	s_add_u32 s40, s40, 0x100
	s_addc_u32 s41, s41, 0
	s_add_u32 s65, s65, 0x100
	s_addc_u32 s66, s66, 0
	s_cmp_gt_u32 s67, 29
	s_cbranch_scc0 .LBB0_1032
	s_and_b64 vcc, exec, s[22:23]
	s_cbranch_vccz .LBB0_1035
	s_barrier

.LBB0_1203:
	ds_read_b128 v[132:135], v187
	ds_read_b128 v[136:139], v187 offset:1024
	ds_read_b128 v[140:143], v187 offset:2048
	ds_read_b128 v[144:147], v187 offset:3072
	ds_read_b128 v[148:151], v188
	ds_read_b128 v[152:155], v188 offset:1024
	ds_read_b128 v[172:175], v188 offset:2048
	ds_read_b128 v[176:179], v188 offset:3072
	s_add_u32 s0, s42, 0xfff00080
	s_addc_u32 s50, s43, -1
	s_cmp_eq_u32 s65, 60
	s_cselect_b32 s53, s25, s50
	s_cselect_b32 s52, s31, s0
	s_cselect_b32 s51, s23, s64
	s_cselect_b32 s50, s62, s63
	s_add_i32 m0, s41, 0xc000
	ds_read_b128 v[180:183], v189
	ds_read_b128 v[192:195], v189 offset:1024
	ds_read_b128 v[196:199], v189 offset:2048
	ds_read_b128 v[200:203], v189 offset:3072
	ds_read_b128 v[204:207], v189 offset:4096
	ds_read_b128 v[208:211], v189 offset:5120
	ds_read_b128 v[212:215], v189 offset:6144
	ds_read_b128 v[216:219], v189 offset:7168
	global_load_lds_dwordx4 v164, s[42:43]
	s_add_i32 m0, s41, 0xe000
	s_nop 0
	global_load_lds_dwordx4 v166, s[42:43]
	s_waitcnt vmcnt(8)
	s_waitcnt lgkmcnt(0)
	s_setprio 1
	s_barrier
	v_mfma_f32_16x16x32_bf16 v[128:131], v[132:135], v[180:183], v[128:131]
	v_mfma_f32_16x16x32_bf16 v[128:131], v[136:139], v[192:195], v[128:131]
	v_mfma_f32_16x16x32_bf16 v[124:127], v[140:143], v[180:183], v[124:127]
	v_mfma_f32_16x16x32_bf16 v[124:127], v[144:147], v[192:195], v[124:127]
	v_mfma_f32_16x16x32_bf16 v[120:123], v[148:151], v[180:183], v[120:123]
	v_mfma_f32_16x16x32_bf16 v[120:123], v[152:155], v[192:195], v[120:123]
	v_mfma_f32_16x16x32_bf16 v[116:119], v[172:175], v[180:183], v[116:119]
	v_mfma_f32_16x16x32_bf16 v[116:119], v[176:179], v[192:195], v[116:119]
	v_mfma_f32_16x16x32_bf16 v[100:103], v[172:175], v[196:199], v[100:103]
	v_mfma_f32_16x16x32_bf16 v[100:103], v[176:179], v[200:203], v[100:103]
	v_mfma_f32_16x16x32_bf16 v[104:107], v[148:151], v[196:199], v[104:107]
	v_mfma_f32_16x16x32_bf16 v[104:107], v[152:155], v[200:203], v[104:107]
	v_mfma_f32_16x16x32_bf16 v[108:111], v[140:143], v[196:199], v[108:111]
	v_mfma_f32_16x16x32_bf16 v[108:111], v[144:147], v[200:203], v[108:111]
	v_mfma_f32_16x16x32_bf16 v[112:115], v[132:135], v[196:199], v[112:115]
	v_mfma_f32_16x16x32_bf16 v[112:115], v[136:139], v[200:203], v[112:115]
	v_mfma_f32_16x16x32_bf16 v[96:99], v[132:135], v[204:207], v[96:99]
	v_mfma_f32_16x16x32_bf16 v[96:99], v[136:139], v[208:211], v[96:99]
	v_mfma_f32_16x16x32_bf16 v[92:95], v[140:143], v[204:207], v[92:95]
	v_mfma_f32_16x16x32_bf16 v[92:95], v[144:147], v[208:211], v[92:95]
	v_mfma_f32_16x16x32_bf16 v[88:91], v[148:151], v[204:207], v[88:91]
	v_mfma_f32_16x16x32_bf16 v[88:91], v[152:155], v[208:211], v[88:91]
	v_mfma_f32_16x16x32_bf16 v[84:87], v[172:175], v[204:207], v[84:87]
	v_mfma_f32_16x16x32_bf16 v[84:87], v[176:179], v[208:211], v[84:87]
	v_mfma_f32_16x16x32_bf16 v[68:71], v[172:175], v[212:215], v[68:71]
	v_mfma_f32_16x16x32_bf16 v[68:71], v[176:179], v[216:219], v[68:71]
	v_mfma_f32_16x16x32_bf16 v[72:75], v[148:151], v[212:215], v[72:75]
	v_mfma_f32_16x16x32_bf16 v[72:75], v[152:155], v[216:219], v[72:75]
	v_mfma_f32_16x16x32_bf16 v[76:79], v[140:143], v[212:215], v[76:79]
	v_mfma_f32_16x16x32_bf16 v[76:79], v[144:147], v[216:219], v[76:79]
	v_mfma_f32_16x16x32_bf16 v[80:83], v[132:135], v[212:215], v[80:83]
	v_mfma_f32_16x16x32_bf16 v[80:83], v[136:139], v[216:219], v[80:83]
	s_setprio 0
	s_barrier
	s_add_i32 s0, s59, s46
	s_mov_b32 m0, s0
	ds_read_b128 v[180:183], v189 offset:16384
	ds_read_b128 v[192:195], v189 offset:17408
	ds_read_b128 v[196:199], v189 offset:18432
	ds_read_b128 v[200:203], v189 offset:19456
	ds_read_b128 v[204:207], v189 offset:20480
	ds_read_b128 v[208:211], v189 offset:21504
	ds_read_b128 v[212:215], v189 offset:22528
	ds_read_b128 v[216:219], v189 offset:23552
	global_load_lds_dwordx4 v158, s[50:51]
	s_add_i32 m0, s0, 0x2000
	s_add_u32 s66, s50, 0x100000
	s_addc_u32 s67, s51, 0
	s_add_i32 s0, s60, s46
	global_load_lds_dwordx4 v162, s[50:51]
	s_mov_b32 m0, s0
	s_nop 0
	global_load_lds_dwordx4 v158, s[66:67]
	s_add_i32 m0, s0, 0x2000
	s_nop 0
	global_load_lds_dwordx4 v162, s[66:67]
	s_mov_b32 m0, s41
	s_nop 0
	global_load_lds_dwordx4 v156, s[52:53]
	s_mov_b32 m0, s47
	s_nop 0
	global_load_lds_dwordx4 v160, s[52:53]
	s_waitcnt vmcnt(8)
	s_waitcnt lgkmcnt(0)
	s_setprio 1
	s_barrier
	v_mfma_f32_16x16x32_bf16 v[64:67], v[132:135], v[180:183], v[64:67]
	v_mfma_f32_16x16x32_bf16 v[64:67], v[136:139], v[192:195], v[64:67]
	v_mfma_f32_16x16x32_bf16 v[60:63], v[140:143], v[180:183], v[60:63]
	v_mfma_f32_16x16x32_bf16 v[60:63], v[144:147], v[192:195], v[60:63]
	v_mfma_f32_16x16x32_bf16 v[56:59], v[148:151], v[180:183], v[56:59]
	v_mfma_f32_16x16x32_bf16 v[56:59], v[152:155], v[192:195], v[56:59]
	v_mfma_f32_16x16x32_bf16 v[52:55], v[172:175], v[180:183], v[52:55]
	v_mfma_f32_16x16x32_bf16 v[52:55], v[176:179], v[192:195], v[52:55]
	v_mfma_f32_16x16x32_bf16 v[36:39], v[172:175], v[196:199], v[36:39]
	v_mfma_f32_16x16x32_bf16 v[36:39], v[176:179], v[200:203], v[36:39]
	v_mfma_f32_16x16x32_bf16 v[40:43], v[148:151], v[196:199], v[40:43]
	v_mfma_f32_16x16x32_bf16 v[40:43], v[152:155], v[200:203], v[40:43]
	v_mfma_f32_16x16x32_bf16 v[44:47], v[140:143], v[196:199], v[44:47]
	v_mfma_f32_16x16x32_bf16 v[44:47], v[144:147], v[200:203], v[44:47]
	v_mfma_f32_16x16x32_bf16 v[48:51], v[132:135], v[196:199], v[48:51]
	v_mfma_f32_16x16x32_bf16 v[48:51], v[136:139], v[200:203], v[48:51]
	v_mfma_f32_16x16x32_bf16 v[32:35], v[132:135], v[204:207], v[32:35]
	v_mfma_f32_16x16x32_bf16 v[32:35], v[136:139], v[208:211], v[32:35]
	v_mfma_f32_16x16x32_bf16 v[28:31], v[140:143], v[204:207], v[28:31]
	v_mfma_f32_16x16x32_bf16 v[28:31], v[144:147], v[208:211], v[28:31]
	v_mfma_f32_16x16x32_bf16 v[24:27], v[148:151], v[204:207], v[24:27]
	v_mfma_f32_16x16x32_bf16 v[24:27], v[152:155], v[208:211], v[24:27]
	v_mfma_f32_16x16x32_bf16 v[20:23], v[172:175], v[204:207], v[20:23]
	v_mfma_f32_16x16x32_bf16 v[20:23], v[176:179], v[208:211], v[20:23]
	v_mfma_f32_16x16x32_bf16 v[4:7], v[172:175], v[212:215], v[4:7]
	v_mfma_f32_16x16x32_bf16 v[4:7], v[176:179], v[216:219], v[4:7]
	v_mfma_f32_16x16x32_bf16 v[8:11], v[148:151], v[212:215], v[8:11]
	v_mfma_f32_16x16x32_bf16 v[8:11], v[152:155], v[216:219], v[8:11]
	v_mfma_f32_16x16x32_bf16 v[12:15], v[140:143], v[212:215], v[12:15]
	v_mfma_f32_16x16x32_bf16 v[12:15], v[144:147], v[216:219], v[12:15]
	v_mfma_f32_16x16x32_bf16 v[16:19], v[132:135], v[212:215], v[16:19]
	v_mfma_f32_16x16x32_bf16 v[16:19], v[136:139], v[216:219], v[16:19]
	s_setprio 0
	s_barrier
	s_add_i32 s0, 0, 0x18000
	s_add_i32 s66, 0, 0x1c000
	v_add_u32_e32 v144, s0, v3
	v_add_u32_e32 v176, s66, v3
	ds_read_b128 v[132:135], v144
	ds_read_b128 v[136:139], v144 offset:1024
	ds_read_b128 v[140:143], v144 offset:2048
	ds_read_b128 v[144:147], v144 offset:3072
	ds_read_b128 v[148:151], v176
	ds_read_b128 v[152:155], v176 offset:1024
	ds_read_b128 v[172:175], v176 offset:2048
	ds_read_b128 v[176:179], v176 offset:3072
	s_add_u32 s98, s52, 0x100000
	s_addc_u32 s99, s53, 0
	s_mov_b32 m0, s48
	ds_read_b128 v[180:183], v189 offset:32768
	ds_read_b128 v[192:195], v189 offset:33792
	ds_read_b128 v[196:199], v189 offset:34816
	ds_read_b128 v[200:203], v189 offset:35840
	ds_read_b128 v[204:207], v189 offset:36864
	ds_read_b128 v[208:211], v189 offset:37888
	ds_read_b128 v[212:215], v189 offset:38912
	ds_read_b128 v[216:219], v189 offset:39936
	global_load_lds_dwordx4 v156, s[98:99]
	s_mov_b32 m0, s49
	s_nop 0
	global_load_lds_dwordx4 v160, s[98:99]
	s_waitcnt vmcnt(8)
	s_waitcnt lgkmcnt(0)
	s_setprio 1
	s_barrier
	v_mfma_f32_16x16x32_bf16 v[128:131], v[132:135], v[180:183], v[128:131]
	v_mfma_f32_16x16x32_bf16 v[128:131], v[136:139], v[192:195], v[128:131]
	v_mfma_f32_16x16x32_bf16 v[124:127], v[140:143], v[180:183], v[124:127]
	v_mfma_f32_16x16x32_bf16 v[124:127], v[144:147], v[192:195], v[124:127]
	v_mfma_f32_16x16x32_bf16 v[120:123], v[148:151], v[180:183], v[120:123]
	v_mfma_f32_16x16x32_bf16 v[120:123], v[152:155], v[192:195], v[120:123]
	v_mfma_f32_16x16x32_bf16 v[116:119], v[172:175], v[180:183], v[116:119]
	v_mfma_f32_16x16x32_bf16 v[116:119], v[176:179], v[192:195], v[116:119]
	v_mfma_f32_16x16x32_bf16 v[100:103], v[172:175], v[196:199], v[100:103]
	v_mfma_f32_16x16x32_bf16 v[100:103], v[176:179], v[200:203], v[100:103]
	v_mfma_f32_16x16x32_bf16 v[104:107], v[148:151], v[196:199], v[104:107]
	v_mfma_f32_16x16x32_bf16 v[104:107], v[152:155], v[200:203], v[104:107]
	v_mfma_f32_16x16x32_bf16 v[108:111], v[140:143], v[196:199], v[108:111]
	v_mfma_f32_16x16x32_bf16 v[108:111], v[144:147], v[200:203], v[108:111]
	v_mfma_f32_16x16x32_bf16 v[112:115], v[132:135], v[196:199], v[112:115]
	v_mfma_f32_16x16x32_bf16 v[112:115], v[136:139], v[200:203], v[112:115]
	v_mfma_f32_16x16x32_bf16 v[96:99], v[132:135], v[204:207], v[96:99]
	v_mfma_f32_16x16x32_bf16 v[96:99], v[136:139], v[208:211], v[96:99]
	v_mfma_f32_16x16x32_bf16 v[92:95], v[140:143], v[204:207], v[92:95]
	v_mfma_f32_16x16x32_bf16 v[92:95], v[144:147], v[208:211], v[92:95]
	v_mfma_f32_16x16x32_bf16 v[88:91], v[148:151], v[204:207], v[88:91]
	v_mfma_f32_16x16x32_bf16 v[88:91], v[152:155], v[208:211], v[88:91]
	v_mfma_f32_16x16x32_bf16 v[84:87], v[172:175], v[204:207], v[84:87]
	v_mfma_f32_16x16x32_bf16 v[84:87], v[176:179], v[208:211], v[84:87]
	v_mfma_f32_16x16x32_bf16 v[68:71], v[172:175], v[212:215], v[68:71]
	v_mfma_f32_16x16x32_bf16 v[68:71], v[176:179], v[216:219], v[68:71]
	v_mfma_f32_16x16x32_bf16 v[72:75], v[148:151], v[212:215], v[72:75]
	v_mfma_f32_16x16x32_bf16 v[72:75], v[152:155], v[216:219], v[72:75]
	v_mfma_f32_16x16x32_bf16 v[76:79], v[140:143], v[212:215], v[76:79]
	v_mfma_f32_16x16x32_bf16 v[76:79], v[144:147], v[216:219], v[76:79]
	v_mfma_f32_16x16x32_bf16 v[80:83], v[132:135], v[212:215], v[80:83]
	v_mfma_f32_16x16x32_bf16 v[80:83], v[136:139], v[216:219], v[80:83]
	s_setprio 0
	s_barrier
	s_add_i32 s0, s0, s46
	s_add_i32 m0, s0, 0xffffff80
	ds_read_b128 v[180:183], v189 offset:49152
	ds_read_b128 v[192:195], v189 offset:50176
	ds_read_b128 v[196:199], v189 offset:51200
	ds_read_b128 v[200:203], v189 offset:52224
	ds_read_b128 v[204:207], v189 offset:53248
	ds_read_b128 v[208:211], v189 offset:54272
	ds_read_b128 v[212:215], v189 offset:55296
	ds_read_b128 v[216:219], v189 offset:56320
	global_load_lds_dwordx4 v158, s[50:51] offset:128
	s_add_i32 m0, s0, 0x1f80
	s_add_i32 s0, s66, s46
	global_load_lds_dwordx4 v162, s[50:51] offset:128
	s_add_u32 s50, s50, 0x100080
	s_addc_u32 s51, s51, 0
	s_mov_b32 m0, s0
	s_nop 0
	global_load_lds_dwordx4 v158, s[50:51]
	s_add_i32 m0, s0, 0x2000
	s_nop 0
	global_load_lds_dwordx4 v162, s[50:51]
	s_add_i32 m0, s57, 0xffffff80
	s_nop 0
	global_load_lds_dwordx4 v156, s[52:53] offset:128
	s_add_i32 m0, s58, 0xffffff80
	s_nop 0
	global_load_lds_dwordx4 v160, s[52:53] offset:128
	s_waitcnt vmcnt(8)
	s_waitcnt lgkmcnt(0)
	s_setprio 1
	s_barrier
	v_mfma_f32_16x16x32_bf16 v[64:67], v[132:135], v[180:183], v[64:67]
	v_mfma_f32_16x16x32_bf16 v[64:67], v[136:139], v[192:195], v[64:67]
	v_mfma_f32_16x16x32_bf16 v[60:63], v[140:143], v[180:183], v[60:63]
	v_mfma_f32_16x16x32_bf16 v[60:63], v[144:147], v[192:195], v[60:63]
	v_mfma_f32_16x16x32_bf16 v[56:59], v[148:151], v[180:183], v[56:59]
	v_mfma_f32_16x16x32_bf16 v[56:59], v[152:155], v[192:195], v[56:59]
	v_mfma_f32_16x16x32_bf16 v[52:55], v[172:175], v[180:183], v[52:55]
	v_mfma_f32_16x16x32_bf16 v[52:55], v[176:179], v[192:195], v[52:55]
	v_mfma_f32_16x16x32_bf16 v[36:39], v[172:175], v[196:199], v[36:39]
	v_mfma_f32_16x16x32_bf16 v[36:39], v[176:179], v[200:203], v[36:39]
	v_mfma_f32_16x16x32_bf16 v[40:43], v[148:151], v[196:199], v[40:43]
	v_mfma_f32_16x16x32_bf16 v[40:43], v[152:155], v[200:203], v[40:43]
	v_mfma_f32_16x16x32_bf16 v[44:47], v[140:143], v[196:199], v[44:47]
	v_mfma_f32_16x16x32_bf16 v[44:47], v[144:147], v[200:203], v[44:47]
	v_mfma_f32_16x16x32_bf16 v[48:51], v[132:135], v[196:199], v[48:51]
	v_mfma_f32_16x16x32_bf16 v[48:51], v[136:139], v[200:203], v[48:51]
	v_mfma_f32_16x16x32_bf16 v[32:35], v[132:135], v[204:207], v[32:35]
	v_mfma_f32_16x16x32_bf16 v[32:35], v[136:139], v[208:211], v[32:35]
	v_mfma_f32_16x16x32_bf16 v[28:31], v[140:143], v[204:207], v[28:31]
	v_mfma_f32_16x16x32_bf16 v[28:31], v[144:147], v[208:211], v[28:31]
	v_mfma_f32_16x16x32_bf16 v[24:27], v[148:151], v[204:207], v[24:27]
	v_mfma_f32_16x16x32_bf16 v[24:27], v[152:155], v[208:211], v[24:27]
	v_mfma_f32_16x16x32_bf16 v[20:23], v[172:175], v[204:207], v[20:23]
	v_mfma_f32_16x16x32_bf16 v[20:23], v[176:179], v[208:211], v[20:23]
	v_mfma_f32_16x16x32_bf16 v[4:7], v[172:175], v[212:215], v[4:7]
	v_mfma_f32_16x16x32_bf16 v[4:7], v[176:179], v[216:219], v[4:7]
	v_mfma_f32_16x16x32_bf16 v[8:11], v[148:151], v[212:215], v[8:11]
	v_mfma_f32_16x16x32_bf16 v[8:11], v[152:155], v[216:219], v[8:11]
	v_mfma_f32_16x16x32_bf16 v[12:15], v[140:143], v[212:215], v[12:15]
	v_mfma_f32_16x16x32_bf16 v[12:15], v[144:147], v[216:219], v[12:15]
	v_mfma_f32_16x16x32_bf16 v[16:19], v[132:135], v[212:215], v[16:19]
	v_mfma_f32_16x16x32_bf16 v[16:19], v[136:139], v[216:219], v[16:19]
	s_setprio 0
	s_barrier
	s_add_i32 s65, s65, 2
	s_add_u32 s42, s42, 0x100
	s_addc_u32 s43, s43, 0
	s_add_u32 s63, s63, 0x100
	s_addc_u32 s64, s64, 0
	s_cmp_gt_u32 s65, 61
	s_cbranch_scc0 .LBB0_1203
	s_and_b64 vcc, exec, s[20:21]
	s_cbranch_vccz .LBB0_1206
	s_barrier

.LBB0_1288:
	ds_read_b128 v[154:157], v150
	ds_read_b128 v[158:161], v150 offset:1024
	ds_read_b128 v[162:165], v150 offset:2048
	ds_read_b128 v[166:169], v150 offset:3072
	ds_read_b128 v[170:173], v151
	ds_read_b128 v[174:177], v151 offset:1024
	ds_read_b128 v[178:181], v151 offset:2048
	ds_read_b128 v[182:185], v151 offset:3072
	s_add_u32 s0, s42, 0xfff00080
	s_addc_u32 s50, s43, -1
	s_cmp_eq_u32 s70, 12
	s_cselect_b32 s53, s29, s50
	s_cselect_b32 s52, s28, s0
	s_cselect_b32 s51, s5, s41
	s_cselect_b32 s50, s4, s31
	s_add_i32 m0, s17, 0xc000
	ds_read_b128 v[186:189], v152
	ds_read_b128 v[190:193], v152 offset:1024
	ds_read_b128 v[194:197], v152 offset:2048
	ds_read_b128 v[198:201], v152 offset:3072
	ds_read_b128 v[202:205], v152 offset:4096
	ds_read_b128 v[206:209], v152 offset:5120
	ds_read_b128 v[210:213], v152 offset:6144
	ds_read_b128 v[214:217], v152 offset:7168
	global_load_lds_dwordx4 v142, s[42:43]
	s_add_i32 m0, s17, 0xe000
	s_nop 0
	global_load_lds_dwordx4 v144, s[42:43]
	s_waitcnt vmcnt(8)
	s_waitcnt lgkmcnt(0)
	s_setprio 1
	s_barrier
	v_mfma_f32_16x16x32_bf16 v[128:131], v[154:157], v[186:189], v[128:131]
	v_mfma_f32_16x16x32_bf16 v[128:131], v[158:161], v[190:193], v[128:131]
	v_mfma_f32_16x16x32_bf16 v[124:127], v[162:165], v[186:189], v[124:127]
	v_mfma_f32_16x16x32_bf16 v[124:127], v[166:169], v[190:193], v[124:127]
	v_mfma_f32_16x16x32_bf16 v[112:115], v[170:173], v[186:189], v[112:115]
	v_mfma_f32_16x16x32_bf16 v[112:115], v[174:177], v[190:193], v[112:115]
	v_mfma_f32_16x16x32_bf16 v[108:111], v[178:181], v[186:189], v[108:111]
	v_mfma_f32_16x16x32_bf16 v[108:111], v[182:185], v[190:193], v[108:111]
	v_mfma_f32_16x16x32_bf16 v[92:95], v[178:181], v[194:197], v[92:95]
	v_mfma_f32_16x16x32_bf16 v[92:95], v[182:185], v[198:201], v[92:95]
	v_mfma_f32_16x16x32_bf16 v[96:99], v[170:173], v[194:197], v[96:99]
	v_mfma_f32_16x16x32_bf16 v[96:99], v[174:177], v[198:201], v[96:99]
	v_mfma_f32_16x16x32_bf16 v[116:119], v[162:165], v[194:197], v[116:119]
	v_mfma_f32_16x16x32_bf16 v[116:119], v[166:169], v[198:201], v[116:119]
	v_mfma_f32_16x16x32_bf16 v[120:123], v[154:157], v[194:197], v[120:123]
	v_mfma_f32_16x16x32_bf16 v[120:123], v[158:161], v[198:201], v[120:123]
	v_mfma_f32_16x16x32_bf16 v[104:107], v[154:157], v[202:205], v[104:107]
	v_mfma_f32_16x16x32_bf16 v[104:107], v[158:161], v[206:209], v[104:107]
	v_mfma_f32_16x16x32_bf16 v[100:103], v[162:165], v[202:205], v[100:103]
	v_mfma_f32_16x16x32_bf16 v[100:103], v[166:169], v[206:209], v[100:103]
	v_mfma_f32_16x16x32_bf16 v[80:83], v[170:173], v[202:205], v[80:83]
	v_mfma_f32_16x16x32_bf16 v[80:83], v[174:177], v[206:209], v[80:83]
	v_mfma_f32_16x16x32_bf16 v[76:79], v[178:181], v[202:205], v[76:79]
	v_mfma_f32_16x16x32_bf16 v[76:79], v[182:185], v[206:209], v[76:79]
	v_mfma_f32_16x16x32_bf16 v[68:71], v[178:181], v[210:213], v[68:71]
	v_mfma_f32_16x16x32_bf16 v[68:71], v[182:185], v[214:217], v[68:71]
	v_mfma_f32_16x16x32_bf16 v[72:75], v[170:173], v[210:213], v[72:75]
	v_mfma_f32_16x16x32_bf16 v[72:75], v[174:177], v[214:217], v[72:75]
	v_mfma_f32_16x16x32_bf16 v[84:87], v[162:165], v[210:213], v[84:87]
	v_mfma_f32_16x16x32_bf16 v[84:87], v[166:169], v[214:217], v[84:87]
	v_mfma_f32_16x16x32_bf16 v[88:91], v[154:157], v[210:213], v[88:91]
	v_mfma_f32_16x16x32_bf16 v[88:91], v[158:161], v[214:217], v[88:91]
	s_setprio 0
	s_barrier
	s_add_i32 s0, s60, s46
	s_mov_b32 m0, s0
	ds_read_b128 v[186:189], v152 offset:16384
	ds_read_b128 v[190:193], v152 offset:17408
	ds_read_b128 v[194:197], v152 offset:18432
	ds_read_b128 v[198:201], v152 offset:19456
	ds_read_b128 v[202:205], v152 offset:20480
	ds_read_b128 v[206:209], v152 offset:21504
	ds_read_b128 v[210:213], v152 offset:22528
	ds_read_b128 v[214:217], v152 offset:23552
	global_load_lds_dwordx4 v136, s[50:51]
	s_add_i32 m0, s0, 0x2000
	s_add_u32 s72, s50, 0x100000
	s_addc_u32 s73, s51, 0
	s_add_i32 s0, s61, s46
	global_load_lds_dwordx4 v132, s[50:51]
	s_mov_b32 m0, s0
	s_nop 0
	global_load_lds_dwordx4 v136, s[72:73]
	s_add_i32 m0, s0, 0x2000
	s_nop 0
	global_load_lds_dwordx4 v132, s[72:73]
	s_mov_b32 m0, s17
	s_nop 0
	global_load_lds_dwordx4 v138, s[52:53]
	s_mov_b32 m0, s47
	s_nop 0
	global_load_lds_dwordx4 v134, s[52:53]
	s_waitcnt vmcnt(8)
	s_waitcnt lgkmcnt(0)
	s_setprio 1
	s_barrier
	v_mfma_f32_16x16x32_bf16 v[64:67], v[154:157], v[186:189], v[64:67]
	v_mfma_f32_16x16x32_bf16 v[64:67], v[158:161], v[190:193], v[64:67]
	v_mfma_f32_16x16x32_bf16 v[60:63], v[162:165], v[186:189], v[60:63]
	v_mfma_f32_16x16x32_bf16 v[60:63], v[166:169], v[190:193], v[60:63]
	v_mfma_f32_16x16x32_bf16 v[48:51], v[170:173], v[186:189], v[48:51]
	v_mfma_f32_16x16x32_bf16 v[48:51], v[174:177], v[190:193], v[48:51]
	v_mfma_f32_16x16x32_bf16 v[44:47], v[178:181], v[186:189], v[44:47]
	v_mfma_f32_16x16x32_bf16 v[44:47], v[182:185], v[190:193], v[44:47]
	v_mfma_f32_16x16x32_bf16 v[28:31], v[178:181], v[194:197], v[28:31]
	v_mfma_f32_16x16x32_bf16 v[28:31], v[182:185], v[198:201], v[28:31]
	v_mfma_f32_16x16x32_bf16 v[32:35], v[170:173], v[194:197], v[32:35]
	v_mfma_f32_16x16x32_bf16 v[32:35], v[174:177], v[198:201], v[32:35]
	v_mfma_f32_16x16x32_bf16 v[52:55], v[162:165], v[194:197], v[52:55]
	v_mfma_f32_16x16x32_bf16 v[52:55], v[166:169], v[198:201], v[52:55]
	v_mfma_f32_16x16x32_bf16 v[56:59], v[154:157], v[194:197], v[56:59]
	v_mfma_f32_16x16x32_bf16 v[56:59], v[158:161], v[198:201], v[56:59]
	v_mfma_f32_16x16x32_bf16 v[40:43], v[154:157], v[202:205], v[40:43]
	v_mfma_f32_16x16x32_bf16 v[40:43], v[158:161], v[206:209], v[40:43]
	v_mfma_f32_16x16x32_bf16 v[36:39], v[162:165], v[202:205], v[36:39]
	v_mfma_f32_16x16x32_bf16 v[36:39], v[166:169], v[206:209], v[36:39]
	v_mfma_f32_16x16x32_bf16 v[16:19], v[170:173], v[202:205], v[16:19]
	v_mfma_f32_16x16x32_bf16 v[16:19], v[174:177], v[206:209], v[16:19]
	v_mfma_f32_16x16x32_bf16 v[12:15], v[178:181], v[202:205], v[12:15]
	v_mfma_f32_16x16x32_bf16 v[12:15], v[182:185], v[206:209], v[12:15]
	v_mfma_f32_16x16x32_bf16 v[4:7], v[178:181], v[210:213], v[4:7]
	v_mfma_f32_16x16x32_bf16 v[4:7], v[182:185], v[214:217], v[4:7]
	v_mfma_f32_16x16x32_bf16 v[8:11], v[170:173], v[210:213], v[8:11]
	v_mfma_f32_16x16x32_bf16 v[8:11], v[174:177], v[214:217], v[8:11]
	v_mfma_f32_16x16x32_bf16 v[20:23], v[162:165], v[210:213], v[20:23]
	v_mfma_f32_16x16x32_bf16 v[20:23], v[166:169], v[214:217], v[20:23]
	v_mfma_f32_16x16x32_bf16 v[24:27], v[154:157], v[210:213], v[24:27]
	v_mfma_f32_16x16x32_bf16 v[24:27], v[158:161], v[214:217], v[24:27]
	s_setprio 0
	s_barrier
	s_add_i32 s0, 0, 0x18000
	v_add_u32_e32 v140, s0, v3
	s_add_i32 s71, 0, 0x1c000
	ds_read_b128 v[154:157], v140
	ds_read_b128 v[158:161], v140 offset:1024
	ds_read_b128 v[162:165], v140 offset:2048
	ds_read_b128 v[166:169], v140 offset:3072
	v_add_u32_e32 v140, s71, v3
	ds_read_b128 v[170:173], v140
	ds_read_b128 v[174:177], v140 offset:1024
	ds_read_b128 v[178:181], v140 offset:2048
	ds_read_b128 v[182:185], v140 offset:3072
	s_add_u32 s98, s52, 0x100000
	s_addc_u32 s99, s53, 0
	s_mov_b32 m0, s48
	ds_read_b128 v[186:189], v152 offset:32768
	ds_read_b128 v[190:193], v152 offset:33792
	ds_read_b128 v[194:197], v152 offset:34816
	ds_read_b128 v[198:201], v152 offset:35840
	ds_read_b128 v[202:205], v152 offset:36864
	ds_read_b128 v[206:209], v152 offset:37888
	ds_read_b128 v[210:213], v152 offset:38912
	ds_read_b128 v[214:217], v152 offset:39936
	global_load_lds_dwordx4 v138, s[98:99]
	s_mov_b32 m0, s49
	s_nop 0
	global_load_lds_dwordx4 v134, s[98:99]
	s_waitcnt vmcnt(8)
	s_waitcnt lgkmcnt(0)
	s_setprio 1
	s_barrier
	v_mfma_f32_16x16x32_bf16 v[128:131], v[154:157], v[186:189], v[128:131]
	v_mfma_f32_16x16x32_bf16 v[128:131], v[158:161], v[190:193], v[128:131]
	v_mfma_f32_16x16x32_bf16 v[124:127], v[162:165], v[186:189], v[124:127]
	v_mfma_f32_16x16x32_bf16 v[124:127], v[166:169], v[190:193], v[124:127]
	v_mfma_f32_16x16x32_bf16 v[112:115], v[170:173], v[186:189], v[112:115]
	v_mfma_f32_16x16x32_bf16 v[112:115], v[174:177], v[190:193], v[112:115]
	v_mfma_f32_16x16x32_bf16 v[108:111], v[178:181], v[186:189], v[108:111]
	v_mfma_f32_16x16x32_bf16 v[108:111], v[182:185], v[190:193], v[108:111]
	v_mfma_f32_16x16x32_bf16 v[92:95], v[178:181], v[194:197], v[92:95]
	v_mfma_f32_16x16x32_bf16 v[92:95], v[182:185], v[198:201], v[92:95]
	v_mfma_f32_16x16x32_bf16 v[96:99], v[170:173], v[194:197], v[96:99]
	v_mfma_f32_16x16x32_bf16 v[96:99], v[174:177], v[198:201], v[96:99]
	v_mfma_f32_16x16x32_bf16 v[116:119], v[162:165], v[194:197], v[116:119]
	v_mfma_f32_16x16x32_bf16 v[116:119], v[166:169], v[198:201], v[116:119]
	v_mfma_f32_16x16x32_bf16 v[120:123], v[154:157], v[194:197], v[120:123]
	v_mfma_f32_16x16x32_bf16 v[120:123], v[158:161], v[198:201], v[120:123]
	v_mfma_f32_16x16x32_bf16 v[104:107], v[154:157], v[202:205], v[104:107]
	v_mfma_f32_16x16x32_bf16 v[104:107], v[158:161], v[206:209], v[104:107]
	v_mfma_f32_16x16x32_bf16 v[100:103], v[162:165], v[202:205], v[100:103]
	v_mfma_f32_16x16x32_bf16 v[100:103], v[166:169], v[206:209], v[100:103]
	v_mfma_f32_16x16x32_bf16 v[80:83], v[170:173], v[202:205], v[80:83]
	v_mfma_f32_16x16x32_bf16 v[80:83], v[174:177], v[206:209], v[80:83]
	v_mfma_f32_16x16x32_bf16 v[76:79], v[178:181], v[202:205], v[76:79]
	v_mfma_f32_16x16x32_bf16 v[76:79], v[182:185], v[206:209], v[76:79]
	v_mfma_f32_16x16x32_bf16 v[68:71], v[178:181], v[210:213], v[68:71]
	v_mfma_f32_16x16x32_bf16 v[68:71], v[182:185], v[214:217], v[68:71]
	v_mfma_f32_16x16x32_bf16 v[72:75], v[170:173], v[210:213], v[72:75]
	v_mfma_f32_16x16x32_bf16 v[72:75], v[174:177], v[214:217], v[72:75]
	v_mfma_f32_16x16x32_bf16 v[84:87], v[162:165], v[210:213], v[84:87]
	v_mfma_f32_16x16x32_bf16 v[84:87], v[166:169], v[214:217], v[84:87]
	v_mfma_f32_16x16x32_bf16 v[88:91], v[154:157], v[210:213], v[88:91]
	v_mfma_f32_16x16x32_bf16 v[88:91], v[158:161], v[214:217], v[88:91]
	s_setprio 0
	s_barrier
	s_add_i32 s0, s0, s46
	s_add_i32 m0, s0, 0xffffff80
	ds_read_b128 v[186:189], v152 offset:49152
	ds_read_b128 v[190:193], v152 offset:50176
	ds_read_b128 v[194:197], v152 offset:51200
	ds_read_b128 v[198:201], v152 offset:52224
	ds_read_b128 v[202:205], v152 offset:53248
	ds_read_b128 v[206:209], v152 offset:54272
	ds_read_b128 v[210:213], v152 offset:55296
	ds_read_b128 v[214:217], v152 offset:56320
	global_load_lds_dwordx4 v136, s[50:51] offset:128
	s_add_i32 m0, s0, 0x1f80
	s_add_i32 s0, s71, s46
	global_load_lds_dwordx4 v132, s[50:51] offset:128
	s_add_u32 s50, s50, 0x100080
	s_addc_u32 s51, s51, 0
	s_mov_b32 m0, s0
	s_nop 0
	global_load_lds_dwordx4 v136, s[50:51]
	s_add_i32 m0, s0, 0x2000
	s_nop 0
	global_load_lds_dwordx4 v132, s[50:51]
	s_add_i32 m0, s58, 0xffffff80
	s_nop 0
	global_load_lds_dwordx4 v138, s[52:53] offset:128
	s_add_i32 m0, s59, 0xffffff80
	s_nop 0
	global_load_lds_dwordx4 v134, s[52:53] offset:128
	s_waitcnt vmcnt(8)
	s_waitcnt lgkmcnt(0)
	s_setprio 1
	s_barrier
	v_mfma_f32_16x16x32_bf16 v[64:67], v[154:157], v[186:189], v[64:67]
	v_mfma_f32_16x16x32_bf16 v[64:67], v[158:161], v[190:193], v[64:67]
	v_mfma_f32_16x16x32_bf16 v[60:63], v[162:165], v[186:189], v[60:63]
	v_mfma_f32_16x16x32_bf16 v[60:63], v[166:169], v[190:193], v[60:63]
	v_mfma_f32_16x16x32_bf16 v[48:51], v[170:173], v[186:189], v[48:51]
	v_mfma_f32_16x16x32_bf16 v[48:51], v[174:177], v[190:193], v[48:51]
	v_mfma_f32_16x16x32_bf16 v[44:47], v[178:181], v[186:189], v[44:47]
	v_mfma_f32_16x16x32_bf16 v[44:47], v[182:185], v[190:193], v[44:47]
	v_mfma_f32_16x16x32_bf16 v[28:31], v[178:181], v[194:197], v[28:31]
	v_mfma_f32_16x16x32_bf16 v[28:31], v[182:185], v[198:201], v[28:31]
	v_mfma_f32_16x16x32_bf16 v[32:35], v[170:173], v[194:197], v[32:35]
	v_mfma_f32_16x16x32_bf16 v[32:35], v[174:177], v[198:201], v[32:35]
	v_mfma_f32_16x16x32_bf16 v[52:55], v[162:165], v[194:197], v[52:55]
	v_mfma_f32_16x16x32_bf16 v[52:55], v[166:169], v[198:201], v[52:55]
	v_mfma_f32_16x16x32_bf16 v[56:59], v[154:157], v[194:197], v[56:59]
	v_mfma_f32_16x16x32_bf16 v[56:59], v[158:161], v[198:201], v[56:59]
	v_mfma_f32_16x16x32_bf16 v[40:43], v[154:157], v[202:205], v[40:43]
	v_mfma_f32_16x16x32_bf16 v[40:43], v[158:161], v[206:209], v[40:43]
	v_mfma_f32_16x16x32_bf16 v[36:39], v[162:165], v[202:205], v[36:39]
	v_mfma_f32_16x16x32_bf16 v[36:39], v[166:169], v[206:209], v[36:39]
	v_mfma_f32_16x16x32_bf16 v[16:19], v[170:173], v[202:205], v[16:19]
	v_mfma_f32_16x16x32_bf16 v[16:19], v[174:177], v[206:209], v[16:19]
	v_mfma_f32_16x16x32_bf16 v[12:15], v[178:181], v[202:205], v[12:15]
	v_mfma_f32_16x16x32_bf16 v[12:15], v[182:185], v[206:209], v[12:15]
	v_mfma_f32_16x16x32_bf16 v[4:7], v[178:181], v[210:213], v[4:7]
	v_mfma_f32_16x16x32_bf16 v[4:7], v[182:185], v[214:217], v[4:7]
	v_mfma_f32_16x16x32_bf16 v[8:11], v[170:173], v[210:213], v[8:11]
	v_mfma_f32_16x16x32_bf16 v[8:11], v[174:177], v[214:217], v[8:11]
	v_mfma_f32_16x16x32_bf16 v[20:23], v[162:165], v[210:213], v[20:23]
	v_mfma_f32_16x16x32_bf16 v[20:23], v[166:169], v[214:217], v[20:23]
	v_mfma_f32_16x16x32_bf16 v[24:27], v[154:157], v[210:213], v[24:27]
	v_mfma_f32_16x16x32_bf16 v[24:27], v[158:161], v[214:217], v[24:27]
	s_setprio 0
	s_barrier
	s_add_i32 s70, s70, 2
	s_add_u32 s42, s42, 0x100
	s_addc_u32 s43, s43, 0
	s_add_u32 s31, s31, 0x100
	s_addc_u32 s41, s41, 0
	s_cmp_gt_u32 s70, 13
	s_cbranch_scc0 .LBB0_1288
	s_and_b64 vcc, exec, s[14:15]
	s_cbranch_vccz .LBB0_1291
	s_barrier

.LBB0_1415:
	ds_read_b128 v[132:135], v187
	ds_read_b128 v[136:139], v187 offset:1024
	ds_read_b128 v[140:143], v187 offset:2048
	ds_read_b128 v[144:147], v187 offset:3072
	ds_read_b128 v[148:151], v188
	ds_read_b128 v[152:155], v188 offset:1024
	ds_read_b128 v[172:175], v188 offset:2048
	ds_read_b128 v[176:179], v188 offset:3072
	s_add_u32 s0, s42, 0xfffe0080
	s_addc_u32 s50, s43, -1
	s_cmp_eq_u32 s64, 4
	s_cselect_b32 s53, s25, s50
	s_cselect_b32 s52, s31, s0
	s_cselect_b32 s51, s23, s63
	s_cselect_b32 s50, s61, s62
	s_add_i32 m0, s41, 0xc000
	ds_read_b128 v[180:183], v189
	ds_read_b128 v[192:195], v189 offset:1024
	ds_read_b128 v[196:199], v189 offset:2048
	ds_read_b128 v[200:203], v189 offset:3072
	ds_read_b128 v[204:207], v189 offset:4096
	ds_read_b128 v[208:211], v189 offset:5120
	ds_read_b128 v[212:215], v189 offset:6144
	ds_read_b128 v[216:219], v189 offset:7168
	global_load_lds_dwordx4 v164, s[42:43]
	s_add_i32 m0, s41, 0xe000
	s_nop 0
	global_load_lds_dwordx4 v166, s[42:43]
	s_waitcnt vmcnt(8)
	s_waitcnt lgkmcnt(0)
	s_setprio 1
	s_barrier
	v_mfma_f32_16x16x32_bf16 v[128:131], v[132:135], v[180:183], v[128:131]
	v_mfma_f32_16x16x32_bf16 v[128:131], v[136:139], v[192:195], v[128:131]
	v_mfma_f32_16x16x32_bf16 v[124:127], v[140:143], v[180:183], v[124:127]
	v_mfma_f32_16x16x32_bf16 v[124:127], v[144:147], v[192:195], v[124:127]
	v_mfma_f32_16x16x32_bf16 v[120:123], v[148:151], v[180:183], v[120:123]
	v_mfma_f32_16x16x32_bf16 v[120:123], v[152:155], v[192:195], v[120:123]
	v_mfma_f32_16x16x32_bf16 v[116:119], v[172:175], v[180:183], v[116:119]
	v_mfma_f32_16x16x32_bf16 v[116:119], v[176:179], v[192:195], v[116:119]
	v_mfma_f32_16x16x32_bf16 v[100:103], v[172:175], v[196:199], v[100:103]
	v_mfma_f32_16x16x32_bf16 v[100:103], v[176:179], v[200:203], v[100:103]
	v_mfma_f32_16x16x32_bf16 v[104:107], v[148:151], v[196:199], v[104:107]
	v_mfma_f32_16x16x32_bf16 v[104:107], v[152:155], v[200:203], v[104:107]
	v_mfma_f32_16x16x32_bf16 v[108:111], v[140:143], v[196:199], v[108:111]
	v_mfma_f32_16x16x32_bf16 v[108:111], v[144:147], v[200:203], v[108:111]
	v_mfma_f32_16x16x32_bf16 v[112:115], v[132:135], v[196:199], v[112:115]
	v_mfma_f32_16x16x32_bf16 v[112:115], v[136:139], v[200:203], v[112:115]
	v_mfma_f32_16x16x32_bf16 v[96:99], v[132:135], v[204:207], v[96:99]
	v_mfma_f32_16x16x32_bf16 v[96:99], v[136:139], v[208:211], v[96:99]
	v_mfma_f32_16x16x32_bf16 v[92:95], v[140:143], v[204:207], v[92:95]
	v_mfma_f32_16x16x32_bf16 v[92:95], v[144:147], v[208:211], v[92:95]
	v_mfma_f32_16x16x32_bf16 v[88:91], v[148:151], v[204:207], v[88:91]
	v_mfma_f32_16x16x32_bf16 v[88:91], v[152:155], v[208:211], v[88:91]
	v_mfma_f32_16x16x32_bf16 v[84:87], v[172:175], v[204:207], v[84:87]
	v_mfma_f32_16x16x32_bf16 v[84:87], v[176:179], v[208:211], v[84:87]
	v_mfma_f32_16x16x32_bf16 v[68:71], v[172:175], v[212:215], v[68:71]
	v_mfma_f32_16x16x32_bf16 v[68:71], v[176:179], v[216:219], v[68:71]
	v_mfma_f32_16x16x32_bf16 v[72:75], v[148:151], v[212:215], v[72:75]
	v_mfma_f32_16x16x32_bf16 v[72:75], v[152:155], v[216:219], v[72:75]
	v_mfma_f32_16x16x32_bf16 v[76:79], v[140:143], v[212:215], v[76:79]
	v_mfma_f32_16x16x32_bf16 v[76:79], v[144:147], v[216:219], v[76:79]
	v_mfma_f32_16x16x32_bf16 v[80:83], v[132:135], v[212:215], v[80:83]
	v_mfma_f32_16x16x32_bf16 v[80:83], v[136:139], v[216:219], v[80:83]
	s_setprio 0
	s_barrier
	s_add_i32 s0, s58, s45
	s_mov_b32 m0, s0
	ds_read_b128 v[180:183], v189 offset:16384
	ds_read_b128 v[192:195], v189 offset:17408
	ds_read_b128 v[196:199], v189 offset:18432
	ds_read_b128 v[200:203], v189 offset:19456
	ds_read_b128 v[204:207], v189 offset:20480
	ds_read_b128 v[208:211], v189 offset:21504
	ds_read_b128 v[212:215], v189 offset:22528
	ds_read_b128 v[216:219], v189 offset:23552
	global_load_lds_dwordx4 v158, s[50:51]
	s_add_i32 m0, s0, 0x2000
	s_add_u32 s66, s50, 0x20000
	s_addc_u32 s67, s51, 0
	s_add_i32 s0, s59, s45
	global_load_lds_dwordx4 v162, s[50:51]
	s_mov_b32 m0, s0
	s_nop 0
	global_load_lds_dwordx4 v158, s[66:67]
	s_add_i32 m0, s0, 0x2000
	s_nop 0
	global_load_lds_dwordx4 v162, s[66:67]
	s_mov_b32 m0, s41
	s_nop 0
	global_load_lds_dwordx4 v156, s[52:53]
	s_mov_b32 m0, s46
	s_nop 0
	global_load_lds_dwordx4 v160, s[52:53]
	s_waitcnt vmcnt(8)
	s_waitcnt lgkmcnt(0)
	s_setprio 1
	s_barrier
	v_mfma_f32_16x16x32_bf16 v[64:67], v[132:135], v[180:183], v[64:67]
	v_mfma_f32_16x16x32_bf16 v[64:67], v[136:139], v[192:195], v[64:67]
	v_mfma_f32_16x16x32_bf16 v[60:63], v[140:143], v[180:183], v[60:63]
	v_mfma_f32_16x16x32_bf16 v[60:63], v[144:147], v[192:195], v[60:63]
	v_mfma_f32_16x16x32_bf16 v[56:59], v[148:151], v[180:183], v[56:59]
	v_mfma_f32_16x16x32_bf16 v[56:59], v[152:155], v[192:195], v[56:59]
	v_mfma_f32_16x16x32_bf16 v[52:55], v[172:175], v[180:183], v[52:55]
	v_mfma_f32_16x16x32_bf16 v[52:55], v[176:179], v[192:195], v[52:55]
	v_mfma_f32_16x16x32_bf16 v[36:39], v[172:175], v[196:199], v[36:39]
	v_mfma_f32_16x16x32_bf16 v[36:39], v[176:179], v[200:203], v[36:39]
	v_mfma_f32_16x16x32_bf16 v[40:43], v[148:151], v[196:199], v[40:43]
	v_mfma_f32_16x16x32_bf16 v[40:43], v[152:155], v[200:203], v[40:43]
	v_mfma_f32_16x16x32_bf16 v[44:47], v[140:143], v[196:199], v[44:47]
	v_mfma_f32_16x16x32_bf16 v[44:47], v[144:147], v[200:203], v[44:47]
	v_mfma_f32_16x16x32_bf16 v[48:51], v[132:135], v[196:199], v[48:51]
	v_mfma_f32_16x16x32_bf16 v[48:51], v[136:139], v[200:203], v[48:51]
	v_mfma_f32_16x16x32_bf16 v[32:35], v[132:135], v[204:207], v[32:35]
	v_mfma_f32_16x16x32_bf16 v[32:35], v[136:139], v[208:211], v[32:35]
	v_mfma_f32_16x16x32_bf16 v[28:31], v[140:143], v[204:207], v[28:31]
	v_mfma_f32_16x16x32_bf16 v[28:31], v[144:147], v[208:211], v[28:31]
	v_mfma_f32_16x16x32_bf16 v[24:27], v[148:151], v[204:207], v[24:27]
	v_mfma_f32_16x16x32_bf16 v[24:27], v[152:155], v[208:211], v[24:27]
	v_mfma_f32_16x16x32_bf16 v[20:23], v[172:175], v[204:207], v[20:23]
	v_mfma_f32_16x16x32_bf16 v[20:23], v[176:179], v[208:211], v[20:23]
	v_mfma_f32_16x16x32_bf16 v[4:7], v[172:175], v[212:215], v[4:7]
	v_mfma_f32_16x16x32_bf16 v[4:7], v[176:179], v[216:219], v[4:7]
	v_mfma_f32_16x16x32_bf16 v[8:11], v[148:151], v[212:215], v[8:11]
	v_mfma_f32_16x16x32_bf16 v[8:11], v[152:155], v[216:219], v[8:11]
	v_mfma_f32_16x16x32_bf16 v[12:15], v[140:143], v[212:215], v[12:15]
	v_mfma_f32_16x16x32_bf16 v[12:15], v[144:147], v[216:219], v[12:15]
	v_mfma_f32_16x16x32_bf16 v[16:19], v[132:135], v[212:215], v[16:19]
	v_mfma_f32_16x16x32_bf16 v[16:19], v[136:139], v[216:219], v[16:19]
	s_setprio 0
	s_barrier
	s_add_i32 s0, 0, 0x18000
	s_add_i32 s65, 0, 0x1c000
	v_add_u32_e32 v144, s0, v3
	v_add_u32_e32 v176, s65, v3
	ds_read_b128 v[132:135], v144
	ds_read_b128 v[136:139], v144 offset:1024
	ds_read_b128 v[140:143], v144 offset:2048
	ds_read_b128 v[144:147], v144 offset:3072
	ds_read_b128 v[148:151], v176
	ds_read_b128 v[152:155], v176 offset:1024
	ds_read_b128 v[172:175], v176 offset:2048
	ds_read_b128 v[176:179], v176 offset:3072
	s_add_u32 s98, s52, 0x20000
	s_addc_u32 s99, s53, 0
	s_mov_b32 m0, s47
	ds_read_b128 v[180:183], v189 offset:32768
	ds_read_b128 v[192:195], v189 offset:33792
	ds_read_b128 v[196:199], v189 offset:34816
	ds_read_b128 v[200:203], v189 offset:35840
	ds_read_b128 v[204:207], v189 offset:36864
	ds_read_b128 v[208:211], v189 offset:37888
	ds_read_b128 v[212:215], v189 offset:38912
	ds_read_b128 v[216:219], v189 offset:39936
	global_load_lds_dwordx4 v156, s[98:99]
	s_mov_b32 m0, s48
	s_nop 0
	global_load_lds_dwordx4 v160, s[98:99]
	s_waitcnt vmcnt(8)
	s_waitcnt lgkmcnt(0)
	s_setprio 1
	s_barrier
	v_mfma_f32_16x16x32_bf16 v[128:131], v[132:135], v[180:183], v[128:131]
	v_mfma_f32_16x16x32_bf16 v[128:131], v[136:139], v[192:195], v[128:131]
	v_mfma_f32_16x16x32_bf16 v[124:127], v[140:143], v[180:183], v[124:127]
	v_mfma_f32_16x16x32_bf16 v[124:127], v[144:147], v[192:195], v[124:127]
	v_mfma_f32_16x16x32_bf16 v[120:123], v[148:151], v[180:183], v[120:123]
	v_mfma_f32_16x16x32_bf16 v[120:123], v[152:155], v[192:195], v[120:123]
	v_mfma_f32_16x16x32_bf16 v[116:119], v[172:175], v[180:183], v[116:119]
	v_mfma_f32_16x16x32_bf16 v[116:119], v[176:179], v[192:195], v[116:119]
	v_mfma_f32_16x16x32_bf16 v[100:103], v[172:175], v[196:199], v[100:103]
	v_mfma_f32_16x16x32_bf16 v[100:103], v[176:179], v[200:203], v[100:103]
	v_mfma_f32_16x16x32_bf16 v[104:107], v[148:151], v[196:199], v[104:107]
	v_mfma_f32_16x16x32_bf16 v[104:107], v[152:155], v[200:203], v[104:107]
	v_mfma_f32_16x16x32_bf16 v[108:111], v[140:143], v[196:199], v[108:111]
	v_mfma_f32_16x16x32_bf16 v[108:111], v[144:147], v[200:203], v[108:111]
	v_mfma_f32_16x16x32_bf16 v[112:115], v[132:135], v[196:199], v[112:115]
	v_mfma_f32_16x16x32_bf16 v[112:115], v[136:139], v[200:203], v[112:115]
	v_mfma_f32_16x16x32_bf16 v[96:99], v[132:135], v[204:207], v[96:99]
	v_mfma_f32_16x16x32_bf16 v[96:99], v[136:139], v[208:211], v[96:99]
	v_mfma_f32_16x16x32_bf16 v[92:95], v[140:143], v[204:207], v[92:95]
	v_mfma_f32_16x16x32_bf16 v[92:95], v[144:147], v[208:211], v[92:95]
	v_mfma_f32_16x16x32_bf16 v[88:91], v[148:151], v[204:207], v[88:91]
	v_mfma_f32_16x16x32_bf16 v[88:91], v[152:155], v[208:211], v[88:91]
	v_mfma_f32_16x16x32_bf16 v[84:87], v[172:175], v[204:207], v[84:87]
	v_mfma_f32_16x16x32_bf16 v[84:87], v[176:179], v[208:211], v[84:87]
	v_mfma_f32_16x16x32_bf16 v[68:71], v[172:175], v[212:215], v[68:71]
	v_mfma_f32_16x16x32_bf16 v[68:71], v[176:179], v[216:219], v[68:71]
	v_mfma_f32_16x16x32_bf16 v[72:75], v[148:151], v[212:215], v[72:75]
	v_mfma_f32_16x16x32_bf16 v[72:75], v[152:155], v[216:219], v[72:75]
	v_mfma_f32_16x16x32_bf16 v[76:79], v[140:143], v[212:215], v[76:79]
	v_mfma_f32_16x16x32_bf16 v[76:79], v[144:147], v[216:219], v[76:79]
	v_mfma_f32_16x16x32_bf16 v[80:83], v[132:135], v[212:215], v[80:83]
	v_mfma_f32_16x16x32_bf16 v[80:83], v[136:139], v[216:219], v[80:83]
	s_setprio 0
	s_barrier
	s_add_i32 s0, s0, s45
	s_add_i32 m0, s0, 0xffffff80
	ds_read_b128 v[180:183], v189 offset:49152
	ds_read_b128 v[192:195], v189 offset:50176
	ds_read_b128 v[196:199], v189 offset:51200
	ds_read_b128 v[200:203], v189 offset:52224
	ds_read_b128 v[204:207], v189 offset:53248
	ds_read_b128 v[208:211], v189 offset:54272
	ds_read_b128 v[212:215], v189 offset:55296
	ds_read_b128 v[216:219], v189 offset:56320
	global_load_lds_dwordx4 v158, s[50:51] offset:128
	s_add_i32 m0, s0, 0x1f80
	s_add_i32 s0, s65, s45
	global_load_lds_dwordx4 v162, s[50:51] offset:128
	s_add_u32 s50, s50, 0x20080
	s_addc_u32 s51, s51, 0
	s_mov_b32 m0, s0
	s_nop 0
	global_load_lds_dwordx4 v158, s[50:51]
	s_add_i32 m0, s0, 0x2000
	s_nop 0
	global_load_lds_dwordx4 v162, s[50:51]
	s_add_i32 m0, s56, 0xffffff80
	s_nop 0
	global_load_lds_dwordx4 v156, s[52:53] offset:128
	s_add_i32 m0, s57, 0xffffff80
	s_nop 0
	global_load_lds_dwordx4 v160, s[52:53] offset:128
	s_waitcnt vmcnt(8)
	s_waitcnt lgkmcnt(0)
	s_setprio 1
	s_barrier
	v_mfma_f32_16x16x32_bf16 v[64:67], v[132:135], v[180:183], v[64:67]
	v_mfma_f32_16x16x32_bf16 v[64:67], v[136:139], v[192:195], v[64:67]
	v_mfma_f32_16x16x32_bf16 v[60:63], v[140:143], v[180:183], v[60:63]
	v_mfma_f32_16x16x32_bf16 v[60:63], v[144:147], v[192:195], v[60:63]
	v_mfma_f32_16x16x32_bf16 v[56:59], v[148:151], v[180:183], v[56:59]
	v_mfma_f32_16x16x32_bf16 v[56:59], v[152:155], v[192:195], v[56:59]
	v_mfma_f32_16x16x32_bf16 v[52:55], v[172:175], v[180:183], v[52:55]
	v_mfma_f32_16x16x32_bf16 v[52:55], v[176:179], v[192:195], v[52:55]
	v_mfma_f32_16x16x32_bf16 v[36:39], v[172:175], v[196:199], v[36:39]
	v_mfma_f32_16x16x32_bf16 v[36:39], v[176:179], v[200:203], v[36:39]
	v_mfma_f32_16x16x32_bf16 v[40:43], v[148:151], v[196:199], v[40:43]
	v_mfma_f32_16x16x32_bf16 v[40:43], v[152:155], v[200:203], v[40:43]
	v_mfma_f32_16x16x32_bf16 v[44:47], v[140:143], v[196:199], v[44:47]
	v_mfma_f32_16x16x32_bf16 v[44:47], v[144:147], v[200:203], v[44:47]
	v_mfma_f32_16x16x32_bf16 v[48:51], v[132:135], v[196:199], v[48:51]
	v_mfma_f32_16x16x32_bf16 v[48:51], v[136:139], v[200:203], v[48:51]
	v_mfma_f32_16x16x32_bf16 v[32:35], v[132:135], v[204:207], v[32:35]
	v_mfma_f32_16x16x32_bf16 v[32:35], v[136:139], v[208:211], v[32:35]
	v_mfma_f32_16x16x32_bf16 v[28:31], v[140:143], v[204:207], v[28:31]
	v_mfma_f32_16x16x32_bf16 v[28:31], v[144:147], v[208:211], v[28:31]
	v_mfma_f32_16x16x32_bf16 v[24:27], v[148:151], v[204:207], v[24:27]
	v_mfma_f32_16x16x32_bf16 v[24:27], v[152:155], v[208:211], v[24:27]
	v_mfma_f32_16x16x32_bf16 v[20:23], v[172:175], v[204:207], v[20:23]
	v_mfma_f32_16x16x32_bf16 v[20:23], v[176:179], v[208:211], v[20:23]
	v_mfma_f32_16x16x32_bf16 v[4:7], v[172:175], v[212:215], v[4:7]
	v_mfma_f32_16x16x32_bf16 v[4:7], v[176:179], v[216:219], v[4:7]
	v_mfma_f32_16x16x32_bf16 v[8:11], v[148:151], v[212:215], v[8:11]
	v_mfma_f32_16x16x32_bf16 v[8:11], v[152:155], v[216:219], v[8:11]
	v_mfma_f32_16x16x32_bf16 v[12:15], v[140:143], v[212:215], v[12:15]
	v_mfma_f32_16x16x32_bf16 v[12:15], v[144:147], v[216:219], v[12:15]
	v_mfma_f32_16x16x32_bf16 v[16:19], v[132:135], v[212:215], v[16:19]
	v_mfma_f32_16x16x32_bf16 v[16:19], v[136:139], v[216:219], v[16:19]
	s_setprio 0
	s_barrier
	s_add_i32 s64, s64, 2
	s_add_u32 s42, s42, 0x100
	s_addc_u32 s43, s43, 0
	s_add_u32 s62, s62, 0x100
	s_addc_u32 s63, s63, 0
	s_cmp_gt_u32 s64, 5
	s_cbranch_scc0 .LBB0_1415
	s_and_b64 vcc, exec, s[16:17]
	s_cbranch_vccz .LBB0_1418
	s_barrier

.LBB0_1503:
	ds_read_b128 v[132:135], v159
	ds_read_b128 v[164:167], v159 offset:1024
	ds_read_b128 v[168:171], v159 offset:2048
	ds_read_b128 v[172:175], v159 offset:3072
	ds_read_b128 v[176:179], v160
	ds_read_b128 v[180:183], v160 offset:1024
	ds_read_b128 v[184:187], v160 offset:2048
	ds_read_b128 v[188:191], v160 offset:3072
	s_add_u32 s0, s54, 0xfff00080
	s_addc_u32 s56, s55, -1
	s_cmp_eq_u32 s75, 60
	s_cselect_b32 s59, s31, s56
	s_cselect_b32 s58, s71, s0
	s_cselect_b32 s57, s29, s74
	s_cselect_b32 s56, s72, s73
	s_add_i32 m0, s48, 0xc000
	ds_read_b128 v[192:195], v161
	ds_read_b128 v[196:199], v161 offset:1024
	ds_read_b128 v[200:203], v161 offset:2048
	ds_read_b128 v[204:207], v161 offset:3072
	ds_read_b128 v[208:211], v161 offset:4096
	ds_read_b128 v[212:215], v161 offset:5120
	ds_read_b128 v[216:219], v161 offset:6144
	ds_read_b128 v[220:223], v161 offset:7168
	global_load_lds_dwordx4 v148, s[54:55]
	s_add_i32 m0, s48, 0xe000
	s_nop 0
	global_load_lds_dwordx4 v150, s[54:55]
	s_waitcnt vmcnt(8)
	s_waitcnt lgkmcnt(0)
	s_setprio 1
	s_barrier
	v_mfma_f32_16x16x32_bf16 v[136:139], v[132:135], v[192:195], v[136:139]
	v_mfma_f32_16x16x32_bf16 v[136:139], v[164:167], v[196:199], v[136:139]
	v_mfma_f32_16x16x32_bf16 v[128:131], v[168:171], v[192:195], v[128:131]
	v_mfma_f32_16x16x32_bf16 v[128:131], v[172:175], v[196:199], v[128:131]
	v_mfma_f32_16x16x32_bf16 v[124:127], v[176:179], v[192:195], v[124:127]
	v_mfma_f32_16x16x32_bf16 v[124:127], v[180:183], v[196:199], v[124:127]
	v_mfma_f32_16x16x32_bf16 v[120:123], v[184:187], v[192:195], v[120:123]
	v_mfma_f32_16x16x32_bf16 v[120:123], v[188:191], v[196:199], v[120:123]
	v_mfma_f32_16x16x32_bf16 v[104:107], v[184:187], v[200:203], v[104:107]
	v_mfma_f32_16x16x32_bf16 v[104:107], v[188:191], v[204:207], v[104:107]
	v_mfma_f32_16x16x32_bf16 v[108:111], v[176:179], v[200:203], v[108:111]
	v_mfma_f32_16x16x32_bf16 v[108:111], v[180:183], v[204:207], v[108:111]
	v_mfma_f32_16x16x32_bf16 v[112:115], v[168:171], v[200:203], v[112:115]
	v_mfma_f32_16x16x32_bf16 v[112:115], v[172:175], v[204:207], v[112:115]
	v_mfma_f32_16x16x32_bf16 v[116:119], v[132:135], v[200:203], v[116:119]
	v_mfma_f32_16x16x32_bf16 v[116:119], v[164:167], v[204:207], v[116:119]
	v_mfma_f32_16x16x32_bf16 v[100:103], v[132:135], v[208:211], v[100:103]
	v_mfma_f32_16x16x32_bf16 v[100:103], v[164:167], v[212:215], v[100:103]
	v_mfma_f32_16x16x32_bf16 v[96:99], v[168:171], v[208:211], v[96:99]
	v_mfma_f32_16x16x32_bf16 v[96:99], v[172:175], v[212:215], v[96:99]
	v_mfma_f32_16x16x32_bf16 v[92:95], v[176:179], v[208:211], v[92:95]
	v_mfma_f32_16x16x32_bf16 v[92:95], v[180:183], v[212:215], v[92:95]
	v_mfma_f32_16x16x32_bf16 v[88:91], v[184:187], v[208:211], v[88:91]
	v_mfma_f32_16x16x32_bf16 v[88:91], v[188:191], v[212:215], v[88:91]
	v_mfma_f32_16x16x32_bf16 v[72:75], v[184:187], v[216:219], v[72:75]
	v_mfma_f32_16x16x32_bf16 v[72:75], v[188:191], v[220:223], v[72:75]
	v_mfma_f32_16x16x32_bf16 v[76:79], v[176:179], v[216:219], v[76:79]
	v_mfma_f32_16x16x32_bf16 v[76:79], v[180:183], v[220:223], v[76:79]
	v_mfma_f32_16x16x32_bf16 v[80:83], v[168:171], v[216:219], v[80:83]
	v_mfma_f32_16x16x32_bf16 v[80:83], v[172:175], v[220:223], v[80:83]
	v_mfma_f32_16x16x32_bf16 v[84:87], v[132:135], v[216:219], v[84:87]
	v_mfma_f32_16x16x32_bf16 v[84:87], v[164:167], v[220:223], v[84:87]
	s_setprio 0
	s_barrier
	s_add_i32 s0, s65, s47
	s_mov_b32 m0, s0
	ds_read_b128 v[192:195], v161 offset:16384
	ds_read_b128 v[196:199], v161 offset:17408
	ds_read_b128 v[200:203], v161 offset:18432
	ds_read_b128 v[204:207], v161 offset:19456
	ds_read_b128 v[208:211], v161 offset:20480
	ds_read_b128 v[212:215], v161 offset:21504
	ds_read_b128 v[216:219], v161 offset:22528
	ds_read_b128 v[220:223], v161 offset:23552
	global_load_lds_dwordx4 v142, s[56:57]
	s_add_i32 m0, s0, 0x2000
	s_add_u32 s76, s56, 0x100000
	s_addc_u32 s77, s57, 0
	s_add_i32 s0, s66, s47
	global_load_lds_dwordx4 v146, s[56:57]
	s_mov_b32 m0, s0
	s_nop 0
	global_load_lds_dwordx4 v142, s[76:77]
	s_add_i32 m0, s0, 0x2000
	s_nop 0
	global_load_lds_dwordx4 v146, s[76:77]
	s_mov_b32 m0, s48
	s_nop 0
	global_load_lds_dwordx4 v140, s[58:59]
	s_mov_b32 m0, s49
	s_nop 0
	global_load_lds_dwordx4 v144, s[58:59]
	s_waitcnt vmcnt(8)
	s_waitcnt lgkmcnt(0)
	s_setprio 1
	s_barrier
	v_mfma_f32_16x16x32_bf16 v[68:71], v[132:135], v[192:195], v[68:71]
	v_mfma_f32_16x16x32_bf16 v[68:71], v[164:167], v[196:199], v[68:71]
	v_mfma_f32_16x16x32_bf16 v[64:67], v[168:171], v[192:195], v[64:67]
	v_mfma_f32_16x16x32_bf16 v[64:67], v[172:175], v[196:199], v[64:67]
	v_mfma_f32_16x16x32_bf16 v[60:63], v[176:179], v[192:195], v[60:63]
	v_mfma_f32_16x16x32_bf16 v[60:63], v[180:183], v[196:199], v[60:63]
	v_mfma_f32_16x16x32_bf16 v[56:59], v[184:187], v[192:195], v[56:59]
	v_mfma_f32_16x16x32_bf16 v[56:59], v[188:191], v[196:199], v[56:59]
	v_mfma_f32_16x16x32_bf16 v[40:43], v[184:187], v[200:203], v[40:43]
	v_mfma_f32_16x16x32_bf16 v[40:43], v[188:191], v[204:207], v[40:43]
	v_mfma_f32_16x16x32_bf16 v[44:47], v[176:179], v[200:203], v[44:47]
	v_mfma_f32_16x16x32_bf16 v[44:47], v[180:183], v[204:207], v[44:47]
	v_mfma_f32_16x16x32_bf16 v[48:51], v[168:171], v[200:203], v[48:51]
	v_mfma_f32_16x16x32_bf16 v[48:51], v[172:175], v[204:207], v[48:51]
	v_mfma_f32_16x16x32_bf16 v[52:55], v[132:135], v[200:203], v[52:55]
	v_mfma_f32_16x16x32_bf16 v[52:55], v[164:167], v[204:207], v[52:55]
	v_mfma_f32_16x16x32_bf16 v[36:39], v[132:135], v[208:211], v[36:39]
	v_mfma_f32_16x16x32_bf16 v[36:39], v[164:167], v[212:215], v[36:39]
	v_mfma_f32_16x16x32_bf16 v[32:35], v[168:171], v[208:211], v[32:35]
	v_mfma_f32_16x16x32_bf16 v[32:35], v[172:175], v[212:215], v[32:35]
	v_mfma_f32_16x16x32_bf16 v[28:31], v[176:179], v[208:211], v[28:31]
	v_mfma_f32_16x16x32_bf16 v[28:31], v[180:183], v[212:215], v[28:31]
	v_mfma_f32_16x16x32_bf16 v[24:27], v[184:187], v[208:211], v[24:27]
	v_mfma_f32_16x16x32_bf16 v[24:27], v[188:191], v[212:215], v[24:27]
	v_mfma_f32_16x16x32_bf16 v[8:11], v[184:187], v[216:219], v[8:11]
	v_mfma_f32_16x16x32_bf16 v[8:11], v[188:191], v[220:223], v[8:11]
	v_mfma_f32_16x16x32_bf16 v[12:15], v[176:179], v[216:219], v[12:15]
	v_mfma_f32_16x16x32_bf16 v[12:15], v[180:183], v[220:223], v[12:15]
	v_mfma_f32_16x16x32_bf16 v[16:19], v[168:171], v[216:219], v[16:19]
	v_mfma_f32_16x16x32_bf16 v[16:19], v[172:175], v[220:223], v[16:19]
	v_mfma_f32_16x16x32_bf16 v[20:23], v[132:135], v[216:219], v[20:23]
	v_mfma_f32_16x16x32_bf16 v[20:23], v[164:167], v[220:223], v[20:23]
	s_setprio 0
	s_barrier
	s_add_i32 s0, 0, 0x18000
	s_add_i32 s76, 0, 0x1c000
	v_add_u32_e32 v172, s0, v156
	v_add_u32_e32 v188, s76, v156
	ds_read_b128 v[132:135], v172
	ds_read_b128 v[164:167], v172 offset:1024
	ds_read_b128 v[168:171], v172 offset:2048
	ds_read_b128 v[172:175], v172 offset:3072
	ds_read_b128 v[176:179], v188
	ds_read_b128 v[180:183], v188 offset:1024
	ds_read_b128 v[184:187], v188 offset:2048
	ds_read_b128 v[188:191], v188 offset:3072
	s_add_u32 s98, s58, 0x100000
	s_addc_u32 s99, s59, 0
	s_mov_b32 m0, s51
	ds_read_b128 v[192:195], v161 offset:32768
	ds_read_b128 v[196:199], v161 offset:33792
	ds_read_b128 v[200:203], v161 offset:34816
	ds_read_b128 v[204:207], v161 offset:35840
	ds_read_b128 v[208:211], v161 offset:36864
	ds_read_b128 v[212:215], v161 offset:37888
	ds_read_b128 v[216:219], v161 offset:38912
	ds_read_b128 v[220:223], v161 offset:39936
	global_load_lds_dwordx4 v140, s[98:99]
	s_mov_b32 m0, s53
	s_nop 0
	global_load_lds_dwordx4 v144, s[98:99]
	s_waitcnt vmcnt(8)
	s_waitcnt lgkmcnt(0)
	s_setprio 1
	s_barrier
	v_mfma_f32_16x16x32_bf16 v[136:139], v[132:135], v[192:195], v[136:139]
	v_mfma_f32_16x16x32_bf16 v[136:139], v[164:167], v[196:199], v[136:139]
	v_mfma_f32_16x16x32_bf16 v[128:131], v[168:171], v[192:195], v[128:131]
	v_mfma_f32_16x16x32_bf16 v[128:131], v[172:175], v[196:199], v[128:131]
	v_mfma_f32_16x16x32_bf16 v[124:127], v[176:179], v[192:195], v[124:127]
	v_mfma_f32_16x16x32_bf16 v[124:127], v[180:183], v[196:199], v[124:127]
	v_mfma_f32_16x16x32_bf16 v[120:123], v[184:187], v[192:195], v[120:123]
	v_mfma_f32_16x16x32_bf16 v[120:123], v[188:191], v[196:199], v[120:123]
	v_mfma_f32_16x16x32_bf16 v[104:107], v[184:187], v[200:203], v[104:107]
	v_mfma_f32_16x16x32_bf16 v[104:107], v[188:191], v[204:207], v[104:107]
	v_mfma_f32_16x16x32_bf16 v[108:111], v[176:179], v[200:203], v[108:111]
	v_mfma_f32_16x16x32_bf16 v[108:111], v[180:183], v[204:207], v[108:111]
	v_mfma_f32_16x16x32_bf16 v[112:115], v[168:171], v[200:203], v[112:115]
	v_mfma_f32_16x16x32_bf16 v[112:115], v[172:175], v[204:207], v[112:115]
	v_mfma_f32_16x16x32_bf16 v[116:119], v[132:135], v[200:203], v[116:119]
	v_mfma_f32_16x16x32_bf16 v[116:119], v[164:167], v[204:207], v[116:119]
	v_mfma_f32_16x16x32_bf16 v[100:103], v[132:135], v[208:211], v[100:103]
	v_mfma_f32_16x16x32_bf16 v[100:103], v[164:167], v[212:215], v[100:103]
	v_mfma_f32_16x16x32_bf16 v[96:99], v[168:171], v[208:211], v[96:99]
	v_mfma_f32_16x16x32_bf16 v[96:99], v[172:175], v[212:215], v[96:99]
	v_mfma_f32_16x16x32_bf16 v[92:95], v[176:179], v[208:211], v[92:95]
	v_mfma_f32_16x16x32_bf16 v[92:95], v[180:183], v[212:215], v[92:95]
	v_mfma_f32_16x16x32_bf16 v[88:91], v[184:187], v[208:211], v[88:91]
	v_mfma_f32_16x16x32_bf16 v[88:91], v[188:191], v[212:215], v[88:91]
	v_mfma_f32_16x16x32_bf16 v[72:75], v[184:187], v[216:219], v[72:75]
	v_mfma_f32_16x16x32_bf16 v[72:75], v[188:191], v[220:223], v[72:75]
	v_mfma_f32_16x16x32_bf16 v[76:79], v[176:179], v[216:219], v[76:79]
	v_mfma_f32_16x16x32_bf16 v[76:79], v[180:183], v[220:223], v[76:79]
	v_mfma_f32_16x16x32_bf16 v[80:83], v[168:171], v[216:219], v[80:83]
	v_mfma_f32_16x16x32_bf16 v[80:83], v[172:175], v[220:223], v[80:83]
	v_mfma_f32_16x16x32_bf16 v[84:87], v[132:135], v[216:219], v[84:87]
	v_mfma_f32_16x16x32_bf16 v[84:87], v[164:167], v[220:223], v[84:87]
	s_setprio 0
	s_barrier
	s_add_i32 s0, s0, s47
	s_add_i32 m0, s0, 0xffffff80
	ds_read_b128 v[192:195], v161 offset:49152
	ds_read_b128 v[196:199], v161 offset:50176
	ds_read_b128 v[200:203], v161 offset:51200
	ds_read_b128 v[204:207], v161 offset:52224
	ds_read_b128 v[208:211], v161 offset:53248
	ds_read_b128 v[212:215], v161 offset:54272
	ds_read_b128 v[216:219], v161 offset:55296
	ds_read_b128 v[220:223], v161 offset:56320
	global_load_lds_dwordx4 v142, s[56:57] offset:128
	s_add_i32 m0, s0, 0x1f80
	s_add_i32 s0, s76, s47
	global_load_lds_dwordx4 v146, s[56:57] offset:128
	s_add_u32 s56, s56, 0x100080
	s_addc_u32 s57, s57, 0
	s_mov_b32 m0, s0
	s_nop 0
	global_load_lds_dwordx4 v142, s[56:57]
	s_add_i32 m0, s0, 0x2000
	s_nop 0
	global_load_lds_dwordx4 v146, s[56:57]
	s_add_i32 m0, s62, 0xffffff80
	s_nop 0
	global_load_lds_dwordx4 v140, s[58:59] offset:128
	s_add_i32 m0, s63, 0xffffff80
	s_nop 0
	global_load_lds_dwordx4 v144, s[58:59] offset:128
	s_waitcnt vmcnt(8)
	s_waitcnt lgkmcnt(0)
	s_setprio 1
	s_barrier
	v_mfma_f32_16x16x32_bf16 v[68:71], v[132:135], v[192:195], v[68:71]
	v_mfma_f32_16x16x32_bf16 v[68:71], v[164:167], v[196:199], v[68:71]
	v_mfma_f32_16x16x32_bf16 v[64:67], v[168:171], v[192:195], v[64:67]
	v_mfma_f32_16x16x32_bf16 v[64:67], v[172:175], v[196:199], v[64:67]
	v_mfma_f32_16x16x32_bf16 v[60:63], v[176:179], v[192:195], v[60:63]
	v_mfma_f32_16x16x32_bf16 v[60:63], v[180:183], v[196:199], v[60:63]
	v_mfma_f32_16x16x32_bf16 v[56:59], v[184:187], v[192:195], v[56:59]
	v_mfma_f32_16x16x32_bf16 v[56:59], v[188:191], v[196:199], v[56:59]
	v_mfma_f32_16x16x32_bf16 v[40:43], v[184:187], v[200:203], v[40:43]
	v_mfma_f32_16x16x32_bf16 v[40:43], v[188:191], v[204:207], v[40:43]
	v_mfma_f32_16x16x32_bf16 v[44:47], v[176:179], v[200:203], v[44:47]
	v_mfma_f32_16x16x32_bf16 v[44:47], v[180:183], v[204:207], v[44:47]
	v_mfma_f32_16x16x32_bf16 v[48:51], v[168:171], v[200:203], v[48:51]
	v_mfma_f32_16x16x32_bf16 v[48:51], v[172:175], v[204:207], v[48:51]
	v_mfma_f32_16x16x32_bf16 v[52:55], v[132:135], v[200:203], v[52:55]
	v_mfma_f32_16x16x32_bf16 v[52:55], v[164:167], v[204:207], v[52:55]
	v_mfma_f32_16x16x32_bf16 v[36:39], v[132:135], v[208:211], v[36:39]
	v_mfma_f32_16x16x32_bf16 v[36:39], v[164:167], v[212:215], v[36:39]
	v_mfma_f32_16x16x32_bf16 v[32:35], v[168:171], v[208:211], v[32:35]
	v_mfma_f32_16x16x32_bf16 v[32:35], v[172:175], v[212:215], v[32:35]
	v_mfma_f32_16x16x32_bf16 v[28:31], v[176:179], v[208:211], v[28:31]
	v_mfma_f32_16x16x32_bf16 v[28:31], v[180:183], v[212:215], v[28:31]
	v_mfma_f32_16x16x32_bf16 v[24:27], v[184:187], v[208:211], v[24:27]
	v_mfma_f32_16x16x32_bf16 v[24:27], v[188:191], v[212:215], v[24:27]
	v_mfma_f32_16x16x32_bf16 v[8:11], v[184:187], v[216:219], v[8:11]
	v_mfma_f32_16x16x32_bf16 v[8:11], v[188:191], v[220:223], v[8:11]
	v_mfma_f32_16x16x32_bf16 v[12:15], v[176:179], v[216:219], v[12:15]
	v_mfma_f32_16x16x32_bf16 v[12:15], v[180:183], v[220:223], v[12:15]
	v_mfma_f32_16x16x32_bf16 v[16:19], v[168:171], v[216:219], v[16:19]
	v_mfma_f32_16x16x32_bf16 v[16:19], v[172:175], v[220:223], v[16:19]
	v_mfma_f32_16x16x32_bf16 v[20:23], v[132:135], v[216:219], v[20:23]
	v_mfma_f32_16x16x32_bf16 v[20:23], v[164:167], v[220:223], v[20:23]
	s_setprio 0
	s_barrier
	s_add_i32 s75, s75, 2
	s_add_u32 s54, s54, 0x100
	s_addc_u32 s55, s55, 0
	s_add_u32 s73, s73, 0x100
	s_addc_u32 s74, s74, 0
	s_cmp_gt_u32 s75, 61
	s_cbranch_scc0 .LBB0_1503
	s_and_b64 vcc, exec, s[26:27]
	s_cbranch_vccz .LBB0_1506
	s_barrier

.LBB0_1672:
	ds_read_b128 v[132:135], v193
	ds_read_b128 v[136:139], v193 offset:1024
	ds_read_b128 v[140:143], v193 offset:2048
	ds_read_b128 v[144:147], v193 offset:3072
	ds_read_b128 v[148:151], v194
	ds_read_b128 v[152:155], v194 offset:1024
	ds_read_b128 v[172:175], v194 offset:2048
	ds_read_b128 v[176:179], v194 offset:3072
	s_add_u32 s0, s30, 0xffd50080
	s_addc_u32 s42, s31, -1
	s_cmpk_eq_i32 s66, 0xa8
	s_cselect_b32 s51, s7, s42
	s_cselect_b32 s50, s6, s0
	s_cselect_b32 s43, s29, s65
	s_cselect_b32 s42, s28, s64
	s_add_i32 m0, s46, 0xc000
	ds_read_b128 v[180:183], v195
	ds_read_b128 v[198:201], v195 offset:1024
	ds_read_b128 v[202:205], v195 offset:2048
	ds_read_b128 v[206:209], v195 offset:3072
	ds_read_b128 v[210:213], v195 offset:4096
	ds_read_b128 v[214:217], v195 offset:5120
	ds_read_b128 v[218:221], v195 offset:6144
	ds_read_b128 v[222:225], v195 offset:7168
	global_load_lds_dwordx4 v164, s[30:31]
	s_add_i32 m0, s46, 0xe000
	s_nop 0
	global_load_lds_dwordx4 v166, s[30:31]
	s_waitcnt vmcnt(8)
	s_waitcnt lgkmcnt(0)
	s_setprio 1
	s_barrier
	v_mfma_f32_16x16x32_bf16 v[128:131], v[132:135], v[180:183], v[128:131]
	v_mfma_f32_16x16x32_bf16 v[128:131], v[136:139], v[198:201], v[128:131]
	v_mfma_f32_16x16x32_bf16 v[124:127], v[140:143], v[180:183], v[124:127]
	v_mfma_f32_16x16x32_bf16 v[124:127], v[144:147], v[198:201], v[124:127]
	v_mfma_f32_16x16x32_bf16 v[120:123], v[148:151], v[180:183], v[120:123]
	v_mfma_f32_16x16x32_bf16 v[120:123], v[152:155], v[198:201], v[120:123]
	v_mfma_f32_16x16x32_bf16 v[116:119], v[172:175], v[180:183], v[116:119]
	v_mfma_f32_16x16x32_bf16 v[116:119], v[176:179], v[198:201], v[116:119]
	v_mfma_f32_16x16x32_bf16 v[100:103], v[172:175], v[202:205], v[100:103]
	v_mfma_f32_16x16x32_bf16 v[100:103], v[176:179], v[206:209], v[100:103]
	v_mfma_f32_16x16x32_bf16 v[104:107], v[148:151], v[202:205], v[104:107]
	v_mfma_f32_16x16x32_bf16 v[104:107], v[152:155], v[206:209], v[104:107]
	v_mfma_f32_16x16x32_bf16 v[108:111], v[140:143], v[202:205], v[108:111]
	v_mfma_f32_16x16x32_bf16 v[108:111], v[144:147], v[206:209], v[108:111]
	v_mfma_f32_16x16x32_bf16 v[112:115], v[132:135], v[202:205], v[112:115]
	v_mfma_f32_16x16x32_bf16 v[112:115], v[136:139], v[206:209], v[112:115]
	v_mfma_f32_16x16x32_bf16 v[96:99], v[132:135], v[210:213], v[96:99]
	v_mfma_f32_16x16x32_bf16 v[96:99], v[136:139], v[214:217], v[96:99]
	v_mfma_f32_16x16x32_bf16 v[92:95], v[140:143], v[210:213], v[92:95]
	v_mfma_f32_16x16x32_bf16 v[92:95], v[144:147], v[214:217], v[92:95]
	v_mfma_f32_16x16x32_bf16 v[88:91], v[148:151], v[210:213], v[88:91]
	v_mfma_f32_16x16x32_bf16 v[88:91], v[152:155], v[214:217], v[88:91]
	v_mfma_f32_16x16x32_bf16 v[84:87], v[172:175], v[210:213], v[84:87]
	v_mfma_f32_16x16x32_bf16 v[84:87], v[176:179], v[214:217], v[84:87]
	v_mfma_f32_16x16x32_bf16 v[68:71], v[172:175], v[218:221], v[68:71]
	v_mfma_f32_16x16x32_bf16 v[68:71], v[176:179], v[222:225], v[68:71]
	v_mfma_f32_16x16x32_bf16 v[72:75], v[148:151], v[218:221], v[72:75]
	v_mfma_f32_16x16x32_bf16 v[72:75], v[152:155], v[222:225], v[72:75]
	v_mfma_f32_16x16x32_bf16 v[76:79], v[140:143], v[218:221], v[76:79]
	v_mfma_f32_16x16x32_bf16 v[76:79], v[144:147], v[222:225], v[76:79]
	v_mfma_f32_16x16x32_bf16 v[80:83], v[132:135], v[218:221], v[80:83]
	v_mfma_f32_16x16x32_bf16 v[80:83], v[136:139], v[222:225], v[80:83]
	s_setprio 0
	s_barrier
	s_add_i32 s0, s57, s45
	s_mov_b32 m0, s0
	ds_read_b128 v[180:183], v195 offset:16384
	ds_read_b128 v[198:201], v195 offset:17408
	ds_read_b128 v[202:205], v195 offset:18432
	ds_read_b128 v[206:209], v195 offset:19456
	ds_read_b128 v[210:213], v195 offset:20480
	ds_read_b128 v[214:217], v195 offset:21504
	ds_read_b128 v[218:221], v195 offset:22528
	ds_read_b128 v[222:225], v195 offset:23552
	global_load_lds_dwordx4 v158, s[42:43]
	s_add_i32 m0, s0, 0x2000
	s_add_u32 s70, s42, 0x2b0000
	s_addc_u32 s71, s43, 0
	s_add_i32 s0, s58, s45
	global_load_lds_dwordx4 v162, s[42:43]
	s_mov_b32 m0, s0
	s_nop 0
	global_load_lds_dwordx4 v158, s[70:71]
	s_add_i32 m0, s0, 0x2000
	s_nop 0
	global_load_lds_dwordx4 v162, s[70:71]
	s_mov_b32 m0, s46
	s_nop 0
	global_load_lds_dwordx4 v156, s[50:51]
	s_mov_b32 m0, s47
	s_nop 0
	global_load_lds_dwordx4 v160, s[50:51]
	s_waitcnt vmcnt(8)
	s_waitcnt lgkmcnt(0)
	s_setprio 1
	s_barrier
	v_mfma_f32_16x16x32_bf16 v[64:67], v[132:135], v[180:183], v[64:67]
	v_mfma_f32_16x16x32_bf16 v[64:67], v[136:139], v[198:201], v[64:67]
	v_mfma_f32_16x16x32_bf16 v[60:63], v[140:143], v[180:183], v[60:63]
	v_mfma_f32_16x16x32_bf16 v[60:63], v[144:147], v[198:201], v[60:63]
	v_mfma_f32_16x16x32_bf16 v[56:59], v[148:151], v[180:183], v[56:59]
	v_mfma_f32_16x16x32_bf16 v[56:59], v[152:155], v[198:201], v[56:59]
	v_mfma_f32_16x16x32_bf16 v[52:55], v[172:175], v[180:183], v[52:55]
	v_mfma_f32_16x16x32_bf16 v[52:55], v[176:179], v[198:201], v[52:55]
	v_mfma_f32_16x16x32_bf16 v[36:39], v[172:175], v[202:205], v[36:39]
	v_mfma_f32_16x16x32_bf16 v[36:39], v[176:179], v[206:209], v[36:39]
	v_mfma_f32_16x16x32_bf16 v[40:43], v[148:151], v[202:205], v[40:43]
	v_mfma_f32_16x16x32_bf16 v[40:43], v[152:155], v[206:209], v[40:43]
	v_mfma_f32_16x16x32_bf16 v[44:47], v[140:143], v[202:205], v[44:47]
	v_mfma_f32_16x16x32_bf16 v[44:47], v[144:147], v[206:209], v[44:47]
	v_mfma_f32_16x16x32_bf16 v[48:51], v[132:135], v[202:205], v[48:51]
	v_mfma_f32_16x16x32_bf16 v[48:51], v[136:139], v[206:209], v[48:51]
	v_mfma_f32_16x16x32_bf16 v[32:35], v[132:135], v[210:213], v[32:35]
	v_mfma_f32_16x16x32_bf16 v[32:35], v[136:139], v[214:217], v[32:35]
	v_mfma_f32_16x16x32_bf16 v[28:31], v[140:143], v[210:213], v[28:31]
	v_mfma_f32_16x16x32_bf16 v[28:31], v[144:147], v[214:217], v[28:31]
	v_mfma_f32_16x16x32_bf16 v[24:27], v[148:151], v[210:213], v[24:27]
	v_mfma_f32_16x16x32_bf16 v[24:27], v[152:155], v[214:217], v[24:27]
	v_mfma_f32_16x16x32_bf16 v[20:23], v[172:175], v[210:213], v[20:23]
	v_mfma_f32_16x16x32_bf16 v[20:23], v[176:179], v[214:217], v[20:23]
	v_mfma_f32_16x16x32_bf16 v[4:7], v[172:175], v[218:221], v[4:7]
	v_mfma_f32_16x16x32_bf16 v[4:7], v[176:179], v[222:225], v[4:7]
	v_mfma_f32_16x16x32_bf16 v[8:11], v[148:151], v[218:221], v[8:11]
	v_mfma_f32_16x16x32_bf16 v[8:11], v[152:155], v[222:225], v[8:11]
	v_mfma_f32_16x16x32_bf16 v[12:15], v[140:143], v[218:221], v[12:15]
	v_mfma_f32_16x16x32_bf16 v[12:15], v[144:147], v[222:225], v[12:15]
	v_mfma_f32_16x16x32_bf16 v[16:19], v[132:135], v[218:221], v[16:19]
	v_mfma_f32_16x16x32_bf16 v[16:19], v[136:139], v[222:225], v[16:19]
	s_setprio 0
	s_barrier
	s_add_i32 s0, 0, 0x18000
	s_add_i32 s67, 0, 0x1c000
	v_add_u32_e32 v144, s0, v191
	v_add_u32_e32 v176, s67, v191
	ds_read_b128 v[132:135], v144
	ds_read_b128 v[136:139], v144 offset:1024
	ds_read_b128 v[140:143], v144 offset:2048
	ds_read_b128 v[144:147], v144 offset:3072
	ds_read_b128 v[148:151], v176
	ds_read_b128 v[152:155], v176 offset:1024
	ds_read_b128 v[172:175], v176 offset:2048
	ds_read_b128 v[176:179], v176 offset:3072
	s_add_u32 s98, s50, 0x2b0000
	s_addc_u32 s99, s51, 0
	s_mov_b32 m0, s48
	ds_read_b128 v[180:183], v195 offset:32768
	ds_read_b128 v[198:201], v195 offset:33792
	ds_read_b128 v[202:205], v195 offset:34816
	ds_read_b128 v[206:209], v195 offset:35840
	ds_read_b128 v[210:213], v195 offset:36864
	ds_read_b128 v[214:217], v195 offset:37888
	ds_read_b128 v[218:221], v195 offset:38912
	ds_read_b128 v[222:225], v195 offset:39936
	global_load_lds_dwordx4 v156, s[98:99]
	s_mov_b32 m0, s49
	s_nop 0
	global_load_lds_dwordx4 v160, s[98:99]
	s_waitcnt vmcnt(8)
	s_waitcnt lgkmcnt(0)
	s_setprio 1
	s_barrier
	v_mfma_f32_16x16x32_bf16 v[128:131], v[132:135], v[180:183], v[128:131]
	v_mfma_f32_16x16x32_bf16 v[128:131], v[136:139], v[198:201], v[128:131]
	v_mfma_f32_16x16x32_bf16 v[124:127], v[140:143], v[180:183], v[124:127]
	v_mfma_f32_16x16x32_bf16 v[124:127], v[144:147], v[198:201], v[124:127]
	v_mfma_f32_16x16x32_bf16 v[120:123], v[148:151], v[180:183], v[120:123]
	v_mfma_f32_16x16x32_bf16 v[120:123], v[152:155], v[198:201], v[120:123]
	v_mfma_f32_16x16x32_bf16 v[116:119], v[172:175], v[180:183], v[116:119]
	v_mfma_f32_16x16x32_bf16 v[116:119], v[176:179], v[198:201], v[116:119]
	v_mfma_f32_16x16x32_bf16 v[100:103], v[172:175], v[202:205], v[100:103]
	v_mfma_f32_16x16x32_bf16 v[100:103], v[176:179], v[206:209], v[100:103]
	v_mfma_f32_16x16x32_bf16 v[104:107], v[148:151], v[202:205], v[104:107]
	v_mfma_f32_16x16x32_bf16 v[104:107], v[152:155], v[206:209], v[104:107]
	v_mfma_f32_16x16x32_bf16 v[108:111], v[140:143], v[202:205], v[108:111]
	v_mfma_f32_16x16x32_bf16 v[108:111], v[144:147], v[206:209], v[108:111]
	v_mfma_f32_16x16x32_bf16 v[112:115], v[132:135], v[202:205], v[112:115]
	v_mfma_f32_16x16x32_bf16 v[112:115], v[136:139], v[206:209], v[112:115]
	v_mfma_f32_16x16x32_bf16 v[96:99], v[132:135], v[210:213], v[96:99]
	v_mfma_f32_16x16x32_bf16 v[96:99], v[136:139], v[214:217], v[96:99]
	v_mfma_f32_16x16x32_bf16 v[92:95], v[140:143], v[210:213], v[92:95]
	v_mfma_f32_16x16x32_bf16 v[92:95], v[144:147], v[214:217], v[92:95]
	v_mfma_f32_16x16x32_bf16 v[88:91], v[148:151], v[210:213], v[88:91]
	v_mfma_f32_16x16x32_bf16 v[88:91], v[152:155], v[214:217], v[88:91]
	v_mfma_f32_16x16x32_bf16 v[84:87], v[172:175], v[210:213], v[84:87]
	v_mfma_f32_16x16x32_bf16 v[84:87], v[176:179], v[214:217], v[84:87]
	v_mfma_f32_16x16x32_bf16 v[68:71], v[172:175], v[218:221], v[68:71]
	v_mfma_f32_16x16x32_bf16 v[68:71], v[176:179], v[222:225], v[68:71]
	v_mfma_f32_16x16x32_bf16 v[72:75], v[148:151], v[218:221], v[72:75]
	v_mfma_f32_16x16x32_bf16 v[72:75], v[152:155], v[222:225], v[72:75]
	v_mfma_f32_16x16x32_bf16 v[76:79], v[140:143], v[218:221], v[76:79]
	v_mfma_f32_16x16x32_bf16 v[76:79], v[144:147], v[222:225], v[76:79]
	v_mfma_f32_16x16x32_bf16 v[80:83], v[132:135], v[218:221], v[80:83]
	v_mfma_f32_16x16x32_bf16 v[80:83], v[136:139], v[222:225], v[80:83]
	s_setprio 0
	s_barrier
	s_add_i32 s0, s0, s45
	s_add_i32 m0, s0, 0xffffff80
	ds_read_b128 v[180:183], v195 offset:49152
	ds_read_b128 v[198:201], v195 offset:50176
	ds_read_b128 v[202:205], v195 offset:51200
	ds_read_b128 v[206:209], v195 offset:52224
	ds_read_b128 v[210:213], v195 offset:53248
	ds_read_b128 v[214:217], v195 offset:54272
	ds_read_b128 v[218:221], v195 offset:55296
	ds_read_b128 v[222:225], v195 offset:56320
	global_load_lds_dwordx4 v158, s[42:43] offset:128
	s_add_i32 m0, s0, 0x1f80
	s_add_i32 s0, s67, s45
	global_load_lds_dwordx4 v162, s[42:43] offset:128
	s_add_u32 s42, s42, 0x2b0080
	s_addc_u32 s43, s43, 0
	s_mov_b32 m0, s0
	s_nop 0
	global_load_lds_dwordx4 v158, s[42:43]
	s_add_i32 m0, s0, 0x2000
	s_nop 0
	global_load_lds_dwordx4 v162, s[42:43]
	s_add_i32 m0, s55, 0xffffff80
	s_nop 0
	global_load_lds_dwordx4 v156, s[50:51] offset:128
	s_add_i32 m0, s56, 0xffffff80
	s_nop 0
	global_load_lds_dwordx4 v160, s[50:51] offset:128
	s_waitcnt vmcnt(8)
	s_waitcnt lgkmcnt(0)
	s_setprio 1
	s_barrier
	v_mfma_f32_16x16x32_bf16 v[64:67], v[132:135], v[180:183], v[64:67]
	v_mfma_f32_16x16x32_bf16 v[64:67], v[136:139], v[198:201], v[64:67]
	v_mfma_f32_16x16x32_bf16 v[60:63], v[140:143], v[180:183], v[60:63]
	v_mfma_f32_16x16x32_bf16 v[60:63], v[144:147], v[198:201], v[60:63]
	v_mfma_f32_16x16x32_bf16 v[56:59], v[148:151], v[180:183], v[56:59]
	v_mfma_f32_16x16x32_bf16 v[56:59], v[152:155], v[198:201], v[56:59]
	v_mfma_f32_16x16x32_bf16 v[52:55], v[172:175], v[180:183], v[52:55]
	v_mfma_f32_16x16x32_bf16 v[52:55], v[176:179], v[198:201], v[52:55]
	v_mfma_f32_16x16x32_bf16 v[36:39], v[172:175], v[202:205], v[36:39]
	v_mfma_f32_16x16x32_bf16 v[36:39], v[176:179], v[206:209], v[36:39]
	v_mfma_f32_16x16x32_bf16 v[40:43], v[148:151], v[202:205], v[40:43]
	v_mfma_f32_16x16x32_bf16 v[40:43], v[152:155], v[206:209], v[40:43]
	v_mfma_f32_16x16x32_bf16 v[44:47], v[140:143], v[202:205], v[44:47]
	v_mfma_f32_16x16x32_bf16 v[44:47], v[144:147], v[206:209], v[44:47]
	v_mfma_f32_16x16x32_bf16 v[48:51], v[132:135], v[202:205], v[48:51]
	v_mfma_f32_16x16x32_bf16 v[48:51], v[136:139], v[206:209], v[48:51]
	v_mfma_f32_16x16x32_bf16 v[32:35], v[132:135], v[210:213], v[32:35]
	v_mfma_f32_16x16x32_bf16 v[32:35], v[136:139], v[214:217], v[32:35]
	v_mfma_f32_16x16x32_bf16 v[28:31], v[140:143], v[210:213], v[28:31]
	v_mfma_f32_16x16x32_bf16 v[28:31], v[144:147], v[214:217], v[28:31]
	v_mfma_f32_16x16x32_bf16 v[24:27], v[148:151], v[210:213], v[24:27]
	v_mfma_f32_16x16x32_bf16 v[24:27], v[152:155], v[214:217], v[24:27]
	v_mfma_f32_16x16x32_bf16 v[20:23], v[172:175], v[210:213], v[20:23]
	v_mfma_f32_16x16x32_bf16 v[20:23], v[176:179], v[214:217], v[20:23]
	v_mfma_f32_16x16x32_bf16 v[4:7], v[172:175], v[218:221], v[4:7]
	v_mfma_f32_16x16x32_bf16 v[4:7], v[176:179], v[222:225], v[4:7]
	v_mfma_f32_16x16x32_bf16 v[8:11], v[148:151], v[218:221], v[8:11]
	v_mfma_f32_16x16x32_bf16 v[8:11], v[152:155], v[222:225], v[8:11]
	v_mfma_f32_16x16x32_bf16 v[12:15], v[140:143], v[218:221], v[12:15]
	v_mfma_f32_16x16x32_bf16 v[12:15], v[144:147], v[222:225], v[12:15]
	v_mfma_f32_16x16x32_bf16 v[16:19], v[132:135], v[218:221], v[16:19]
	v_mfma_f32_16x16x32_bf16 v[16:19], v[136:139], v[222:225], v[16:19]
	s_setprio 0
	s_barrier
	s_add_i32 s66, s66, 2
	s_add_u32 s30, s30, 0x100
	s_addc_u32 s31, s31, 0
	s_add_u32 s64, s64, 0x100
	s_addc_u32 s65, s65, 0
	s_cmpk_gt_u32 s66, 0xa9
	s_cbranch_scc0 .LBB0_1672
	s_and_b64 vcc, exec, s[24:25]
	s_cbranch_vccz .LBB0_1675
	s_barrier

.LBB0_1703:
	ds_read_b128 v[136:139], v196
	ds_read_b128 v[140:143], v196 offset:1024
	ds_read_b128 v[144:147], v196 offset:2048
	ds_read_b128 v[148:151], v196 offset:3072
	ds_read_b128 v[152:155], v197
	ds_read_b128 v[176:179], v197 offset:1024
	ds_read_b128 v[180:183], v197 offset:2048
	ds_read_b128 v[184:187], v197 offset:3072
	s_add_u32 s8, s6, 0x100
	s_addc_u32 s9, s7, 0
	s_add_u32 s0, s65, s6
	s_addc_u32 s40, s66, s7
	s_cmpk_eq_i32 s67, 0xa8
	s_cselect_b32 s43, s50, s40
	s_cselect_b32 s40, 0, s8
	s_cselect_b32 s42, s51, s0
	s_cselect_b32 s0, 0, s9
	s_add_u32 s40, s16, s40
	s_addc_u32 s41, s17, s0
	s_mov_b32 m0, s58
	v_lshl_add_u64 v[226:227], v[132:133], 0, s[6:7]
	ds_read_b128 v[188:191], v198
	ds_read_b128 v[192:195], v198 offset:1024
	ds_read_b128 v[202:205], v198 offset:2048
	ds_read_b128 v[206:209], v198 offset:3072
	ds_read_b128 v[210:213], v198 offset:4096
	ds_read_b128 v[214:217], v198 offset:5120
	ds_read_b128 v[218:221], v198 offset:6144
	ds_read_b128 v[222:225], v198 offset:7168
	global_load_lds_dwordx4 v[226:227], off
	v_lshl_add_u64 v[226:227], v[134:135], 0, s[6:7]
	s_mov_b32 m0, s59
	s_nop 0
	global_load_lds_dwordx4 v[226:227], off
	s_waitcnt vmcnt(8)
	s_waitcnt lgkmcnt(0)
	s_setprio 1
	s_barrier
	v_mfma_f32_16x16x32_bf16 v[128:131], v[136:139], v[188:191], v[128:131]
	v_mfma_f32_16x16x32_bf16 v[128:131], v[140:143], v[192:195], v[128:131]
	v_mfma_f32_16x16x32_bf16 v[124:127], v[144:147], v[188:191], v[124:127]
	v_mfma_f32_16x16x32_bf16 v[124:127], v[148:151], v[192:195], v[124:127]
	v_mfma_f32_16x16x32_bf16 v[120:123], v[152:155], v[188:191], v[120:123]
	v_mfma_f32_16x16x32_bf16 v[120:123], v[176:179], v[192:195], v[120:123]
	v_mfma_f32_16x16x32_bf16 v[116:119], v[180:183], v[188:191], v[116:119]
	v_mfma_f32_16x16x32_bf16 v[116:119], v[184:187], v[192:195], v[116:119]
	v_mfma_f32_16x16x32_bf16 v[100:103], v[180:183], v[202:205], v[100:103]
	v_mfma_f32_16x16x32_bf16 v[100:103], v[184:187], v[206:209], v[100:103]
	v_mfma_f32_16x16x32_bf16 v[104:107], v[152:155], v[202:205], v[104:107]
	v_mfma_f32_16x16x32_bf16 v[104:107], v[176:179], v[206:209], v[104:107]
	v_mfma_f32_16x16x32_bf16 v[108:111], v[144:147], v[202:205], v[108:111]
	v_mfma_f32_16x16x32_bf16 v[108:111], v[148:151], v[206:209], v[108:111]
	v_mfma_f32_16x16x32_bf16 v[112:115], v[136:139], v[202:205], v[112:115]
	v_mfma_f32_16x16x32_bf16 v[112:115], v[140:143], v[206:209], v[112:115]
	v_mfma_f32_16x16x32_bf16 v[96:99], v[136:139], v[210:213], v[96:99]
	v_mfma_f32_16x16x32_bf16 v[96:99], v[140:143], v[214:217], v[96:99]
	v_mfma_f32_16x16x32_bf16 v[92:95], v[144:147], v[210:213], v[92:95]
	v_mfma_f32_16x16x32_bf16 v[92:95], v[148:151], v[214:217], v[92:95]
	v_mfma_f32_16x16x32_bf16 v[88:91], v[152:155], v[210:213], v[88:91]
	v_mfma_f32_16x16x32_bf16 v[88:91], v[176:179], v[214:217], v[88:91]
	v_mfma_f32_16x16x32_bf16 v[84:87], v[180:183], v[210:213], v[84:87]
	v_mfma_f32_16x16x32_bf16 v[84:87], v[184:187], v[214:217], v[84:87]
	v_mfma_f32_16x16x32_bf16 v[68:71], v[180:183], v[218:221], v[68:71]
	v_mfma_f32_16x16x32_bf16 v[68:71], v[184:187], v[222:225], v[68:71]
	v_mfma_f32_16x16x32_bf16 v[72:75], v[152:155], v[218:221], v[72:75]
	v_mfma_f32_16x16x32_bf16 v[72:75], v[176:179], v[222:225], v[72:75]
	v_mfma_f32_16x16x32_bf16 v[76:79], v[144:147], v[218:221], v[76:79]
	v_mfma_f32_16x16x32_bf16 v[76:79], v[148:151], v[222:225], v[76:79]
	v_mfma_f32_16x16x32_bf16 v[80:83], v[136:139], v[218:221], v[80:83]
	v_mfma_f32_16x16x32_bf16 v[80:83], v[140:143], v[222:225], v[80:83]
	s_setprio 0
	s_barrier
	s_mov_b32 m0, s60
	v_lshl_add_u64 v[226:227], s[40:41], 0, v[158:159]
	s_add_u32 s6, s40, 0x2b0000
	ds_read_b128 v[188:191], v198 offset:16384
	ds_read_b128 v[192:195], v198 offset:17408
	ds_read_b128 v[202:205], v198 offset:18432
	ds_read_b128 v[206:209], v198 offset:19456
	ds_read_b128 v[210:213], v198 offset:20480
	ds_read_b128 v[214:217], v198 offset:21504
	ds_read_b128 v[218:221], v198 offset:22528
	ds_read_b128 v[222:225], v198 offset:23552
	global_load_lds_dwordx4 v[226:227], off
	v_lshl_add_u64 v[228:229], s[40:41], 0, v[162:163]
	s_mov_b32 m0, s61
	s_addc_u32 s7, s41, 0
	global_load_lds_dwordx4 v[228:229], off
	v_lshl_add_u64 v[230:231], s[6:7], 0, v[158:159]
	s_mov_b32 m0, s62
	v_lshl_add_u64 v[232:233], s[42:43], 0, v[160:161]
	global_load_lds_dwordx4 v[230:231], off
	v_lshl_add_u64 v[230:231], s[6:7], 0, v[162:163]
	s_mov_b32 m0, s63
	s_nop 0
	global_load_lds_dwordx4 v[230:231], off
	v_lshl_add_u64 v[230:231], s[42:43], 0, v[156:157]
	s_mov_b32 m0, s46
	s_nop 0
	global_load_lds_dwordx4 v[230:231], off
	s_mov_b32 m0, s47
	s_nop 0
	global_load_lds_dwordx4 v[232:233], off
	s_waitcnt vmcnt(8)
	s_waitcnt lgkmcnt(0)
	s_setprio 1
	s_barrier
	v_mfma_f32_16x16x32_bf16 v[64:67], v[136:139], v[188:191], v[64:67]
	v_mfma_f32_16x16x32_bf16 v[64:67], v[140:143], v[192:195], v[64:67]
	v_mfma_f32_16x16x32_bf16 v[60:63], v[144:147], v[188:191], v[60:63]
	v_mfma_f32_16x16x32_bf16 v[60:63], v[148:151], v[192:195], v[60:63]
	v_mfma_f32_16x16x32_bf16 v[56:59], v[152:155], v[188:191], v[56:59]
	v_mfma_f32_16x16x32_bf16 v[56:59], v[176:179], v[192:195], v[56:59]
	v_mfma_f32_16x16x32_bf16 v[52:55], v[180:183], v[188:191], v[52:55]
	v_mfma_f32_16x16x32_bf16 v[52:55], v[184:187], v[192:195], v[52:55]
	v_mfma_f32_16x16x32_bf16 v[36:39], v[180:183], v[202:205], v[36:39]
	v_mfma_f32_16x16x32_bf16 v[36:39], v[184:187], v[206:209], v[36:39]
	v_mfma_f32_16x16x32_bf16 v[40:43], v[152:155], v[202:205], v[40:43]
	v_mfma_f32_16x16x32_bf16 v[40:43], v[176:179], v[206:209], v[40:43]
	v_mfma_f32_16x16x32_bf16 v[44:47], v[144:147], v[202:205], v[44:47]
	v_mfma_f32_16x16x32_bf16 v[44:47], v[148:151], v[206:209], v[44:47]
	v_mfma_f32_16x16x32_bf16 v[48:51], v[136:139], v[202:205], v[48:51]
	v_mfma_f32_16x16x32_bf16 v[48:51], v[140:143], v[206:209], v[48:51]
	v_mfma_f32_16x16x32_bf16 v[32:35], v[136:139], v[210:213], v[32:35]
	v_mfma_f32_16x16x32_bf16 v[32:35], v[140:143], v[214:217], v[32:35]
	v_mfma_f32_16x16x32_bf16 v[28:31], v[144:147], v[210:213], v[28:31]
	v_mfma_f32_16x16x32_bf16 v[28:31], v[148:151], v[214:217], v[28:31]
	v_mfma_f32_16x16x32_bf16 v[24:27], v[152:155], v[210:213], v[24:27]
	v_mfma_f32_16x16x32_bf16 v[24:27], v[176:179], v[214:217], v[24:27]
	v_mfma_f32_16x16x32_bf16 v[20:23], v[180:183], v[210:213], v[20:23]
	v_mfma_f32_16x16x32_bf16 v[20:23], v[184:187], v[214:217], v[20:23]
	v_mfma_f32_16x16x32_bf16 v[4:7], v[180:183], v[218:221], v[4:7]
	v_mfma_f32_16x16x32_bf16 v[4:7], v[184:187], v[222:225], v[4:7]
	v_mfma_f32_16x16x32_bf16 v[8:11], v[152:155], v[218:221], v[8:11]
	v_mfma_f32_16x16x32_bf16 v[8:11], v[176:179], v[222:225], v[8:11]
	v_mfma_f32_16x16x32_bf16 v[12:15], v[144:147], v[218:221], v[12:15]
	v_mfma_f32_16x16x32_bf16 v[12:15], v[148:151], v[222:225], v[12:15]
	v_mfma_f32_16x16x32_bf16 v[16:19], v[136:139], v[218:221], v[16:19]
	v_mfma_f32_16x16x32_bf16 v[16:19], v[140:143], v[222:225], v[16:19]
	s_setprio 0
	s_barrier
	s_add_i32 s0, 0, 0x18000
	s_add_i32 s68, 0, 0x1c000
	v_add_u32_e32 v148, s0, v3
	v_add_u32_e32 v170, s68, v3
	ds_read_b128 v[136:139], v148
	ds_read_b128 v[140:143], v148 offset:1024
	ds_read_b128 v[144:147], v148 offset:2048
	ds_read_b128 v[148:151], v148 offset:3072
	ds_read_b128 v[152:155], v170
	ds_read_b128 v[176:179], v170 offset:1024
	ds_read_b128 v[180:183], v170 offset:2048
	ds_read_b128 v[184:187], v170 offset:3072
	s_add_u32 s6, s42, 0x2b0000
	s_addc_u32 s7, s43, 0
	s_mov_b32 m0, s48
	v_lshl_add_u64 v[234:235], s[6:7], 0, v[156:157]
	ds_read_b128 v[188:191], v198 offset:32768
	ds_read_b128 v[192:195], v198 offset:33792
	ds_read_b128 v[202:205], v198 offset:34816
	ds_read_b128 v[206:209], v198 offset:35840
	ds_read_b128 v[210:213], v198 offset:36864
	ds_read_b128 v[214:217], v198 offset:37888
	ds_read_b128 v[218:221], v198 offset:38912
	ds_read_b128 v[222:225], v198 offset:39936
	global_load_lds_dwordx4 v[234:235], off
	v_lshl_add_u64 v[234:235], s[6:7], 0, v[160:161]
	s_mov_b32 m0, s49
	s_nop 0
	global_load_lds_dwordx4 v[234:235], off
	s_waitcnt vmcnt(8)
	s_waitcnt lgkmcnt(0)
	s_setprio 1
	s_barrier
	v_mfma_f32_16x16x32_bf16 v[128:131], v[136:139], v[188:191], v[128:131]
	v_mfma_f32_16x16x32_bf16 v[128:131], v[140:143], v[192:195], v[128:131]
	v_mfma_f32_16x16x32_bf16 v[124:127], v[144:147], v[188:191], v[124:127]
	v_mfma_f32_16x16x32_bf16 v[124:127], v[148:151], v[192:195], v[124:127]
	v_mfma_f32_16x16x32_bf16 v[120:123], v[152:155], v[188:191], v[120:123]
	v_mfma_f32_16x16x32_bf16 v[120:123], v[176:179], v[192:195], v[120:123]
	v_mfma_f32_16x16x32_bf16 v[116:119], v[180:183], v[188:191], v[116:119]
	v_mfma_f32_16x16x32_bf16 v[116:119], v[184:187], v[192:195], v[116:119]
	v_mfma_f32_16x16x32_bf16 v[100:103], v[180:183], v[202:205], v[100:103]
	v_mfma_f32_16x16x32_bf16 v[100:103], v[184:187], v[206:209], v[100:103]
	v_mfma_f32_16x16x32_bf16 v[104:107], v[152:155], v[202:205], v[104:107]
	v_mfma_f32_16x16x32_bf16 v[104:107], v[176:179], v[206:209], v[104:107]
	v_mfma_f32_16x16x32_bf16 v[108:111], v[144:147], v[202:205], v[108:111]
	v_mfma_f32_16x16x32_bf16 v[108:111], v[148:151], v[206:209], v[108:111]
	v_mfma_f32_16x16x32_bf16 v[112:115], v[136:139], v[202:205], v[112:115]
	v_mfma_f32_16x16x32_bf16 v[112:115], v[140:143], v[206:209], v[112:115]
	v_mfma_f32_16x16x32_bf16 v[96:99], v[136:139], v[210:213], v[96:99]
	v_mfma_f32_16x16x32_bf16 v[96:99], v[140:143], v[214:217], v[96:99]
	v_mfma_f32_16x16x32_bf16 v[92:95], v[144:147], v[210:213], v[92:95]
	v_mfma_f32_16x16x32_bf16 v[92:95], v[148:151], v[214:217], v[92:95]
	v_mfma_f32_16x16x32_bf16 v[88:91], v[152:155], v[210:213], v[88:91]
	v_mfma_f32_16x16x32_bf16 v[88:91], v[176:179], v[214:217], v[88:91]
	v_mfma_f32_16x16x32_bf16 v[84:87], v[180:183], v[210:213], v[84:87]
	v_mfma_f32_16x16x32_bf16 v[84:87], v[184:187], v[214:217], v[84:87]
	v_mfma_f32_16x16x32_bf16 v[68:71], v[180:183], v[218:221], v[68:71]
	v_mfma_f32_16x16x32_bf16 v[68:71], v[184:187], v[222:225], v[68:71]
	v_mfma_f32_16x16x32_bf16 v[72:75], v[152:155], v[218:221], v[72:75]
	v_mfma_f32_16x16x32_bf16 v[72:75], v[176:179], v[222:225], v[72:75]
	v_mfma_f32_16x16x32_bf16 v[76:79], v[144:147], v[218:221], v[76:79]
	v_mfma_f32_16x16x32_bf16 v[76:79], v[148:151], v[222:225], v[76:79]
	v_mfma_f32_16x16x32_bf16 v[80:83], v[136:139], v[218:221], v[80:83]
	v_mfma_f32_16x16x32_bf16 v[80:83], v[140:143], v[222:225], v[80:83]
	s_setprio 0
	s_barrier
	s_add_i32 s0, s0, s45
	v_lshl_add_u64 v[226:227], v[226:227], 0, s[28:29]
	s_mov_b32 m0, s0
	ds_read_b128 v[188:191], v198 offset:49152
	ds_read_b128 v[192:195], v198 offset:50176
	ds_read_b128 v[202:205], v198 offset:51200
	ds_read_b128 v[206:209], v198 offset:52224
	ds_read_b128 v[210:213], v198 offset:53248
	ds_read_b128 v[214:217], v198 offset:54272
	ds_read_b128 v[218:221], v198 offset:55296
	ds_read_b128 v[222:225], v198 offset:56320
	global_load_lds_dwordx4 v[226:227], off
	s_add_i32 m0, s0, 0x2000
	s_add_u32 s6, s40, 0x2b0080
	v_lshl_add_u64 v[226:227], v[228:229], 0, s[28:29]
	s_addc_u32 s7, s41, 0
	s_add_i32 s0, s68, s45
	global_load_lds_dwordx4 v[226:227], off
	v_lshl_add_u64 v[226:227], s[6:7], 0, v[158:159]
	s_mov_b32 m0, s0
	s_nop 0
	global_load_lds_dwordx4 v[226:227], off
	v_lshl_add_u64 v[226:227], s[6:7], 0, v[162:163]
	s_add_i32 m0, s0, 0x2000
	s_nop 0
	global_load_lds_dwordx4 v[226:227], off
	v_lshl_add_u64 v[226:227], v[230:231], 0, s[28:29]
	s_mov_b32 m0, s54
	s_nop 0
	global_load_lds_dwordx4 v[226:227], off
	v_lshl_add_u64 v[226:227], v[232:233], 0, s[28:29]
	s_mov_b32 m0, s55
	s_nop 0
	global_load_lds_dwordx4 v[226:227], off
	s_waitcnt vmcnt(8)
	s_waitcnt lgkmcnt(0)
	s_setprio 1
	s_barrier
	v_mfma_f32_16x16x32_bf16 v[64:67], v[136:139], v[188:191], v[64:67]
	v_mfma_f32_16x16x32_bf16 v[64:67], v[140:143], v[192:195], v[64:67]
	v_mfma_f32_16x16x32_bf16 v[60:63], v[144:147], v[188:191], v[60:63]
	v_mfma_f32_16x16x32_bf16 v[60:63], v[148:151], v[192:195], v[60:63]
	v_mfma_f32_16x16x32_bf16 v[56:59], v[152:155], v[188:191], v[56:59]
	v_mfma_f32_16x16x32_bf16 v[56:59], v[176:179], v[192:195], v[56:59]
	v_mfma_f32_16x16x32_bf16 v[52:55], v[180:183], v[188:191], v[52:55]
	v_mfma_f32_16x16x32_bf16 v[52:55], v[184:187], v[192:195], v[52:55]
	v_mfma_f32_16x16x32_bf16 v[36:39], v[180:183], v[202:205], v[36:39]
	v_mfma_f32_16x16x32_bf16 v[36:39], v[184:187], v[206:209], v[36:39]
	v_mfma_f32_16x16x32_bf16 v[40:43], v[152:155], v[202:205], v[40:43]
	v_mfma_f32_16x16x32_bf16 v[40:43], v[176:179], v[206:209], v[40:43]
	v_mfma_f32_16x16x32_bf16 v[44:47], v[144:147], v[202:205], v[44:47]
	v_mfma_f32_16x16x32_bf16 v[44:47], v[148:151], v[206:209], v[44:47]
	v_mfma_f32_16x16x32_bf16 v[48:51], v[136:139], v[202:205], v[48:51]
	v_mfma_f32_16x16x32_bf16 v[48:51], v[140:143], v[206:209], v[48:51]
	v_mfma_f32_16x16x32_bf16 v[32:35], v[136:139], v[210:213], v[32:35]
	v_mfma_f32_16x16x32_bf16 v[32:35], v[140:143], v[214:217], v[32:35]
	v_mfma_f32_16x16x32_bf16 v[28:31], v[144:147], v[210:213], v[28:31]
	v_mfma_f32_16x16x32_bf16 v[28:31], v[148:151], v[214:217], v[28:31]
	v_mfma_f32_16x16x32_bf16 v[24:27], v[152:155], v[210:213], v[24:27]
	v_mfma_f32_16x16x32_bf16 v[24:27], v[176:179], v[214:217], v[24:27]
	v_mfma_f32_16x16x32_bf16 v[20:23], v[180:183], v[210:213], v[20:23]
	v_mfma_f32_16x16x32_bf16 v[20:23], v[184:187], v[214:217], v[20:23]
	v_mfma_f32_16x16x32_bf16 v[4:7], v[180:183], v[218:221], v[4:7]
	v_mfma_f32_16x16x32_bf16 v[4:7], v[184:187], v[222:225], v[4:7]
	v_mfma_f32_16x16x32_bf16 v[8:11], v[152:155], v[218:221], v[8:11]
	v_mfma_f32_16x16x32_bf16 v[8:11], v[176:179], v[222:225], v[8:11]
	v_mfma_f32_16x16x32_bf16 v[12:15], v[144:147], v[218:221], v[12:15]
	v_mfma_f32_16x16x32_bf16 v[12:15], v[148:151], v[222:225], v[12:15]
	v_mfma_f32_16x16x32_bf16 v[16:19], v[136:139], v[218:221], v[16:19]
	v_mfma_f32_16x16x32_bf16 v[16:19], v[140:143], v[222:225], v[16:19]
	s_setprio 0
	s_barrier
	s_add_i32 s67, s67, 2
	s_cmpk_gt_u32 s67, 0xa9
	s_mov_b64 s[6:7], s[8:9]
	s_cbranch_scc0 .LBB0_1703
	s_and_b64 vcc, exec, s[30:31]
	s_cbranch_vccz .LBB0_1706
	s_barrier
